# GEMM LDS-DMA loads use SGPR-base + 32-bit VGPR offset form (57 64-bit VALU adds removed); norm1/norm2 row loops use global stores with a counted vmcnt(8) wait
# baseline (speedup 1.0000x reference)
; template <bool FINAL>
; __device__ __forceinline__ void norm_pass(const float* X, const float* g, const float* scale, const float* shift, bf16_t* H, float* OUTF, int vcu_, int NGW_, int wave_s) {
;     ...
;     for (int m = gw; m < SEQ; m += NGW) {
;         f32x4 v[8]; float ss = 0.f;
; #pragma unroll
;         for (int j = 0; j < 8; ++j) v[j] = nv[j];
;         if (m + NGW < SEQ) { const f32x4* xn = (const f32x4*)(X + (size_t)(m + NGW) * DM) + lane;
; #pragma unroll
;             for (int j = 0; j < 8; ++j) nv[j] = xn[64 * j]; }
; #pragma unroll
;         for (int j = 0; j < 8; ++j) ss += (v[j].x * v[j].x + v[j].y * v[j].y) + (v[j].z * v[j].z + v[j].w * v[j].w);
;         const float rstd = 1.0f / sqrtf(wave_sum(ss) * (1.f / DM) + EPS);
.LBB0_139:
	v_mul_f32_e32 v0, v95, v95
	v_mul_f32_e32 v134, v97, v97
	v_fmac_f32_e32 v0, v94, v94
	v_fmac_f32_e32 v134, v96, v96
	v_add_f32_e32 v0, v0, v134
	v_mul_f32_e32 v134, v91, v91
	v_mul_f32_e32 v135, v93, v93
	v_fmac_f32_e32 v134, v90, v90
	v_fmac_f32_e32 v135, v92, v92
	v_add_f32_e32 v134, v134, v135
	v_add_f32_e32 v0, v134, v0
	v_mul_f32_e32 v134, v87, v87
	v_mul_f32_e32 v135, v89, v89
	v_fmac_f32_e32 v134, v86, v86
	v_fmac_f32_e32 v135, v88, v88
	v_add_f32_e32 v134, v134, v135
	v_add_f32_e32 v0, v134, v0
	v_mul_f32_e32 v134, v83, v83
	v_mul_f32_e32 v135, v85, v85
	v_fmac_f32_e32 v134, v82, v82
	v_fmac_f32_e32 v135, v84, v84
	v_add_f32_e32 v134, v134, v135
	v_add_f32_e32 v0, v134, v0
	v_mul_f32_e32 v134, v79, v79
	v_mul_f32_e32 v135, v81, v81
	v_fmac_f32_e32 v134, v78, v78
	v_fmac_f32_e32 v135, v80, v80
	v_add_f32_e32 v134, v134, v135
	v_add_f32_e32 v0, v134, v0
	v_mul_f32_e32 v134, v43, v43
	v_mul_f32_e32 v135, v45, v45
	v_fmac_f32_e32 v134, v42, v42
	v_fmac_f32_e32 v135, v44, v44
	v_add_f32_e32 v134, v134, v135
	v_add_f32_e32 v0, v134, v0
	v_mul_f32_e32 v134, v39, v39
	v_mul_f32_e32 v135, v41, v41
	v_fmac_f32_e32 v134, v38, v38
	v_fmac_f32_e32 v135, v40, v40
	v_add_f32_e32 v134, v134, v135
	v_add_f32_e32 v0, v134, v0
	v_mul_f32_e32 v134, v35, v35
	v_mul_f32_e32 v135, v37, v37
	v_fmac_f32_e32 v134, v34, v34
	v_fmac_f32_e32 v135, v36, v36
	v_add_f32_e32 v134, v134, v135
	v_add_f32_e32 v0, v134, v0
	ds_swizzle_b32 v134, v0 offset:swizzle(SWAP,1)
	v_lshl_add_u64 v[132:133], v[132:133], 0, s[10:11]
	s_waitcnt lgkmcnt(0)
	v_add_f32_e32 v0, v0, v134
	ds_swizzle_b32 v134, v0 offset:swizzle(SWAP,2)
	s_waitcnt lgkmcnt(0)
	v_add_f32_e32 v0, v0, v134
	ds_swizzle_b32 v134, v0 offset:swizzle(SWAP,4)
	s_waitcnt lgkmcnt(0)
	v_add_f32_e32 v0, v0, v134
	ds_swizzle_b32 v134, v0 offset:swizzle(SWAP,8)
	s_waitcnt lgkmcnt(0)
	v_add_f32_e32 v0, v0, v134
	ds_swizzle_b32 v134, v0 offset:swizzle(SWAP,16)
	s_waitcnt lgkmcnt(0)
; __device__ __forceinline__ unsigned pk2(float lo, float hi) { return f2bf(lo) | (f2bf(hi) << 16); }
; template <bool FINAL>
; __device__ __forceinline__ void norm_pass(const float* X, const float* g, const float* scale, const float* shift, bf16_t* H, float* OUTF, int vcu_, int NGW_, int wave_s) {
;     ...
;     for (int m = gw; m < SEQ; m += NGW) {
;         f32x4 v[8]; float ss = 0.f;
; #pragma unroll
;         for (int j = 0; j < 8; ++j) v[j] = nv[j];
;         if (m + NGW < SEQ) { const f32x4* xn = (const f32x4*)(X + (size_t)(m + NGW) * DM) + lane;
; #pragma unroll
;             for (int j = 0; j < 8; ++j) nv[j] = xn[64 * j]; }
;     ...
;         const float rstd = 1.0f / sqrtf(wave_sum(ss) * (1.f / DM) + EPS);
;         if (FINAL) { f32x4* orow = (f32x4*)(OUTF + (size_t)m * DM) + lane;
; #pragma unroll
;             for (int j = 0; j < 8; ++j) orow[64 * j] = v[j] * rstd * gm[j]; }
;         else { u32x2* orow = (u32x2*)(H + (size_t)m * DM) + lane;
; #pragma unroll
;             for (int j = 0; j < 8; ++j) { const f32x4 y = v[j] * rstd * gm[j] + sh[j]; u32x2 w; w.x = pk2(y.x, y.y); w.y = pk2(y.z, y.w); orow[64 * j] = w; } }
	v_add_f32_e32 v0, v0, v134
	v_mov_b32_e32 v134, v0
	s_nop 1
	v_permlane32_swap_b32_e32 v0, v134
	v_add_f32_e32 v0, v0, v134
	v_fmamk_f32 v0, v0, 0x3a000000, v218
	v_mul_f32_e32 v134, 0x4f800000, v0
	v_cmp_gt_f32_e32 vcc, s68, v0
	s_nop 1
	v_cndmask_b32_e32 v0, v0, v134, vcc
	v_sqrt_f32_e32 v134, v0
	s_nop 0
	v_add_u32_e32 v135, -1, v134
	v_fma_f32 v136, -v135, v134, v0
	v_cmp_ge_f32_e64 s[0:1], 0, v136
	v_add_u32_e32 v136, 1, v134
	s_nop 0
	v_cndmask_b32_e64 v135, v134, v135, s[0:1]
	v_fma_f32 v134, -v136, v134, v0
	v_cmp_lt_f32_e64 s[0:1], 0, v134
	s_nop 1
	v_cndmask_b32_e64 v134, v135, v136, s[0:1]
	v_mul_f32_e32 v135, 0x37800000, v134
	v_cndmask_b32_e32 v134, v134, v135, vcc
	v_cmp_class_f32_e32 vcc, v0, v219
	s_nop 1
	v_cndmask_b32_e32 v0, v134, v0, vcc
	v_div_scale_f32 v134, s[0:1], v0, v0, 1.0
	v_rcp_f32_e32 v135, v134
	s_nop 0
	v_fma_f32 v136, -v134, v135, 1.0
	v_fmac_f32_e32 v135, v136, v135
	v_div_scale_f32 v136, vcc, 1.0, v0, 1.0
	v_mul_f32_e32 v137, v136, v135
	v_fma_f32 v138, -v134, v137, v136
	v_fmac_f32_e32 v137, v138, v135
	v_fma_f32 v134, -v134, v137, v136
	v_div_fmas_f32 v134, v134, v135, v137
	v_div_fixup_f32 v0, v134, v0, 1.0
	v_pk_mul_f32 v[94:95], v[94:95], v[0:1] op_sel_hi:[1,0]
	v_pk_mul_f32 v[96:97], v[96:97], v[0:1] op_sel_hi:[1,0]
	v_pk_fma_f32 v[94:95], v[100:101], v[94:95], v[18:19]
	v_pk_fma_f32 v[96:97], v[98:99], v[96:97], v[20:21]
	v_bfe_u32 v134, v94, 16, 1
	v_add3_u32 v94, v94, v134, s33
	v_bfe_u32 v134, v95, 16, 1
	v_lshrrev_b32_e32 v94, 16, v94
	v_add3_u32 v95, v95, v134, s33
	v_and_or_b32 v94, v95, s48, v94
	v_bfe_u32 v95, v96, 16, 1
	v_add3_u32 v95, v96, v95, s33
	v_bfe_u32 v96, v97, 16, 1
	v_lshrrev_b32_e32 v95, 16, v95
	v_add3_u32 v96, v97, v96, s33
	v_pk_mul_f32 v[90:91], v[90:91], v[0:1] op_sel_hi:[1,0]
	v_and_or_b32 v95, v96, s48, v95
	v_pk_fma_f32 v[90:91], v[104:105], v[90:91], v[10:11]
	global_store_dwordx2 v[130:131], v[94:95], off
	v_bfe_u32 v94, v90, 16, 1
	v_pk_mul_f32 v[92:93], v[92:93], v[0:1] op_sel_hi:[1,0]
	v_add3_u32 v90, v90, v94, s33
	v_bfe_u32 v94, v91, 16, 1
	v_pk_fma_f32 v[92:93], v[102:103], v[92:93], v[12:13]
	v_lshrrev_b32_e32 v90, 16, v90
	v_add3_u32 v91, v91, v94, s33
	v_and_or_b32 v90, v91, s48, v90
	v_bfe_u32 v91, v92, 16, 1
	v_add3_u32 v91, v92, v91, s33
	v_bfe_u32 v92, v93, 16, 1
	v_lshrrev_b32_e32 v91, 16, v91
	v_add3_u32 v92, v93, v92, s33
	v_pk_mul_f32 v[86:87], v[86:87], v[0:1] op_sel_hi:[1,0]
	v_and_or_b32 v91, v92, s48, v91
	v_pk_fma_f32 v[86:87], v[108:109], v[86:87], v[14:15]
	global_store_dwordx2 v[130:131], v[90:91], off offset:512
	v_bfe_u32 v90, v86, 16, 1
	v_pk_mul_f32 v[88:89], v[88:89], v[0:1] op_sel_hi:[1,0]
	v_add3_u32 v86, v86, v90, s33
	v_bfe_u32 v90, v87, 16, 1
	v_pk_fma_f32 v[88:89], v[106:107], v[88:89], v[16:17]
	v_lshrrev_b32_e32 v86, 16, v86
	v_add3_u32 v87, v87, v90, s33
	v_and_or_b32 v86, v87, s48, v86
	v_bfe_u32 v87, v88, 16, 1
	v_add3_u32 v87, v88, v87, s33
	v_bfe_u32 v88, v89, 16, 1
	v_lshrrev_b32_e32 v87, 16, v87
	v_add3_u32 v88, v89, v88, s33
	v_pk_mul_f32 v[82:83], v[82:83], v[0:1] op_sel_hi:[1,0]
	v_and_or_b32 v87, v88, s48, v87
	v_pk_fma_f32 v[82:83], v[112:113], v[82:83], v[22:23]
	global_store_dwordx2 v[130:131], v[86:87], off offset:1024
	v_bfe_u32 v86, v82, 16, 1
	v_pk_mul_f32 v[84:85], v[84:85], v[0:1] op_sel_hi:[1,0]
	v_add3_u32 v82, v82, v86, s33
	v_bfe_u32 v86, v83, 16, 1
	v_pk_fma_f32 v[84:85], v[110:111], v[84:85], v[24:25]
	v_lshrrev_b32_e32 v82, 16, v82
	v_add3_u32 v83, v83, v86, s33
	v_and_or_b32 v82, v83, s48, v82
	v_bfe_u32 v83, v84, 16, 1
	v_add3_u32 v83, v84, v83, s33
	v_bfe_u32 v84, v85, 16, 1
	v_lshrrev_b32_e32 v83, 16, v83
	v_add3_u32 v84, v85, v84, s33
	v_pk_mul_f32 v[78:79], v[78:79], v[0:1] op_sel_hi:[1,0]
	v_and_or_b32 v83, v84, s48, v83
	v_pk_fma_f32 v[78:79], v[116:117], v[78:79], v[6:7]
	global_store_dwordx2 v[130:131], v[82:83], off offset:1536
	v_bfe_u32 v82, v78, 16, 1
	v_pk_mul_f32 v[80:81], v[80:81], v[0:1] op_sel_hi:[1,0]
	v_add3_u32 v78, v78, v82, s33
	v_bfe_u32 v82, v79, 16, 1
	v_pk_fma_f32 v[80:81], v[114:115], v[80:81], v[8:9]
	v_lshrrev_b32_e32 v78, 16, v78
	v_add3_u32 v79, v79, v82, s33
	v_and_or_b32 v78, v79, s48, v78
	v_bfe_u32 v79, v80, 16, 1
	v_add3_u32 v79, v80, v79, s33
	v_bfe_u32 v80, v81, 16, 1
	v_lshrrev_b32_e32 v79, 16, v79
	v_add3_u32 v80, v81, v80, s33
	v_pk_mul_f32 v[42:43], v[42:43], v[0:1] op_sel_hi:[1,0]
	v_and_or_b32 v79, v80, s48, v79
	v_pk_fma_f32 v[42:43], v[120:121], v[42:43], v[26:27]
	global_store_dwordx2 v[130:131], v[78:79], off offset:2048
	v_bfe_u32 v78, v42, 16, 1
	v_pk_mul_f32 v[44:45], v[44:45], v[0:1] op_sel_hi:[1,0]
	v_add3_u32 v42, v42, v78, s33
	v_bfe_u32 v78, v43, 16, 1
	v_pk_fma_f32 v[44:45], v[118:119], v[44:45], v[28:29]
	v_lshrrev_b32_e32 v42, 16, v42
	v_add3_u32 v43, v43, v78, s33
	v_and_or_b32 v42, v43, s48, v42
	v_bfe_u32 v43, v44, 16, 1
	v_add3_u32 v43, v44, v43, s33
	v_bfe_u32 v44, v45, 16, 1
	v_lshrrev_b32_e32 v43, 16, v43
	v_add3_u32 v44, v45, v44, s33
	v_pk_mul_f32 v[38:39], v[38:39], v[0:1] op_sel_hi:[1,0]
	v_pk_mul_f32 v[34:35], v[34:35], v[0:1] op_sel_hi:[1,0]
	v_and_or_b32 v43, v44, s48, v43
	v_pk_fma_f32 v[38:39], v[124:125], v[38:39], v[2:3]
	v_pk_fma_f32 v[34:35], v[128:129], v[34:35], v[30:31]
	global_store_dwordx2 v[130:131], v[42:43], off offset:2560
	v_pk_mul_f32 v[40:41], v[40:41], v[0:1] op_sel_hi:[1,0]
	v_bfe_u32 v42, v38, 16, 1
	v_pk_mul_f32 v[36:37], v[36:37], v[0:1] op_sel_hi:[1,0]
	v_bfe_u32 v0, v34, 16, 1
	v_add3_u32 v38, v38, v42, s33
	v_bfe_u32 v42, v39, 16, 1
	v_add3_u32 v0, v34, v0, s33
	v_bfe_u32 v34, v35, 16, 1
	v_pk_fma_f32 v[40:41], v[122:123], v[40:41], v[4:5]
	v_lshrrev_b32_e32 v38, 16, v38
	v_add3_u32 v39, v39, v42, s33
	v_pk_fma_f32 v[36:37], v[126:127], v[36:37], v[32:33]
	v_lshrrev_b32_e32 v0, 16, v0
	v_add3_u32 v34, v35, v34, s33
	v_and_or_b32 v38, v39, s48, v38
	v_bfe_u32 v39, v40, 16, 1
	v_and_or_b32 v34, v34, s48, v0
	v_bfe_u32 v0, v36, 16, 1
	v_add3_u32 v39, v40, v39, s33
	v_bfe_u32 v40, v41, 16, 1
	v_add3_u32 v0, v36, v0, s33
	v_bfe_u32 v35, v37, 16, 1
	v_lshrrev_b32_e32 v39, 16, v39
	v_add3_u32 v40, v41, v40, s33
	v_lshrrev_b32_e32 v0, 16, v0
	v_add3_u32 v35, v37, v35, s33
	v_and_or_b32 v39, v40, s48, v39
	v_and_or_b32 v35, v35, s48, v0
	global_store_dwordx2 v[130:131], v[38:39], off offset:3072
	global_store_dwordx2 v[130:131], v[34:35], off offset:3584
	s_waitcnt vmcnt(8)
	v_mov_b64_e32 v[34:35], v[46:47]
	v_mov_b64_e32 v[38:39], v[50:51]
	v_mov_b64_e32 v[42:43], v[54:55]
	v_mov_b64_e32 v[80:81], v[60:61]
	v_mov_b64_e32 v[84:85], v[64:65]
	v_mov_b64_e32 v[88:89], v[68:69]
	v_mov_b64_e32 v[92:93], v[72:73]
	v_mov_b64_e32 v[96:97], v[76:77]
	v_lshl_add_u64 v[130:131], v[130:131], 0, s[8:9]
	s_andn2_b64 vcc, exec, s[12:13]
	v_mov_b64_e32 v[36:37], v[48:49]
	v_mov_b64_e32 v[40:41], v[52:53]
	v_mov_b64_e32 v[44:45], v[56:57]
	v_mov_b64_e32 v[78:79], v[58:59]
	v_mov_b64_e32 v[82:83], v[62:63]
	v_mov_b64_e32 v[86:87], v[66:67]
	v_mov_b64_e32 v[90:91], v[70:71]
	v_mov_b64_e32 v[94:95], v[74:75]
	s_cbranch_vccz .LBB0_142

; #define PG8_STAGE(bufoff, gbase, voff) do { _Pragma("unroll") for (int _i = 0; _i < 2; ++_i) \
;         __builtin_amdgcn_global_load_lds((const unsigned*)((const char*)(gbase) + (voff)[_i]), (LAS unsigned*)(lds + (bufoff) + ldsw + _i * 8192), 16, 0, 0); } while (0)
; #define PG8_WAIT_V(n) asm volatile("s_waitcnt vmcnt(" #n ")" ::: "memory")
; #define PG8_BAR __builtin_amdgcn_s_barrier()
; template <class Epi>
; __device__ __forceinline__ void gemm_phase(LAS unsigned char* lds, const Gemm g, const StaticOrder& S, const Epi& E, int wave_s) {
;     ...
;     PG8_STAGE(PG8_SB(0, 0), cB, voffB); PG8_STAGE(PG8_SB(0, 1), cB + hstepB, voffB); PG8_STAGE(PG8_SA(0, 0), cA, voffA); PG8_STAGE(PG8_SA(0, 1), cA + hstepA, voffA);
;     if (wr == 1) PG8_BAR;
;     PG8_WAIT_V(2); PG8_BAR;
;     PG8_STAGE(PG8_SB(1, 0), cB + kstep, voffB); PG8_STAGE(PG8_SA(1, 0), cA + kstep, voffA); PG8_STAGE(PG8_SB(1, 1), cB + hstepB + kstep, voffB);
;     PG8_WAIT_V(6); PG8_BAR;
.LBB0_189:
	s_add_u32 s6, s0, 0x12000000
	s_addc_u32 s7, s1, 0
	v_and_b32_e32 v17, 48, v16
	v_lshlrev_b32_e32 v18, 6, v16
	s_movk_i32 s1, 0x3c0
	v_lshlrev_b32_e32 v16, 2, v16
	s_lshl_b32 s0, s10, 13
	v_and_or_b32 v17, v18, s1, v17
	v_and_b32_e32 v16, 32, v16
	v_bitop3_b32 v18, v17, s0, v16 bitop3:0xde
	s_lshl_b32 s0, s9, 5
	s_and_b32 s37, s0, 0x60
	s_add_i32 m0, s29, 0x18000
	v_lshl_add_u64 v[8:9], v[8:9], 0, s[42:43]
	s_lshl_b32 s35, s10, 6
	s_lshl_b32 s0, s37, 7
	s_waitcnt vmcnt(2)
	s_barrier
	global_load_lds_dwordx4 v[8:9], off
	v_lshl_add_u64 v[6:7], v[6:7], 0, s[42:43]
	s_add_i32 m0, s29, 0x1a000
	s_add_i32 s38, s29, 0x8000
	s_add_i32 s39, s29, 0xa000
	v_bitop3_b32 v145, s0, v17, v16 bitop3:0xf6
	global_load_lds_dwordx4 v[6:7], off
	v_lshl_add_u64 v[2:3], v[2:3], 0, s[42:43]
	s_mov_b32 m0, s38
	s_add_u32 s0, s18, 0x80080
	global_load_lds_dwordx4 v[2:3], off
	v_lshl_add_u64 v[2:3], v[4:5], 0, s[42:43]
	s_mov_b32 m0, s39
	s_addc_u32 s1, s19, 0
	global_load_lds_dwordx4 v[2:3], off
	s_add_i32 m0, s29, 0x1c000
	s_nop 0
	global_load_lds_dwordx4 v0, s[0:1]
	v_lshl_add_u64 v[2:3], s[0:1], 0, v[130:131]
	s_add_i32 m0, s29, 0x1e000
	s_cmpk_lt_u32 s8, 0x100
	global_load_lds_dwordx4 v[2:3], off
	v_lshlrev_b32_e32 v2, 15, v10
	v_and_b32_e32 v2, 0xffff0000, v2
	v_lshl_add_u32 v2, v11, 12, v2
	v_and_b32_e32 v3, 1, v10
	v_lshl_or_b32 v2, v3, 6, v2
	v_lshl_add_u32 v136, v12, 1, v2
	v_lshlrev_b32_e32 v2, 15, v14
	v_and_b32_e32 v2, 0xffff0000, v2
	s_waitcnt vmcnt(6)
	v_lshl_add_u32 v2, v13, 12, v2
	v_and_b32_e32 v3, 1, v14
	v_lshl_or_b32 v2, v3, 6, v2
	v_readlane_b32 s0, v254, 55
	s_cselect_b64 s[8:9], -1, 0
	v_mov_b32_e32 v137, v1
	v_lshl_add_u32 v138, v15, 1, v2
	v_mov_b32_e32 v139, v1
	s_mov_b32 s40, 0
	v_add_u32_e32 v146, 0, v18
	v_readlane_b32 s41, v254, 54
	s_mov_b32 s56, s0
	s_barrier
	v_readlane_b32 s1, v254, 56
	s_branch .LBB0_192

; #define PG8_STAGE(bufoff, gbase, voff) do { _Pragma("unroll") for (int _i = 0; _i < 2; ++_i) \
;         __builtin_amdgcn_global_load_lds((const unsigned*)((const char*)(gbase) + (voff)[_i]), (LAS unsigned*)(lds + (bufoff) + ldsw + _i * 8192), 16, 0, 0); } while (0)
; #define PG8_LDA(dst, b, h) do { _Pragma("unroll") for (int m = 0; m < 4; ++m) _Pragma("unroll") for (int k = 0; k < 2; ++k) dst[m][k] = *(const LAS bf16x8*)(lds + PG8_SA(b, h) + aoff + m * 2048 + k * 1024); } while (0)
; #define PG8_LDB(dst, b, h) do { _Pragma("unroll") for (int n = 0; n < 2; ++n) _Pragma("unroll") for (int k = 0; k < 2; ++k) dst[n][k] = *(const LAS bf16x8*)(lds + PG8_SB(b, h) + boff + n * 2048 + k * 1024); } while (0)
; #define PG8_MMA(ai, bj, At, Bt) do { __builtin_amdgcn_s_setprio(1); _Pragma("unroll") for (int m = 0; m < 4; ++m) _Pragma("unroll") for (int n = 0; n < 2; ++n) _Pragma("unroll") for (int k = 0; k < 2; ++k) \
;         acc[ai][bj][m][n] = __builtin_amdgcn_mfma_f32_16x16x32_bf16(Bt[n][k], At[m][k], acc[ai][bj][m][n], 0, 0, 0); __builtin_amdgcn_s_setprio(0); } while (0)
; #define PG8_WAIT_V(n) asm volatile("s_waitcnt vmcnt(" #n ")" ::: "memory")
; #define PG8_WAIT_L(n) asm volatile("s_waitcnt lgkmcnt(" #n ")" ::: "memory")
; #define PG8_BAR __builtin_amdgcn_s_barrier()
; #define PG8_SCHED __builtin_amdgcn_sched_barrier(0)
; template <class Epi>
; __device__ __forceinline__ void gemm_phase(LAS unsigned char* lds, const Gemm g, const StaticOrder& S, const Epi& E, int wave_s) {
;     ...
;             PG8_LDB(B0, 0, 0); PG8_LDB(B1, 0, 1); PG8_SCHED; PG8_LDA(At, 0, 0); PG8_STAGE(PG8_SA(1, 1), a1 + hstepA, voffA);
;             PG8_WAIT_V(8); PG8_WAIT_L(0); PG8_BAR; PG8_MMA(0, 0, At, B0); PG8_MMA(0, 1, At, B1); PG8_BAR; PG8_SCHED;
;             PG8_LDA(At, 0, 1); PG8_STAGE(PG8_SB(0, 0), b2, voffB); PG8_STAGE(PG8_SB(0, 1), b2 + hstepB, voffB); PG8_STAGE(PG8_SA(0, 0), a2, voffA);
;             PG8_WAIT_V(8); PG8_WAIT_L(0); PG8_BAR; PG8_MMA(1, 0, At, B0); PG8_MMA(1, 1, At, B1); PG8_BAR; PG8_SCHED;
.LBB0_195:
	s_add_u32 s20, s18, 0xfff80080
	s_addc_u32 s21, s19, -1
	s_add_i32 s70, 0, 0x10000
	s_cmp_eq_u32 s67, 28
	s_cselect_b32 s23, s13, s21
	s_cselect_b32 s22, s57, s20
	v_add_u32_e32 v147, s70, v145
	s_cselect_b32 s21, s11, s66
	s_cselect_b32 s20, s64, s65
	s_add_i32 s72, 0, 0x14000
	ds_read_b128 v[140:143], v147
	ds_read_b128 v[148:151], v147 offset:1024
	ds_read_b128 v[152:155], v147 offset:2048
	ds_read_b128 v[156:159], v147 offset:3072
	v_add_u32_e32 v147, s72, v145
	ds_read_b128 v[160:163], v147
	ds_read_b128 v[164:167], v147 offset:1024
	ds_read_b128 v[168:171], v147 offset:2048
	ds_read_b128 v[172:175], v147 offset:3072
	s_add_i32 m0, s29, 0xc000
	ds_read_b128 v[176:179], v146
	ds_read_b128 v[180:183], v146 offset:1024
	ds_read_b128 v[184:187], v146 offset:2048
	ds_read_b128 v[188:191], v146 offset:3072
	ds_read_b128 v[192:195], v146 offset:4096
	ds_read_b128 v[196:199], v146 offset:5120
	ds_read_b128 v[200:203], v146 offset:6144
	ds_read_b128 v[212:215], v146 offset:7168
	global_load_lds_dwordx4 v138, s[18:19]
	s_add_i32 m0, s29, 0xe000
	s_nop 0
	global_load_lds_dwordx4 v136, s[18:19]
	s_waitcnt vmcnt(8)
	s_waitcnt lgkmcnt(0)
	s_barrier
	s_setprio 1
	s_waitcnt lgkmcnt(0)
	v_mfma_f32_16x16x32_bf16 v[126:129], v[140:143], v[176:179], v[126:129]
	v_mfma_f32_16x16x32_bf16 v[122:125], v[152:155], v[176:179], v[122:125]
	v_mfma_f32_16x16x32_bf16 v[118:121], v[140:143], v[184:187], v[118:121]
	v_mfma_f32_16x16x32_bf16 v[110:113], v[152:155], v[184:187], v[110:113]
	v_mfma_f32_16x16x32_bf16 v[102:105], v[140:143], v[192:195], v[102:105]
	v_mfma_f32_16x16x32_bf16 v[94:97], v[152:155], v[192:195], v[94:97]
	v_mfma_f32_16x16x32_bf16 v[86:89], v[140:143], v[200:203], v[86:89]
	v_mfma_f32_16x16x32_bf16 v[78:81], v[152:155], v[200:203], v[78:81]
	v_mfma_f32_16x16x32_bf16 v[126:129], v[148:151], v[180:183], v[126:129]
	v_mfma_f32_16x16x32_bf16 v[122:125], v[156:159], v[180:183], v[122:125]
	v_mfma_f32_16x16x32_bf16 v[118:121], v[148:151], v[188:191], v[118:121]
	v_mfma_f32_16x16x32_bf16 v[110:113], v[156:159], v[188:191], v[110:113]
	v_mfma_f32_16x16x32_bf16 v[102:105], v[148:151], v[196:199], v[102:105]
	v_mfma_f32_16x16x32_bf16 v[94:97], v[156:159], v[196:199], v[94:97]
	v_mfma_f32_16x16x32_bf16 v[86:89], v[148:151], v[212:215], v[86:89]
	v_mfma_f32_16x16x32_bf16 v[78:81], v[156:159], v[212:215], v[78:81]
	s_setprio 0
	s_setprio 1
	v_mfma_f32_16x16x32_bf16 v[114:117], v[160:163], v[176:179], v[114:117]
	v_mfma_f32_16x16x32_bf16 v[106:109], v[168:171], v[176:179], v[106:109]
	v_mfma_f32_16x16x32_bf16 v[98:101], v[160:163], v[184:187], v[98:101]
	v_mfma_f32_16x16x32_bf16 v[90:93], v[168:171], v[184:187], v[90:93]
	v_mfma_f32_16x16x32_bf16 v[82:85], v[160:163], v[192:195], v[82:85]
	v_mfma_f32_16x16x32_bf16 v[74:77], v[168:171], v[192:195], v[74:77]
	v_mfma_f32_16x16x32_bf16 v[70:73], v[160:163], v[200:203], v[70:73]
	v_mfma_f32_16x16x32_bf16 v[66:69], v[168:171], v[200:203], v[66:69]
	v_mfma_f32_16x16x32_bf16 v[114:117], v[164:167], v[180:183], v[114:117]
	v_mfma_f32_16x16x32_bf16 v[106:109], v[172:175], v[180:183], v[106:109]
	v_mfma_f32_16x16x32_bf16 v[98:101], v[164:167], v[188:191], v[98:101]
	v_mfma_f32_16x16x32_bf16 v[90:93], v[172:175], v[188:191], v[90:93]
	v_mfma_f32_16x16x32_bf16 v[82:85], v[164:167], v[196:199], v[82:85]
	v_mfma_f32_16x16x32_bf16 v[74:77], v[172:175], v[196:199], v[74:77]
	v_mfma_f32_16x16x32_bf16 v[70:73], v[164:167], v[212:215], v[70:73]
	v_mfma_f32_16x16x32_bf16 v[66:69], v[172:175], v[212:215], v[66:69]
	s_setprio 0
	s_barrier
	s_add_i32 s70, s70, s28
	v_lshl_add_u64 v[208:209], s[20:21], 0, v[0:1]
	s_mov_b32 m0, s70
	ds_read_b128 v[176:179], v146 offset:16384
	ds_read_b128 v[180:183], v146 offset:17408
	ds_read_b128 v[184:187], v146 offset:18432
	ds_read_b128 v[188:191], v146 offset:19456
	ds_read_b128 v[192:195], v146 offset:20480
	ds_read_b128 v[196:199], v146 offset:21504
	ds_read_b128 v[200:203], v146 offset:22528
	ds_read_b128 v[212:215], v146 offset:23552
	global_load_lds_dwordx4 v[208:209], off
	s_add_i32 m0, s70, 0x2000
	s_add_u32 s70, s20, 0x80000
	v_lshl_add_u64 v[210:211], s[20:21], 0, v[130:131]
	s_addc_u32 s71, s21, 0
	s_add_i32 s72, s72, s28
	global_load_lds_dwordx4 v[210:211], off
	s_mov_b32 m0, s72
	v_lshl_add_u64 v[226:227], s[22:23], 0, v[132:133]
	global_load_lds_dwordx4 v0, s[70:71]
	s_add_i32 m0, s72, 0x2000
	s_nop 0
	global_load_lds_dwordx4 v130, s[70:71]
	v_lshl_add_u64 v[216:217], s[22:23], 0, v[134:135]
	s_mov_b32 m0, s29
	s_nop 0
	global_load_lds_dwordx4 v[216:217], off
	s_mov_b32 m0, s30
	s_nop 0
	global_load_lds_dwordx4 v[226:227], off
	s_waitcnt vmcnt(8)
	s_waitcnt lgkmcnt(0)
	s_barrier
; #define PG8_STAGE(bufoff, gbase, voff) do { _Pragma("unroll") for (int _i = 0; _i < 2; ++_i) \
;         __builtin_amdgcn_global_load_lds((const unsigned*)((const char*)(gbase) + (voff)[_i]), (LAS unsigned*)(lds + (bufoff) + ldsw + _i * 8192), 16, 0, 0); } while (0)
; #define PG8_LDA(dst, b, h) do { _Pragma("unroll") for (int m = 0; m < 4; ++m) _Pragma("unroll") for (int k = 0; k < 2; ++k) dst[m][k] = *(const LAS bf16x8*)(lds + PG8_SA(b, h) + aoff + m * 2048 + k * 1024); } while (0)
; #define PG8_LDB(dst, b, h) do { _Pragma("unroll") for (int n = 0; n < 2; ++n) _Pragma("unroll") for (int k = 0; k < 2; ++k) dst[n][k] = *(const LAS bf16x8*)(lds + PG8_SB(b, h) + boff + n * 2048 + k * 1024); } while (0)
; #define PG8_MMA(ai, bj, At, Bt) do { __builtin_amdgcn_s_setprio(1); _Pragma("unroll") for (int m = 0; m < 4; ++m) _Pragma("unroll") for (int n = 0; n < 2; ++n) _Pragma("unroll") for (int k = 0; k < 2; ++k) \
;         acc[ai][bj][m][n] = __builtin_amdgcn_mfma_f32_16x16x32_bf16(Bt[n][k], At[m][k], acc[ai][bj][m][n], 0, 0, 0); __builtin_amdgcn_s_setprio(0); } while (0)
; #define PG8_WAIT_V(n) asm volatile("s_waitcnt vmcnt(" #n ")" ::: "memory")
; #define PG8_WAIT_L(n) asm volatile("s_waitcnt lgkmcnt(" #n ")" ::: "memory")
; #define PG8_BAR __builtin_amdgcn_s_barrier()
; #define PG8_SCHED __builtin_amdgcn_sched_barrier(0)
; template <class Epi>
; __device__ __forceinline__ void gemm_phase(LAS unsigned char* lds, const Gemm g, const StaticOrder& S, const Epi& E, int wave_s) {
;     ...
;             PG8_WAIT_V(8); PG8_WAIT_L(0); PG8_BAR; PG8_MMA(1, 0, At, B0); PG8_MMA(1, 1, At, B1); PG8_BAR; PG8_SCHED;
;             PG8_LDB(B0, 1, 0); PG8_LDB(B1, 1, 1); PG8_SCHED; PG8_LDA(At, 1, 0); PG8_STAGE(PG8_SA(0, 1), a2 + hstepA, voffA);
;             PG8_WAIT_V(8); PG8_WAIT_L(0); PG8_BAR; PG8_MMA(0, 0, At, B0); PG8_MMA(0, 1, At, B1); PG8_BAR; PG8_SCHED;
	s_setprio 1
	s_waitcnt lgkmcnt(0)
	v_mfma_f32_16x16x32_bf16 v[62:65], v[140:143], v[176:179], v[62:65]
	v_mfma_f32_16x16x32_bf16 v[58:61], v[152:155], v[176:179], v[58:61]
	v_mfma_f32_16x16x32_bf16 v[54:57], v[140:143], v[184:187], v[54:57]
	v_mfma_f32_16x16x32_bf16 v[46:49], v[152:155], v[184:187], v[46:49]
	v_mfma_f32_16x16x32_bf16 v[38:41], v[140:143], v[192:195], v[38:41]
	v_mfma_f32_16x16x32_bf16 v[30:33], v[152:155], v[192:195], v[30:33]
	v_mfma_f32_16x16x32_bf16 v[22:25], v[140:143], v[200:203], v[22:25]
	v_mfma_f32_16x16x32_bf16 v[14:17], v[152:155], v[200:203], v[14:17]
	v_mfma_f32_16x16x32_bf16 v[62:65], v[148:151], v[180:183], v[62:65]
	v_mfma_f32_16x16x32_bf16 v[58:61], v[156:159], v[180:183], v[58:61]
	v_mfma_f32_16x16x32_bf16 v[54:57], v[148:151], v[188:191], v[54:57]
	v_mfma_f32_16x16x32_bf16 v[46:49], v[156:159], v[188:191], v[46:49]
	v_mfma_f32_16x16x32_bf16 v[38:41], v[148:151], v[196:199], v[38:41]
	v_mfma_f32_16x16x32_bf16 v[30:33], v[156:159], v[196:199], v[30:33]
	v_mfma_f32_16x16x32_bf16 v[22:25], v[148:151], v[212:215], v[22:25]
	v_mfma_f32_16x16x32_bf16 v[14:17], v[156:159], v[212:215], v[14:17]
	s_setprio 0
	s_setprio 1
	v_mfma_f32_16x16x32_bf16 v[50:53], v[160:163], v[176:179], v[50:53]
	v_mfma_f32_16x16x32_bf16 v[42:45], v[168:171], v[176:179], v[42:45]
	v_mfma_f32_16x16x32_bf16 v[34:37], v[160:163], v[184:187], v[34:37]
	v_mfma_f32_16x16x32_bf16 v[26:29], v[168:171], v[184:187], v[26:29]
	v_mfma_f32_16x16x32_bf16 v[18:21], v[160:163], v[192:195], v[18:21]
	v_mfma_f32_16x16x32_bf16 v[10:13], v[168:171], v[192:195], v[10:13]
	v_mfma_f32_16x16x32_bf16 v[6:9], v[160:163], v[200:203], v[6:9]
	v_mfma_f32_16x16x32_bf16 v[2:5], v[168:171], v[200:203], v[2:5]
	v_mfma_f32_16x16x32_bf16 v[50:53], v[164:167], v[180:183], v[50:53]
	v_mfma_f32_16x16x32_bf16 v[42:45], v[172:175], v[180:183], v[42:45]
	v_mfma_f32_16x16x32_bf16 v[34:37], v[164:167], v[188:191], v[34:37]
	v_mfma_f32_16x16x32_bf16 v[26:29], v[172:175], v[188:191], v[26:29]
	v_mfma_f32_16x16x32_bf16 v[18:21], v[164:167], v[196:199], v[18:21]
	v_mfma_f32_16x16x32_bf16 v[10:13], v[172:175], v[196:199], v[10:13]
	v_mfma_f32_16x16x32_bf16 v[6:9], v[164:167], v[212:215], v[6:9]
	v_mfma_f32_16x16x32_bf16 v[2:5], v[172:175], v[212:215], v[2:5]
	s_setprio 0
	s_barrier
	s_add_i32 s70, 0, 0x18000
	v_add_u32_e32 v147, s70, v145
	s_add_i32 s71, 0, 0x1c000
	ds_read_b128 v[140:143], v147
	ds_read_b128 v[148:151], v147 offset:1024
	ds_read_b128 v[152:155], v147 offset:2048
	ds_read_b128 v[156:159], v147 offset:3072
	v_add_u32_e32 v147, s71, v145
	ds_read_b128 v[160:163], v147
	ds_read_b128 v[164:167], v147 offset:1024
	ds_read_b128 v[168:171], v147 offset:2048
	ds_read_b128 v[172:175], v147 offset:3072
	s_add_u32 s22, s22, 0x80000
	s_addc_u32 s23, s23, 0
	s_mov_b32 m0, s31
	ds_read_b128 v[176:179], v146 offset:32768
	ds_read_b128 v[180:183], v146 offset:33792
	ds_read_b128 v[184:187], v146 offset:34816
	ds_read_b128 v[188:191], v146 offset:35840
	ds_read_b128 v[192:195], v146 offset:36864
	ds_read_b128 v[196:199], v146 offset:37888
	ds_read_b128 v[200:203], v146 offset:38912
	ds_read_b128 v[212:215], v146 offset:39936
	global_load_lds_dwordx4 v134, s[22:23]
	v_lshl_add_u64 v[228:229], s[22:23], 0, v[132:133]
	s_mov_b32 m0, s34
	s_nop 0
	global_load_lds_dwordx4 v[228:229], off
	s_waitcnt vmcnt(8)
	s_waitcnt lgkmcnt(0)
	s_barrier
	s_setprio 1
	s_waitcnt lgkmcnt(0)
	v_mfma_f32_16x16x32_bf16 v[126:129], v[140:143], v[176:179], v[126:129]
	v_mfma_f32_16x16x32_bf16 v[122:125], v[152:155], v[176:179], v[122:125]
	v_mfma_f32_16x16x32_bf16 v[118:121], v[140:143], v[184:187], v[118:121]
	v_mfma_f32_16x16x32_bf16 v[110:113], v[152:155], v[184:187], v[110:113]
	v_mfma_f32_16x16x32_bf16 v[102:105], v[140:143], v[192:195], v[102:105]
	v_mfma_f32_16x16x32_bf16 v[94:97], v[152:155], v[192:195], v[94:97]
	v_mfma_f32_16x16x32_bf16 v[86:89], v[140:143], v[200:203], v[86:89]
	v_mfma_f32_16x16x32_bf16 v[78:81], v[152:155], v[200:203], v[78:81]
	v_mfma_f32_16x16x32_bf16 v[126:129], v[148:151], v[180:183], v[126:129]
	v_mfma_f32_16x16x32_bf16 v[122:125], v[156:159], v[180:183], v[122:125]
	v_mfma_f32_16x16x32_bf16 v[118:121], v[148:151], v[188:191], v[118:121]
	v_mfma_f32_16x16x32_bf16 v[110:113], v[156:159], v[188:191], v[110:113]
	v_mfma_f32_16x16x32_bf16 v[102:105], v[148:151], v[196:199], v[102:105]
	v_mfma_f32_16x16x32_bf16 v[94:97], v[156:159], v[196:199], v[94:97]
	v_mfma_f32_16x16x32_bf16 v[86:89], v[148:151], v[212:215], v[86:89]
	v_mfma_f32_16x16x32_bf16 v[78:81], v[156:159], v[212:215], v[78:81]
	s_setprio 0
	s_setprio 1
	v_mfma_f32_16x16x32_bf16 v[114:117], v[160:163], v[176:179], v[114:117]
	v_mfma_f32_16x16x32_bf16 v[106:109], v[168:171], v[176:179], v[106:109]
	v_mfma_f32_16x16x32_bf16 v[98:101], v[160:163], v[184:187], v[98:101]
	v_mfma_f32_16x16x32_bf16 v[90:93], v[168:171], v[184:187], v[90:93]
	v_mfma_f32_16x16x32_bf16 v[82:85], v[160:163], v[192:195], v[82:85]
	v_mfma_f32_16x16x32_bf16 v[74:77], v[168:171], v[192:195], v[74:77]
	v_mfma_f32_16x16x32_bf16 v[70:73], v[160:163], v[200:203], v[70:73]
	v_mfma_f32_16x16x32_bf16 v[66:69], v[168:171], v[200:203], v[66:69]
	v_mfma_f32_16x16x32_bf16 v[114:117], v[164:167], v[180:183], v[114:117]
	v_mfma_f32_16x16x32_bf16 v[106:109], v[172:175], v[180:183], v[106:109]
	v_mfma_f32_16x16x32_bf16 v[98:101], v[164:167], v[188:191], v[98:101]
	v_mfma_f32_16x16x32_bf16 v[90:93], v[172:175], v[188:191], v[90:93]
	v_mfma_f32_16x16x32_bf16 v[82:85], v[164:167], v[196:199], v[82:85]
	v_mfma_f32_16x16x32_bf16 v[74:77], v[172:175], v[196:199], v[74:77]
	v_mfma_f32_16x16x32_bf16 v[70:73], v[164:167], v[212:215], v[70:73]
	v_mfma_f32_16x16x32_bf16 v[66:69], v[172:175], v[212:215], v[66:69]
	s_setprio 0
	s_barrier
; #define PG8_STAGE(bufoff, gbase, voff) do { _Pragma("unroll") for (int _i = 0; _i < 2; ++_i) \
;         __builtin_amdgcn_global_load_lds((const unsigned*)((const char*)(gbase) + (voff)[_i]), (LAS unsigned*)(lds + (bufoff) + ldsw + _i * 8192), 16, 0, 0); } while (0)
; #define PG8_LDA(dst, b, h) do { _Pragma("unroll") for (int m = 0; m < 4; ++m) _Pragma("unroll") for (int k = 0; k < 2; ++k) dst[m][k] = *(const LAS bf16x8*)(lds + PG8_SA(b, h) + aoff + m * 2048 + k * 1024); } while (0)
; #define PG8_MMA(ai, bj, At, Bt) do { __builtin_amdgcn_s_setprio(1); _Pragma("unroll") for (int m = 0; m < 4; ++m) _Pragma("unroll") for (int n = 0; n < 2; ++n) _Pragma("unroll") for (int k = 0; k < 2; ++k) \
;         acc[ai][bj][m][n] = __builtin_amdgcn_mfma_f32_16x16x32_bf16(Bt[n][k], At[m][k], acc[ai][bj][m][n], 0, 0, 0); __builtin_amdgcn_s_setprio(0); } while (0)
; #define PG8_WAIT_V(n) asm volatile("s_waitcnt vmcnt(" #n ")" ::: "memory")
; #define PG8_WAIT_L(n) asm volatile("s_waitcnt lgkmcnt(" #n ")" ::: "memory")
; #define PG8_BAR __builtin_amdgcn_s_barrier()
; #define PG8_SCHED __builtin_amdgcn_sched_barrier(0)
; template <class Epi>
; __device__ __forceinline__ void gemm_phase(LAS unsigned char* lds, const Gemm g, const StaticOrder& S, const Epi& E, int wave_s) {
;     ...
;             PG8_LDA(At, 1, 1); PG8_STAGE(PG8_SB(1, 0), b3, voffB); PG8_STAGE(PG8_SB(1, 1), b3 + hstepB, voffB); PG8_STAGE(PG8_SA(1, 0), a3, voffA);
;             PG8_WAIT_V(8); PG8_WAIT_L(0); PG8_BAR; PG8_MMA(1, 0, At, B0); PG8_MMA(1, 1, At, B1); PG8_BAR; PG8_SCHED;
;         }
;         if (wr == 0) PG8_BAR;
	s_add_i32 s22, s70, s28
	v_lshl_add_u64 v[208:209], v[208:209], 0, s[42:43]
	s_mov_b32 m0, s22
	ds_read_b128 v[176:179], v146 offset:49152
	ds_read_b128 v[180:183], v146 offset:50176
	ds_read_b128 v[184:187], v146 offset:51200
	ds_read_b128 v[188:191], v146 offset:52224
	ds_read_b128 v[192:195], v146 offset:53248
	ds_read_b128 v[196:199], v146 offset:54272
	ds_read_b128 v[200:203], v146 offset:55296
	ds_read_b128 v[212:215], v146 offset:56320
	global_load_lds_dwordx4 v[208:209], off
	s_add_i32 m0, s22, 0x2000
	s_add_u32 s20, s20, 0x80080
	v_lshl_add_u64 v[208:209], v[210:211], 0, s[42:43]
	s_addc_u32 s21, s21, 0
	s_add_i32 s22, s71, s28
	global_load_lds_dwordx4 v[208:209], off
	s_mov_b32 m0, s22
	s_nop 0
	global_load_lds_dwordx4 v0, s[20:21]
	s_add_i32 m0, s22, 0x2000
	s_nop 0
	global_load_lds_dwordx4 v130, s[20:21]
	v_lshl_add_u64 v[208:209], v[216:217], 0, s[42:43]
	s_mov_b32 m0, s38
	s_nop 0
	global_load_lds_dwordx4 v[208:209], off
	v_lshl_add_u64 v[208:209], v[226:227], 0, s[42:43]
	s_mov_b32 m0, s39
	s_nop 0
	global_load_lds_dwordx4 v[208:209], off
	s_waitcnt vmcnt(8)
	s_waitcnt lgkmcnt(0)
	s_barrier
	s_setprio 1
	s_waitcnt lgkmcnt(0)
	v_mfma_f32_16x16x32_bf16 v[62:65], v[140:143], v[176:179], v[62:65]
	v_mfma_f32_16x16x32_bf16 v[58:61], v[152:155], v[176:179], v[58:61]
	v_mfma_f32_16x16x32_bf16 v[54:57], v[140:143], v[184:187], v[54:57]
	v_mfma_f32_16x16x32_bf16 v[46:49], v[152:155], v[184:187], v[46:49]
	v_mfma_f32_16x16x32_bf16 v[38:41], v[140:143], v[192:195], v[38:41]
	v_mfma_f32_16x16x32_bf16 v[30:33], v[152:155], v[192:195], v[30:33]
	v_mfma_f32_16x16x32_bf16 v[22:25], v[140:143], v[200:203], v[22:25]
	v_mfma_f32_16x16x32_bf16 v[14:17], v[152:155], v[200:203], v[14:17]
	v_mfma_f32_16x16x32_bf16 v[62:65], v[148:151], v[180:183], v[62:65]
	v_mfma_f32_16x16x32_bf16 v[58:61], v[156:159], v[180:183], v[58:61]
	v_mfma_f32_16x16x32_bf16 v[54:57], v[148:151], v[188:191], v[54:57]
	v_mfma_f32_16x16x32_bf16 v[46:49], v[156:159], v[188:191], v[46:49]
	v_mfma_f32_16x16x32_bf16 v[38:41], v[148:151], v[196:199], v[38:41]
	v_mfma_f32_16x16x32_bf16 v[30:33], v[156:159], v[196:199], v[30:33]
	v_mfma_f32_16x16x32_bf16 v[22:25], v[148:151], v[212:215], v[22:25]
	v_mfma_f32_16x16x32_bf16 v[14:17], v[156:159], v[212:215], v[14:17]
	s_setprio 0
	s_setprio 1
	v_mfma_f32_16x16x32_bf16 v[50:53], v[160:163], v[176:179], v[50:53]
	v_mfma_f32_16x16x32_bf16 v[42:45], v[168:171], v[176:179], v[42:45]
	v_mfma_f32_16x16x32_bf16 v[34:37], v[160:163], v[184:187], v[34:37]
	v_mfma_f32_16x16x32_bf16 v[26:29], v[168:171], v[184:187], v[26:29]
	v_mfma_f32_16x16x32_bf16 v[18:21], v[160:163], v[192:195], v[18:21]
	v_mfma_f32_16x16x32_bf16 v[10:13], v[168:171], v[192:195], v[10:13]
	v_mfma_f32_16x16x32_bf16 v[6:9], v[160:163], v[200:203], v[6:9]
	v_mfma_f32_16x16x32_bf16 v[2:5], v[168:171], v[200:203], v[2:5]
	v_mfma_f32_16x16x32_bf16 v[50:53], v[164:167], v[180:183], v[50:53]
	v_mfma_f32_16x16x32_bf16 v[42:45], v[172:175], v[180:183], v[42:45]
	v_mfma_f32_16x16x32_bf16 v[34:37], v[164:167], v[188:191], v[34:37]
	v_mfma_f32_16x16x32_bf16 v[26:29], v[172:175], v[188:191], v[26:29]
	v_mfma_f32_16x16x32_bf16 v[18:21], v[164:167], v[196:199], v[18:21]
	v_mfma_f32_16x16x32_bf16 v[10:13], v[172:175], v[196:199], v[10:13]
	v_mfma_f32_16x16x32_bf16 v[6:9], v[164:167], v[212:215], v[6:9]
	v_mfma_f32_16x16x32_bf16 v[2:5], v[172:175], v[212:215], v[2:5]
	s_setprio 0
	s_barrier
	s_add_i32 s67, s67, 2
	s_add_u32 s65, s65, 0x100
	s_addc_u32 s66, s66, 0
	s_add_u32 s18, s18, 0x100
	s_addc_u32 s19, s19, 0
	s_cmp_gt_u32 s67, 29
	s_cbranch_scc0 .LBB0_195
	s_and_b64 vcc, exec, s[8:9]
	s_cbranch_vccz .LBB0_198
	s_barrier

; #define PG8_STAGE(bufoff, gbase, voff) do { _Pragma("unroll") for (int _i = 0; _i < 2; ++_i) \
;         __builtin_amdgcn_global_load_lds((const unsigned*)((const char*)(gbase) + (voff)[_i]), (LAS unsigned*)(lds + (bufoff) + ldsw + _i * 8192), 16, 0, 0); } while (0)
; #define PG8_WAIT_V(n) asm volatile("s_waitcnt vmcnt(" #n ")" ::: "memory")
; #define PG8_BAR __builtin_amdgcn_s_barrier()
; template <class Epi>
; __device__ __forceinline__ void gemm_phase(LAS unsigned char* lds, const Gemm g, const StaticOrder& S, const Epi& E, int wave_s) {
;     ...
;     PG8_STAGE(PG8_SB(0, 0), cB, voffB); PG8_STAGE(PG8_SB(0, 1), cB + hstepB, voffB); PG8_STAGE(PG8_SA(0, 0), cA, voffA); PG8_STAGE(PG8_SA(0, 1), cA + hstepA, voffA);
;     if (wr == 1) PG8_BAR;
;     PG8_WAIT_V(2); PG8_BAR;
;     PG8_STAGE(PG8_SB(1, 0), cB + kstep, voffB); PG8_STAGE(PG8_SA(1, 0), cA + kstep, voffA); PG8_STAGE(PG8_SB(1, 1), cB + hstepB + kstep, voffB);
;     PG8_WAIT_V(6); PG8_BAR;
.LBB0_300:
	s_add_u32 s8, s0, 0x1a800000
	s_addc_u32 s9, s1, 0
	s_add_u32 s10, s0, 0x600000
	s_addc_u32 s11, s1, 0
	s_add_u32 s12, s0, 0x200000
	s_addc_u32 s13, s1, 0
	v_and_b32_e32 v10, 48, v0
	v_lshlrev_b32_e32 v11, 6, v0
	s_movk_i32 s1, 0x3c0
	v_lshlrev_b32_e32 v0, 2, v0
	s_lshl_b32 s0, s14, 13
	v_and_or_b32 v10, v11, s1, v10
	v_and_b32_e32 v0, 32, v0
	v_bitop3_b32 v11, v10, s0, v0 bitop3:0xde
	s_lshl_b32 s0, s5, 5
	s_and_b32 s39, s0, 0x60
	s_add_i32 m0, s31, 0x18000
	v_lshl_add_u64 v[8:9], v[8:9], 0, s[42:43]
	s_lshl_b32 s38, s14, 6
	s_lshl_b32 s0, s39, 7
	s_waitcnt vmcnt(2)
	s_barrier
	global_load_lds_dwordx4 v[8:9], off
	v_lshl_add_u64 v[6:7], v[6:7], 0, s[42:43]
	s_add_i32 m0, s31, 0x1a000
	s_add_i32 s40, s31, 0x8000
	s_add_i32 s41, s31, 0xa000
	v_bitop3_b32 v151, s0, v10, v0 bitop3:0xf6
	global_load_lds_dwordx4 v[6:7], off
	v_lshl_add_u64 v[2:3], v[2:3], 0, s[42:43]
	s_mov_b32 m0, s40
	s_add_u32 s0, s24, 0x18080
	global_load_lds_dwordx4 v[2:3], off
	v_lshl_add_u64 v[2:3], v[4:5], 0, s[42:43]
	s_mov_b32 m0, s41
	s_addc_u32 s1, s25, 0
	global_load_lds_dwordx4 v[2:3], off
	s_add_i32 m0, s31, 0x1c000
	s_nop 0
	global_load_lds_dwordx4 v134, s[0:1]
	v_lshl_add_u64 v[2:3], s[0:1], 0, v[130:131]
	s_add_i32 m0, s31, 0x1e000
	s_cmpk_lt_u32 s4, 0x100
	global_load_lds_dwordx4 v[2:3], off
	s_waitcnt vmcnt(6)
	v_readlane_b32 s16, v255, 34
	v_add_u32_e32 v155, 0, v11
	s_cselect_b64 s[14:15], -1, 0
	v_readlane_b32 s17, v255, 35
	v_readlane_b32 s64, v254, 62
	v_readlane_b32 s65, v254, 61
	s_barrier
	s_branch .LBB0_303

; #define PG8_STAGE(bufoff, gbase, voff) do { _Pragma("unroll") for (int _i = 0; _i < 2; ++_i) \
;         __builtin_amdgcn_global_load_lds((const unsigned*)((const char*)(gbase) + (voff)[_i]), (LAS unsigned*)(lds + (bufoff) + ldsw + _i * 8192), 16, 0, 0); } while (0)
; #define PG8_LDA(dst, b, h) do { _Pragma("unroll") for (int m = 0; m < 4; ++m) _Pragma("unroll") for (int k = 0; k < 2; ++k) dst[m][k] = *(const LAS bf16x8*)(lds + PG8_SA(b, h) + aoff + m * 2048 + k * 1024); } while (0)
; #define PG8_LDB(dst, b, h) do { _Pragma("unroll") for (int n = 0; n < 2; ++n) _Pragma("unroll") for (int k = 0; k < 2; ++k) dst[n][k] = *(const LAS bf16x8*)(lds + PG8_SB(b, h) + boff + n * 2048 + k * 1024); } while (0)
; #define PG8_MMA(ai, bj, At, Bt) do { __builtin_amdgcn_s_setprio(1); _Pragma("unroll") for (int m = 0; m < 4; ++m) _Pragma("unroll") for (int n = 0; n < 2; ++n) _Pragma("unroll") for (int k = 0; k < 2; ++k) \
;         acc[ai][bj][m][n] = __builtin_amdgcn_mfma_f32_16x16x32_bf16(Bt[n][k], At[m][k], acc[ai][bj][m][n], 0, 0, 0); __builtin_amdgcn_s_setprio(0); } while (0)
; #define PG8_WAIT_V(n) asm volatile("s_waitcnt vmcnt(" #n ")" ::: "memory")
; #define PG8_WAIT_L(n) asm volatile("s_waitcnt lgkmcnt(" #n ")" ::: "memory")
; #define PG8_BAR __builtin_amdgcn_s_barrier()
; #define PG8_SCHED __builtin_amdgcn_sched_barrier(0)
; template <class Epi>
; __device__ __forceinline__ void gemm_phase(LAS unsigned char* lds, const Gemm g, const StaticOrder& S, const Epi& E, int wave_s) {
;     ...
;             PG8_LDB(B0, 0, 0); PG8_LDB(B1, 0, 1); PG8_SCHED; PG8_LDA(At, 0, 0); PG8_STAGE(PG8_SA(1, 1), a1 + hstepA, voffA);
;             PG8_WAIT_V(8); PG8_WAIT_L(0); PG8_BAR; PG8_MMA(0, 0, At, B0); PG8_MMA(0, 1, At, B1); PG8_BAR; PG8_SCHED;
;             PG8_LDA(At, 0, 1); PG8_STAGE(PG8_SB(0, 0), b2, voffB); PG8_STAGE(PG8_SB(0, 1), b2 + hstepB, voffB); PG8_STAGE(PG8_SA(0, 0), a2, voffA);
;             PG8_WAIT_V(8); PG8_WAIT_L(0); PG8_BAR; PG8_MMA(1, 0, At, B0); PG8_MMA(1, 1, At, B1); PG8_BAR; PG8_SCHED;
;             PG8_LDB(B0, 1, 0); PG8_LDB(B1, 1, 1); PG8_SCHED; PG8_LDA(At, 1, 0); PG8_STAGE(PG8_SA(0, 1), a2 + hstepA, voffA);
;             PG8_WAIT_V(8); PG8_WAIT_L(0); PG8_BAR; PG8_MMA(0, 0, At, B0); PG8_MMA(0, 1, At, B1); PG8_BAR; PG8_SCHED;
.LBB0_309:
	s_add_i32 s70, 0, 0x10000
	s_add_i32 s66, 0, 0x14000
	v_add_u32_e32 v0, s70, v151
	v_add_u32_e32 v10, s66, v151
	ds_read_b128 v[12:15], v0
	ds_read_b128 v[16:19], v0 offset:1024
	ds_read_b128 v[20:23], v0 offset:2048
	ds_read_b128 v[24:27], v0 offset:3072
	ds_read_b128 v[28:31], v10
	ds_read_b128 v[32:35], v10 offset:1024
	ds_read_b128 v[36:39], v10 offset:2048
	ds_read_b128 v[40:43], v10 offset:3072
	s_add_u32 s4, s22, 0x110080
	s_addc_u32 s5, s23, 0
	s_add_i32 s73, s31, 0xc000
	s_mov_b32 m0, s73
	ds_read_b128 v[2:5], v155
	ds_read_b128 v[6:9], v155 offset:1024
	ds_read_b128 v[44:47], v155 offset:2048
	ds_read_b128 v[48:51], v155 offset:3072
	ds_read_b128 v[52:55], v155 offset:4096
	ds_read_b128 v[56:59], v155 offset:5120
	ds_read_b128 v[60:63], v155 offset:6144
	ds_read_b128 v[64:67], v155 offset:7168
	global_load_lds_dwordx4 v136, s[4:5]
	v_lshl_add_u64 v[68:69], s[4:5], 0, v[132:133]
	s_add_i32 s4, s31, 0xe000
	s_mov_b32 m0, s4
	s_nop 0
	global_load_lds_dwordx4 v[68:69], off
	s_waitcnt vmcnt(8)
	s_waitcnt lgkmcnt(0)
	s_barrier
	s_setprio 1
	s_waitcnt lgkmcnt(0)
	v_mfma_f32_16x16x32_bf16 v[68:71], v[12:15], v[2:5], 0
	v_mfma_f32_16x16x32_bf16 v[72:75], v[20:23], v[2:5], 0
	v_mfma_f32_16x16x32_bf16 v[76:79], v[12:15], v[44:47], 0
	v_mfma_f32_16x16x32_bf16 v[80:83], v[20:23], v[44:47], 0
	v_mfma_f32_16x16x32_bf16 v[84:87], v[12:15], v[52:55], 0
	v_mfma_f32_16x16x32_bf16 v[88:91], v[20:23], v[52:55], 0
	v_mfma_f32_16x16x32_bf16 v[92:95], v[12:15], v[60:63], 0
	v_mfma_f32_16x16x32_bf16 v[96:99], v[20:23], v[60:63], 0
	v_mfma_f32_16x16x32_bf16 v[68:71], v[16:19], v[6:9], v[68:71]
	v_mfma_f32_16x16x32_bf16 v[72:75], v[24:27], v[6:9], v[72:75]
	v_mfma_f32_16x16x32_bf16 v[76:79], v[16:19], v[48:51], v[76:79]
	v_mfma_f32_16x16x32_bf16 v[80:83], v[24:27], v[48:51], v[80:83]
	v_mfma_f32_16x16x32_bf16 v[84:87], v[16:19], v[56:59], v[84:87]
	v_mfma_f32_16x16x32_bf16 v[88:91], v[24:27], v[56:59], v[88:91]
	v_mfma_f32_16x16x32_bf16 v[92:95], v[16:19], v[64:67], v[92:95]
	v_mfma_f32_16x16x32_bf16 v[96:99], v[24:27], v[64:67], v[96:99]
	s_setprio 0
	s_setprio 1
	v_mfma_f32_16x16x32_bf16 v[100:103], v[28:31], v[2:5], 0
	v_mfma_f32_16x16x32_bf16 v[2:5], v[36:39], v[2:5], 0
	v_mfma_f32_16x16x32_bf16 v[104:107], v[40:43], v[6:9], v[2:5]
	v_mfma_f32_16x16x32_bf16 v[2:5], v[28:31], v[44:47], 0
	v_mfma_f32_16x16x32_bf16 v[108:111], v[32:35], v[48:51], v[2:5]
	v_mfma_f32_16x16x32_bf16 v[2:5], v[36:39], v[44:47], 0
	v_mfma_f32_16x16x32_bf16 v[44:47], v[40:43], v[48:51], v[2:5]
	v_mfma_f32_16x16x32_bf16 v[2:5], v[28:31], v[52:55], 0
	v_mfma_f32_16x16x32_bf16 v[48:51], v[32:35], v[56:59], v[2:5]
	v_mfma_f32_16x16x32_bf16 v[2:5], v[36:39], v[52:55], 0
	v_mfma_f32_16x16x32_bf16 v[52:55], v[40:43], v[56:59], v[2:5]
	v_mfma_f32_16x16x32_bf16 v[2:5], v[28:31], v[60:63], 0
	v_mfma_f32_16x16x32_bf16 v[56:59], v[32:35], v[64:67], v[2:5]
	v_mfma_f32_16x16x32_bf16 v[2:5], v[36:39], v[60:63], 0
	v_mfma_f32_16x16x32_bf16 v[100:103], v[32:35], v[6:9], v[100:103]
	v_mfma_f32_16x16x32_bf16 v[60:63], v[40:43], v[64:67], v[2:5]
	s_setprio 0
	s_barrier
	s_nop 3
	v_lshl_add_u64 v[2:3], s[24:25], 0, v[134:135]
	s_mov_b64 s[82:83], 0x100
	s_add_i32 s70, s70, s30
	v_lshl_add_u64 v[4:5], v[2:3], 0, s[82:83]
	s_mov_b32 m0, s70
	s_add_i32 s5, s70, 0x2000
	ds_read_b128 v[64:67], v155 offset:16384
	ds_read_b128 v[112:115], v155 offset:17408
	ds_read_b128 v[116:119], v155 offset:18432
	ds_read_b128 v[120:123], v155 offset:19456
	ds_read_b128 v[124:127], v155 offset:20480
	ds_read_b128 v[138:141], v155 offset:21504
	ds_read_b128 v[142:145], v155 offset:22528
	ds_read_b128 v[146:149], v155 offset:23552
	global_load_lds_dwordx4 v[4:5], off
	v_lshl_add_u64 v[4:5], s[24:25], 0, v[130:131]
	s_add_u32 s78, s24, 0x18100
	v_lshl_add_u64 v[6:7], v[4:5], 0, s[82:83]
	s_mov_b32 m0, s5
	s_addc_u32 s79, s25, 0
	s_add_i32 s66, s66, s30
	global_load_lds_dwordx4 v[6:7], off
	s_mov_b32 m0, s66
	s_add_i32 s67, s66, 0x2000
	global_load_lds_dwordx4 v134, s[78:79]
	s_mov_b32 m0, s67
	s_nop 0
	global_load_lds_dwordx4 v130, s[78:79]
	v_lshl_add_u64 v[6:7], s[22:23], 0, v[136:137]
	v_lshl_add_u64 v[8:9], v[6:7], 0, s[82:83]
	s_mov_b32 m0, s31
	s_nop 0
	global_load_lds_dwordx4 v[8:9], off
	v_lshl_add_u64 v[8:9], s[22:23], 0, v[132:133]
	v_lshl_add_u64 v[128:129], v[8:9], 0, s[82:83]
	s_mov_b32 m0, s34
	s_nop 0
	global_load_lds_dwordx4 v[128:129], off
	s_waitcnt vmcnt(8)
	s_waitcnt lgkmcnt(0)
	s_barrier
	s_setprio 1
	s_waitcnt lgkmcnt(0)
	v_mfma_f32_16x16x32_bf16 v[156:159], v[12:15], v[64:67], 0
	v_mfma_f32_16x16x32_bf16 v[164:167], v[12:15], v[116:119], 0
	v_mfma_f32_16x16x32_bf16 v[172:175], v[12:15], v[124:127], 0
	v_mfma_f32_16x16x32_bf16 v[12:15], v[12:15], v[142:145], 0
	v_mfma_f32_16x16x32_bf16 v[156:159], v[16:19], v[112:115], v[156:159]
	v_mfma_f32_16x16x32_bf16 v[160:163], v[20:23], v[64:67], 0
	v_mfma_f32_16x16x32_bf16 v[164:167], v[16:19], v[120:123], v[164:167]
	v_mfma_f32_16x16x32_bf16 v[168:171], v[20:23], v[116:119], 0
	v_mfma_f32_16x16x32_bf16 v[172:175], v[16:19], v[138:141], v[172:175]
	v_mfma_f32_16x16x32_bf16 v[176:179], v[20:23], v[124:127], 0
	v_mfma_f32_16x16x32_bf16 v[14:17], v[16:19], v[146:149], v[12:15]
	v_mfma_f32_16x16x32_bf16 v[18:21], v[20:23], v[142:145], 0
	v_mfma_f32_16x16x32_bf16 v[18:21], v[24:27], v[146:149], v[18:21]
	v_mfma_f32_16x16x32_bf16 v[160:163], v[24:27], v[112:115], v[160:163]
	v_mfma_f32_16x16x32_bf16 v[168:171], v[24:27], v[120:123], v[168:171]
	v_mfma_f32_16x16x32_bf16 v[176:179], v[24:27], v[138:141], v[176:179]
	s_setprio 0
	s_setprio 1
	v_mfma_f32_16x16x32_bf16 v[22:25], v[28:31], v[64:67], 0
	v_mfma_f32_16x16x32_bf16 v[64:67], v[36:39], v[64:67], 0
	v_mfma_f32_16x16x32_bf16 v[22:25], v[32:35], v[112:115], v[22:25]
	v_mfma_f32_16x16x32_bf16 v[64:67], v[40:43], v[112:115], v[64:67]
	v_mfma_f32_16x16x32_bf16 v[112:115], v[28:31], v[116:119], 0
	v_mfma_f32_16x16x32_bf16 v[116:119], v[36:39], v[116:119], 0
	v_mfma_f32_16x16x32_bf16 v[112:115], v[32:35], v[120:123], v[112:115]
	v_mfma_f32_16x16x32_bf16 v[116:119], v[40:43], v[120:123], v[116:119]
	v_mfma_f32_16x16x32_bf16 v[120:123], v[28:31], v[124:127], 0
	v_mfma_f32_16x16x32_bf16 v[26:29], v[28:31], v[142:145], 0
	v_mfma_f32_16x16x32_bf16 v[120:123], v[32:35], v[138:141], v[120:123]
	v_mfma_f32_16x16x32_bf16 v[124:127], v[36:39], v[124:127], 0
	v_mfma_f32_16x16x32_bf16 v[26:29], v[32:35], v[146:149], v[26:29]
	v_mfma_f32_16x16x32_bf16 v[30:33], v[36:39], v[142:145], 0
	v_mfma_f32_16x16x32_bf16 v[124:127], v[40:43], v[138:141], v[124:127]
	v_mfma_f32_16x16x32_bf16 v[30:33], v[40:43], v[146:149], v[30:33]
	s_setprio 0
	s_barrier
; #define PG8_STAGE(bufoff, gbase, voff) do { _Pragma("unroll") for (int _i = 0; _i < 2; ++_i) \
;         __builtin_amdgcn_global_load_lds((const unsigned*)((const char*)(gbase) + (voff)[_i]), (LAS unsigned*)(lds + (bufoff) + ldsw + _i * 8192), 16, 0, 0); } while (0)
; #define PG8_LDA(dst, b, h) do { _Pragma("unroll") for (int m = 0; m < 4; ++m) _Pragma("unroll") for (int k = 0; k < 2; ++k) dst[m][k] = *(const LAS bf16x8*)(lds + PG8_SA(b, h) + aoff + m * 2048 + k * 1024); } while (0)
; #define PG8_LDB(dst, b, h) do { _Pragma("unroll") for (int n = 0; n < 2; ++n) _Pragma("unroll") for (int k = 0; k < 2; ++k) dst[n][k] = *(const LAS bf16x8*)(lds + PG8_SB(b, h) + boff + n * 2048 + k * 1024); } while (0)
; #define PG8_MMA(ai, bj, At, Bt) do { __builtin_amdgcn_s_setprio(1); _Pragma("unroll") for (int m = 0; m < 4; ++m) _Pragma("unroll") for (int n = 0; n < 2; ++n) _Pragma("unroll") for (int k = 0; k < 2; ++k) \
;         acc[ai][bj][m][n] = __builtin_amdgcn_mfma_f32_16x16x32_bf16(Bt[n][k], At[m][k], acc[ai][bj][m][n], 0, 0, 0); __builtin_amdgcn_s_setprio(0); } while (0)
; #define PG8_WAIT_V(n) asm volatile("s_waitcnt vmcnt(" #n ")" ::: "memory")
; #define PG8_WAIT_L(n) asm volatile("s_waitcnt lgkmcnt(" #n ")" ::: "memory")
; #define PG8_BAR __builtin_amdgcn_s_barrier()
; #define PG8_SCHED __builtin_amdgcn_sched_barrier(0)
; template <class Epi>
; __device__ __forceinline__ void gemm_phase(LAS unsigned char* lds, const Gemm g, const StaticOrder& S, const Epi& E, int wave_s) {
;     ...
;             PG8_LDB(B0, 1, 0); PG8_LDB(B1, 1, 1); PG8_SCHED; PG8_LDA(At, 1, 0); PG8_STAGE(PG8_SA(0, 1), a2 + hstepA, voffA);
;             PG8_WAIT_V(8); PG8_WAIT_L(0); PG8_BAR; PG8_MMA(0, 0, At, B0); PG8_MMA(0, 1, At, B1); PG8_BAR; PG8_SCHED;
;             PG8_LDA(At, 1, 1); PG8_STAGE(PG8_SB(1, 0), b3, voffB); PG8_STAGE(PG8_SB(1, 1), b3 + hstepB, voffB); PG8_STAGE(PG8_SA(1, 0), a3, voffA);
;             PG8_WAIT_V(8); PG8_WAIT_L(0); PG8_BAR; PG8_MMA(1, 0, At, B0); PG8_MMA(1, 1, At, B1); PG8_BAR; PG8_SCHED;
	s_add_i32 s71, 0, 0x18000
	s_add_i32 s72, 0, 0x1c000
	v_add_u32_e32 v11, s71, v151
	v_add_u32_e32 v12, s72, v151
	ds_read_b128 v[34:37], v11
	ds_read_b128 v[38:41], v11 offset:1024
	ds_read_b128 v[138:141], v11 offset:2048
	ds_read_b128 v[142:145], v11 offset:3072
	ds_read_b128 v[146:149], v12
	ds_read_b128 v[180:183], v12 offset:1024
	ds_read_b128 v[184:187], v12 offset:2048
	ds_read_b128 v[188:191], v12 offset:3072
	s_add_u32 s78, s22, 0x110100
	s_addc_u32 s79, s23, 0
	s_mov_b32 m0, s35
	ds_read_b128 v[192:195], v155 offset:32768
	ds_read_b128 v[196:199], v155 offset:33792
	ds_read_b128 v[200:203], v155 offset:34816
	ds_read_b128 v[212:215], v155 offset:35840
	ds_read_b128 v[226:229], v155 offset:36864
	ds_read_b128 v[230:233], v155 offset:37888
	ds_read_b128 v[234:237], v155 offset:38912
	ds_read_b128 v[238:241], v155 offset:39936
	global_load_lds_dwordx4 v136, s[78:79]
	v_lshl_add_u64 v[42:43], s[78:79], 0, v[132:133]
	s_mov_b32 m0, s37
	s_nop 0
	global_load_lds_dwordx4 v[42:43], off
	s_waitcnt vmcnt(8)
	s_waitcnt lgkmcnt(0)
	s_barrier
	s_setprio 1
	s_waitcnt lgkmcnt(0)
	v_mfma_f32_16x16x32_bf16 v[68:71], v[34:37], v[192:195], v[68:71]
	v_mfma_f32_16x16x32_bf16 v[72:75], v[138:141], v[192:195], v[72:75]
	v_mfma_f32_16x16x32_bf16 v[76:79], v[34:37], v[200:203], v[76:79]
	v_mfma_f32_16x16x32_bf16 v[80:83], v[138:141], v[200:203], v[80:83]
	v_mfma_f32_16x16x32_bf16 v[84:87], v[34:37], v[226:229], v[84:87]
	v_mfma_f32_16x16x32_bf16 v[88:91], v[138:141], v[226:229], v[88:91]
	v_mfma_f32_16x16x32_bf16 v[92:95], v[34:37], v[234:237], v[92:95]
	v_mfma_f32_16x16x32_bf16 v[96:99], v[138:141], v[234:237], v[96:99]
	v_mfma_f32_16x16x32_bf16 v[68:71], v[38:41], v[196:199], v[68:71]
	v_mfma_f32_16x16x32_bf16 v[72:75], v[142:145], v[196:199], v[72:75]
	v_mfma_f32_16x16x32_bf16 v[76:79], v[38:41], v[212:215], v[76:79]
	v_mfma_f32_16x16x32_bf16 v[80:83], v[142:145], v[212:215], v[80:83]
	v_mfma_f32_16x16x32_bf16 v[84:87], v[38:41], v[230:233], v[84:87]
	v_mfma_f32_16x16x32_bf16 v[88:91], v[142:145], v[230:233], v[88:91]
	v_mfma_f32_16x16x32_bf16 v[92:95], v[38:41], v[238:241], v[92:95]
	v_mfma_f32_16x16x32_bf16 v[96:99], v[142:145], v[238:241], v[96:99]
	s_setprio 0
	s_setprio 1
	v_mfma_f32_16x16x32_bf16 v[100:103], v[146:149], v[192:195], v[100:103]
	v_mfma_f32_16x16x32_bf16 v[104:107], v[184:187], v[192:195], v[104:107]
	v_mfma_f32_16x16x32_bf16 v[108:111], v[146:149], v[200:203], v[108:111]
	v_mfma_f32_16x16x32_bf16 v[42:45], v[184:187], v[200:203], v[44:47]
	v_mfma_f32_16x16x32_bf16 v[46:49], v[146:149], v[226:229], v[48:51]
	v_mfma_f32_16x16x32_bf16 v[50:53], v[184:187], v[226:229], v[52:55]
	v_mfma_f32_16x16x32_bf16 v[54:57], v[146:149], v[234:237], v[56:59]
	v_mfma_f32_16x16x32_bf16 v[58:61], v[184:187], v[234:237], v[60:63]
	v_mfma_f32_16x16x32_bf16 v[100:103], v[180:183], v[196:199], v[100:103]
	v_mfma_f32_16x16x32_bf16 v[104:107], v[188:191], v[196:199], v[104:107]
	v_mfma_f32_16x16x32_bf16 v[108:111], v[180:183], v[212:215], v[108:111]
	v_mfma_f32_16x16x32_bf16 v[42:45], v[188:191], v[212:215], v[42:45]
	v_mfma_f32_16x16x32_bf16 v[46:49], v[180:183], v[230:233], v[46:49]
	v_mfma_f32_16x16x32_bf16 v[50:53], v[188:191], v[230:233], v[50:53]
	v_mfma_f32_16x16x32_bf16 v[54:57], v[180:183], v[238:241], v[54:57]
	v_mfma_f32_16x16x32_bf16 v[58:61], v[188:191], v[238:241], v[58:61]
	s_setprio 0
	s_barrier
	s_add_i32 s79, s71, s30
	s_mov_b64 s[88:89], 0x180
	s_add_i32 s71, s79, 0x2000
	v_lshl_add_u64 v[62:63], v[2:3], 0, s[88:89]
	s_mov_b32 m0, s79
	s_add_u32 s82, s24, 0x18180
	ds_read_b128 v[192:195], v155 offset:49152
	ds_read_b128 v[196:199], v155 offset:50176
	ds_read_b128 v[200:203], v155 offset:51200
	ds_read_b128 v[212:215], v155 offset:52224
	ds_read_b128 v[226:229], v155 offset:53248
	ds_read_b128 v[230:233], v155 offset:54272
	ds_read_b128 v[234:237], v155 offset:55296
	ds_read_b128 v[238:241], v155 offset:56320
	global_load_lds_dwordx4 v[62:63], off
	v_lshl_add_u64 v[62:63], v[4:5], 0, s[88:89]
	s_mov_b32 m0, s71
	s_addc_u32 s83, s25, 0
	s_add_i32 s72, s72, s30
	global_load_lds_dwordx4 v[62:63], off
	s_mov_b32 m0, s72
	s_add_i32 s78, s72, 0x2000
	global_load_lds_dwordx4 v134, s[82:83]
	s_mov_b32 m0, s78
	s_nop 0
	global_load_lds_dwordx4 v130, s[82:83]
	v_lshl_add_u64 v[62:63], v[6:7], 0, s[88:89]
	s_mov_b32 m0, s40
	s_nop 0
	global_load_lds_dwordx4 v[62:63], off
	v_lshl_add_u64 v[62:63], v[8:9], 0, s[88:89]
	s_mov_b32 m0, s41
	s_nop 0
	global_load_lds_dwordx4 v[62:63], off
	s_waitcnt vmcnt(8)
	s_waitcnt lgkmcnt(0)
	s_barrier
; #define PG8_STAGE(bufoff, gbase, voff) do { _Pragma("unroll") for (int _i = 0; _i < 2; ++_i) \
;         __builtin_amdgcn_global_load_lds((const unsigned*)((const char*)(gbase) + (voff)[_i]), (LAS unsigned*)(lds + (bufoff) + ldsw + _i * 8192), 16, 0, 0); } while (0)
; #define PG8_LDA(dst, b, h) do { _Pragma("unroll") for (int m = 0; m < 4; ++m) _Pragma("unroll") for (int k = 0; k < 2; ++k) dst[m][k] = *(const LAS bf16x8*)(lds + PG8_SA(b, h) + aoff + m * 2048 + k * 1024); } while (0)
; #define PG8_LDB(dst, b, h) do { _Pragma("unroll") for (int n = 0; n < 2; ++n) _Pragma("unroll") for (int k = 0; k < 2; ++k) dst[n][k] = *(const LAS bf16x8*)(lds + PG8_SB(b, h) + boff + n * 2048 + k * 1024); } while (0)
; #define PG8_MMA(ai, bj, At, Bt) do { __builtin_amdgcn_s_setprio(1); _Pragma("unroll") for (int m = 0; m < 4; ++m) _Pragma("unroll") for (int n = 0; n < 2; ++n) _Pragma("unroll") for (int k = 0; k < 2; ++k) \
;         acc[ai][bj][m][n] = __builtin_amdgcn_mfma_f32_16x16x32_bf16(Bt[n][k], At[m][k], acc[ai][bj][m][n], 0, 0, 0); __builtin_amdgcn_s_setprio(0); } while (0)
; #define PG8_WAIT_V(n) asm volatile("s_waitcnt vmcnt(" #n ")" ::: "memory")
; #define PG8_BAR __builtin_amdgcn_s_barrier()
; template <class Epi>
; __device__ __forceinline__ void gemm_phase(LAS unsigned char* lds, const Gemm g, const StaticOrder& S, const Epi& E, int wave_s) {
;     ...
;             PG8_LDB(B0, 0, 0); PG8_LDB(B1, 0, 1); PG8_SCHED; PG8_LDA(At, 0, 0); PG8_STAGE(PG8_SA(1, 1), a1 + hstepA, voffA);
;             PG8_WAIT_V(8); PG8_WAIT_L(0); PG8_BAR; PG8_MMA(0, 0, At, B0); PG8_MMA(0, 1, At, B1); PG8_BAR; PG8_SCHED;
;             PG8_LDA(At, 0, 1); PG8_STAGE(PG8_SB(0, 0), b2, voffB); PG8_STAGE(PG8_SB(0, 1), b2 + hstepB, voffB); PG8_STAGE(PG8_SA(0, 0), a2, voffA);
;             PG8_WAIT_V(8); PG8_WAIT_L(0); PG8_BAR; PG8_MMA(1, 0, At, B0); PG8_MMA(1, 1, At, B1); PG8_BAR; PG8_SCHED;
;             PG8_LDB(B0, 1, 0); PG8_LDB(B1, 1, 1); PG8_SCHED; PG8_LDA(At, 1, 0); PG8_STAGE(PG8_SA(0, 1), a2 + hstepA, voffA);
;             PG8_WAIT_V(8); PG8_WAIT_L(0); PG8_BAR; PG8_MMA(0, 0, At, B0); PG8_MMA(0, 1, At, B1); PG8_BAR; PG8_SCHED;
;             PG8_LDA(At, 1, 1); PG8_STAGE(PG8_SB(1, 0), b3, voffB); PG8_STAGE(PG8_SB(1, 1), b3 + hstepB, voffB); PG8_STAGE(PG8_SA(1, 0), a3, voffA);
;             PG8_WAIT_V(8); PG8_WAIT_L(0); PG8_BAR; PG8_MMA(1, 0, At, B0); PG8_MMA(1, 1, At, B1); PG8_BAR; PG8_SCHED;
	s_setprio 1
	s_waitcnt lgkmcnt(0)
	v_mfma_f32_16x16x32_bf16 v[14:17], v[34:37], v[234:237], v[14:17]
	v_mfma_f32_16x16x32_bf16 v[18:21], v[138:141], v[234:237], v[18:21]
	v_mfma_f32_16x16x32_bf16 v[156:159], v[34:37], v[192:195], v[156:159]
	v_mfma_f32_16x16x32_bf16 v[160:163], v[138:141], v[192:195], v[160:163]
	v_mfma_f32_16x16x32_bf16 v[164:167], v[34:37], v[200:203], v[164:167]
	v_mfma_f32_16x16x32_bf16 v[168:171], v[138:141], v[200:203], v[168:171]
	v_mfma_f32_16x16x32_bf16 v[172:175], v[34:37], v[226:229], v[172:175]
	v_mfma_f32_16x16x32_bf16 v[176:179], v[138:141], v[226:229], v[176:179]
	v_mfma_f32_16x16x32_bf16 v[14:17], v[38:41], v[238:241], v[14:17]
	v_mfma_f32_16x16x32_bf16 v[18:21], v[142:145], v[238:241], v[18:21]
	v_mfma_f32_16x16x32_bf16 v[156:159], v[38:41], v[196:199], v[156:159]
	v_mfma_f32_16x16x32_bf16 v[160:163], v[142:145], v[196:199], v[160:163]
	v_mfma_f32_16x16x32_bf16 v[164:167], v[38:41], v[212:215], v[164:167]
	v_mfma_f32_16x16x32_bf16 v[168:171], v[142:145], v[212:215], v[168:171]
	v_mfma_f32_16x16x32_bf16 v[172:175], v[38:41], v[230:233], v[172:175]
	v_mfma_f32_16x16x32_bf16 v[176:179], v[142:145], v[230:233], v[176:179]
	s_setprio 0
	s_setprio 1
	v_mfma_f32_16x16x32_bf16 v[22:25], v[146:149], v[192:195], v[22:25]
	v_mfma_f32_16x16x32_bf16 v[34:37], v[184:187], v[192:195], v[64:67]
	v_mfma_f32_16x16x32_bf16 v[38:41], v[146:149], v[200:203], v[112:115]
	v_mfma_f32_16x16x32_bf16 v[62:65], v[184:187], v[200:203], v[116:119]
	v_mfma_f32_16x16x32_bf16 v[112:115], v[146:149], v[226:229], v[120:123]
	v_mfma_f32_16x16x32_bf16 v[116:119], v[184:187], v[226:229], v[124:127]
	v_mfma_f32_16x16x32_bf16 v[26:29], v[146:149], v[234:237], v[26:29]
	v_mfma_f32_16x16x32_bf16 v[30:33], v[184:187], v[234:237], v[30:33]
	v_mfma_f32_16x16x32_bf16 v[22:25], v[180:183], v[196:199], v[22:25]
	v_mfma_f32_16x16x32_bf16 v[34:37], v[188:191], v[196:199], v[34:37]
	v_mfma_f32_16x16x32_bf16 v[38:41], v[180:183], v[212:215], v[38:41]
	v_mfma_f32_16x16x32_bf16 v[62:65], v[188:191], v[212:215], v[62:65]
	v_mfma_f32_16x16x32_bf16 v[112:115], v[180:183], v[230:233], v[112:115]
	v_mfma_f32_16x16x32_bf16 v[116:119], v[188:191], v[230:233], v[116:119]
	v_mfma_f32_16x16x32_bf16 v[26:29], v[180:183], v[238:241], v[26:29]
	v_mfma_f32_16x16x32_bf16 v[30:33], v[188:191], v[238:241], v[30:33]
	s_setprio 0
	s_barrier
	ds_read_b128 v[120:123], v0
	ds_read_b128 v[124:127], v0 offset:1024
	ds_read_b128 v[138:141], v0 offset:2048
	ds_read_b128 v[142:145], v0 offset:3072
	ds_read_b128 v[146:149], v10
	ds_read_b128 v[180:183], v10 offset:1024
	ds_read_b128 v[184:187], v10 offset:2048
	ds_read_b128 v[188:191], v10 offset:3072
	s_add_u32 s82, s22, 0x110180
	s_addc_u32 s83, s23, 0
	s_mov_b32 m0, s73
	ds_read_b128 v[192:195], v155
	ds_read_b128 v[196:199], v155 offset:1024
	ds_read_b128 v[200:203], v155 offset:2048
	ds_read_b128 v[212:215], v155 offset:3072
	ds_read_b128 v[226:229], v155 offset:4096
	ds_read_b128 v[230:233], v155 offset:5120
	ds_read_b128 v[234:237], v155 offset:6144
	ds_read_b128 v[238:241], v155 offset:7168
	global_load_lds_dwordx4 v136, s[82:83]
	v_lshl_add_u64 v[66:67], s[82:83], 0, v[132:133]
	s_mov_b32 m0, s4
	s_nop 0
	global_load_lds_dwordx4 v[66:67], off
	s_waitcnt vmcnt(8)
	s_waitcnt lgkmcnt(0)
	s_barrier
	s_setprio 1
	s_waitcnt lgkmcnt(0)
	v_mfma_f32_16x16x32_bf16 v[66:69], v[120:123], v[192:195], v[68:71]
	v_mfma_f32_16x16x32_bf16 v[70:73], v[138:141], v[192:195], v[72:75]
	v_mfma_f32_16x16x32_bf16 v[74:77], v[120:123], v[200:203], v[76:79]
	v_mfma_f32_16x16x32_bf16 v[78:81], v[138:141], v[200:203], v[80:83]
	v_mfma_f32_16x16x32_bf16 v[82:85], v[120:123], v[226:229], v[84:87]
	v_mfma_f32_16x16x32_bf16 v[86:89], v[138:141], v[226:229], v[88:91]
	v_mfma_f32_16x16x32_bf16 v[90:93], v[120:123], v[234:237], v[92:95]
	v_mfma_f32_16x16x32_bf16 v[94:97], v[138:141], v[234:237], v[96:99]
	v_mfma_f32_16x16x32_bf16 v[66:69], v[124:127], v[196:199], v[66:69]
	v_mfma_f32_16x16x32_bf16 v[70:73], v[142:145], v[196:199], v[70:73]
	v_mfma_f32_16x16x32_bf16 v[74:77], v[124:127], v[212:215], v[74:77]
	v_mfma_f32_16x16x32_bf16 v[78:81], v[142:145], v[212:215], v[78:81]
	v_mfma_f32_16x16x32_bf16 v[82:85], v[124:127], v[230:233], v[82:85]
	v_mfma_f32_16x16x32_bf16 v[86:89], v[142:145], v[230:233], v[86:89]
	v_mfma_f32_16x16x32_bf16 v[90:93], v[124:127], v[238:241], v[90:93]
	v_mfma_f32_16x16x32_bf16 v[94:97], v[142:145], v[238:241], v[94:97]
	s_setprio 0
	s_setprio 1
	v_mfma_f32_16x16x32_bf16 v[98:101], v[146:149], v[192:195], v[100:103]
	v_mfma_f32_16x16x32_bf16 v[102:105], v[184:187], v[192:195], v[104:107]
	v_mfma_f32_16x16x32_bf16 v[106:109], v[146:149], v[200:203], v[108:111]
	v_mfma_f32_16x16x32_bf16 v[42:45], v[184:187], v[200:203], v[42:45]
	v_mfma_f32_16x16x32_bf16 v[46:49], v[146:149], v[226:229], v[46:49]
	v_mfma_f32_16x16x32_bf16 v[50:53], v[184:187], v[226:229], v[50:53]
	v_mfma_f32_16x16x32_bf16 v[54:57], v[146:149], v[234:237], v[54:57]
	v_mfma_f32_16x16x32_bf16 v[58:61], v[184:187], v[234:237], v[58:61]
	v_mfma_f32_16x16x32_bf16 v[98:101], v[180:183], v[196:199], v[98:101]
	v_mfma_f32_16x16x32_bf16 v[102:105], v[188:191], v[196:199], v[102:105]
	v_mfma_f32_16x16x32_bf16 v[106:109], v[180:183], v[212:215], v[106:109]
	v_mfma_f32_16x16x32_bf16 v[42:45], v[188:191], v[212:215], v[42:45]
	v_mfma_f32_16x16x32_bf16 v[46:49], v[180:183], v[230:233], v[46:49]
	v_mfma_f32_16x16x32_bf16 v[50:53], v[188:191], v[230:233], v[50:53]
	v_mfma_f32_16x16x32_bf16 v[54:57], v[180:183], v[238:241], v[54:57]
	v_mfma_f32_16x16x32_bf16 v[58:61], v[188:191], v[238:241], v[58:61]
	s_setprio 0
	s_barrier
; #define PG8_STAGE(bufoff, gbase, voff) do { _Pragma("unroll") for (int _i = 0; _i < 2; ++_i) \
;         __builtin_amdgcn_global_load_lds((const unsigned*)((const char*)(gbase) + (voff)[_i]), (LAS unsigned*)(lds + (bufoff) + ldsw + _i * 8192), 16, 0, 0); } while (0)
; #define PG8_LDA(dst, b, h) do { _Pragma("unroll") for (int m = 0; m < 4; ++m) _Pragma("unroll") for (int k = 0; k < 2; ++k) dst[m][k] = *(const LAS bf16x8*)(lds + PG8_SA(b, h) + aoff + m * 2048 + k * 1024); } while (0)
; #define PG8_LDB(dst, b, h) do { _Pragma("unroll") for (int n = 0; n < 2; ++n) _Pragma("unroll") for (int k = 0; k < 2; ++k) dst[n][k] = *(const LAS bf16x8*)(lds + PG8_SB(b, h) + boff + n * 2048 + k * 1024); } while (0)
; #define PG8_MMA(ai, bj, At, Bt) do { __builtin_amdgcn_s_setprio(1); _Pragma("unroll") for (int m = 0; m < 4; ++m) _Pragma("unroll") for (int n = 0; n < 2; ++n) _Pragma("unroll") for (int k = 0; k < 2; ++k) \
;         acc[ai][bj][m][n] = __builtin_amdgcn_mfma_f32_16x16x32_bf16(Bt[n][k], At[m][k], acc[ai][bj][m][n], 0, 0, 0); __builtin_amdgcn_s_setprio(0); } while (0)
; #define PG8_WAIT_V(n) asm volatile("s_waitcnt vmcnt(" #n ")" ::: "memory")
; #define PG8_WAIT_L(n) asm volatile("s_waitcnt lgkmcnt(" #n ")" ::: "memory")
; #define PG8_BAR __builtin_amdgcn_s_barrier()
; #define PG8_SCHED __builtin_amdgcn_sched_barrier(0)
; template <class Epi>
; __device__ __forceinline__ void gemm_phase(LAS unsigned char* lds, const Gemm g, const StaticOrder& S, const Epi& E, int wave_s) {
;     ...
;             PG8_LDA(At, 0, 1); PG8_STAGE(PG8_SB(0, 0), b2, voffB); PG8_STAGE(PG8_SB(0, 1), b2 + hstepB, voffB); PG8_STAGE(PG8_SA(0, 0), a2, voffA);
;             PG8_WAIT_V(8); PG8_WAIT_L(0); PG8_BAR; PG8_MMA(1, 0, At, B0); PG8_MMA(1, 1, At, B1); PG8_BAR; PG8_SCHED;
;             PG8_LDB(B0, 1, 0); PG8_LDB(B1, 1, 1); PG8_SCHED; PG8_LDA(At, 1, 0); PG8_STAGE(PG8_SA(0, 1), a2 + hstepA, voffA);
;             PG8_WAIT_V(8); PG8_WAIT_L(0); PG8_BAR; PG8_MMA(0, 0, At, B0); PG8_MMA(0, 1, At, B1); PG8_BAR; PG8_SCHED;
	s_mov_b64 s[88:89], 0x200
	s_mov_b32 m0, s70
	v_lshl_add_u64 v[110:111], v[2:3], 0, s[88:89]
	s_add_u32 s82, s24, 0x18200
	ds_read_b128 v[192:195], v155 offset:16384
	ds_read_b128 v[196:199], v155 offset:17408
	ds_read_b128 v[200:203], v155 offset:18432
	ds_read_b128 v[212:215], v155 offset:19456
	ds_read_b128 v[226:229], v155 offset:20480
	ds_read_b128 v[230:233], v155 offset:21504
	ds_read_b128 v[234:237], v155 offset:22528
	ds_read_b128 v[238:241], v155 offset:23552
	global_load_lds_dwordx4 v[110:111], off
	v_lshl_add_u64 v[110:111], v[4:5], 0, s[88:89]
	s_mov_b32 m0, s5
	s_addc_u32 s83, s25, 0
	global_load_lds_dwordx4 v[110:111], off
	s_mov_b32 m0, s66
	s_nop 0
	global_load_lds_dwordx4 v134, s[82:83]
	s_mov_b32 m0, s67
	s_nop 0
	global_load_lds_dwordx4 v130, s[82:83]
	v_lshl_add_u64 v[110:111], v[6:7], 0, s[88:89]
	s_mov_b32 m0, s31
	s_nop 0
	global_load_lds_dwordx4 v[110:111], off
	v_lshl_add_u64 v[110:111], v[8:9], 0, s[88:89]
	s_mov_b32 m0, s34
	s_nop 0
	global_load_lds_dwordx4 v[110:111], off
	s_waitcnt vmcnt(8)
	s_waitcnt lgkmcnt(0)
	s_barrier
	s_setprio 1
	s_waitcnt lgkmcnt(0)
	v_mfma_f32_16x16x32_bf16 v[14:17], v[120:123], v[234:237], v[14:17]
	v_mfma_f32_16x16x32_bf16 v[18:21], v[138:141], v[234:237], v[18:21]
	v_mfma_f32_16x16x32_bf16 v[156:159], v[120:123], v[192:195], v[156:159]
	v_mfma_f32_16x16x32_bf16 v[160:163], v[138:141], v[192:195], v[160:163]
	v_mfma_f32_16x16x32_bf16 v[164:167], v[120:123], v[200:203], v[164:167]
	v_mfma_f32_16x16x32_bf16 v[168:171], v[138:141], v[200:203], v[168:171]
	v_mfma_f32_16x16x32_bf16 v[172:175], v[120:123], v[226:229], v[172:175]
	v_mfma_f32_16x16x32_bf16 v[176:179], v[138:141], v[226:229], v[176:179]
	v_mfma_f32_16x16x32_bf16 v[14:17], v[124:127], v[238:241], v[14:17]
	v_mfma_f32_16x16x32_bf16 v[18:21], v[142:145], v[238:241], v[18:21]
	v_mfma_f32_16x16x32_bf16 v[156:159], v[124:127], v[196:199], v[156:159]
	v_mfma_f32_16x16x32_bf16 v[160:163], v[142:145], v[196:199], v[160:163]
	v_mfma_f32_16x16x32_bf16 v[164:167], v[124:127], v[212:215], v[164:167]
	v_mfma_f32_16x16x32_bf16 v[168:171], v[142:145], v[212:215], v[168:171]
	v_mfma_f32_16x16x32_bf16 v[172:175], v[124:127], v[230:233], v[172:175]
	v_mfma_f32_16x16x32_bf16 v[176:179], v[142:145], v[230:233], v[176:179]
	s_setprio 0
	s_setprio 1
	v_mfma_f32_16x16x32_bf16 v[22:25], v[146:149], v[192:195], v[22:25]
	v_mfma_f32_16x16x32_bf16 v[34:37], v[184:187], v[192:195], v[34:37]
	v_mfma_f32_16x16x32_bf16 v[38:41], v[146:149], v[200:203], v[38:41]
	v_mfma_f32_16x16x32_bf16 v[62:65], v[184:187], v[200:203], v[62:65]
	v_mfma_f32_16x16x32_bf16 v[110:113], v[146:149], v[226:229], v[112:115]
	v_mfma_f32_16x16x32_bf16 v[114:117], v[184:187], v[226:229], v[116:119]
	v_mfma_f32_16x16x32_bf16 v[26:29], v[146:149], v[234:237], v[26:29]
	v_mfma_f32_16x16x32_bf16 v[30:33], v[184:187], v[234:237], v[30:33]
	v_mfma_f32_16x16x32_bf16 v[22:25], v[180:183], v[196:199], v[22:25]
	v_mfma_f32_16x16x32_bf16 v[34:37], v[188:191], v[196:199], v[34:37]
	v_mfma_f32_16x16x32_bf16 v[38:41], v[180:183], v[212:215], v[38:41]
	v_mfma_f32_16x16x32_bf16 v[62:65], v[188:191], v[212:215], v[62:65]
	v_mfma_f32_16x16x32_bf16 v[110:113], v[180:183], v[230:233], v[110:113]
	v_mfma_f32_16x16x32_bf16 v[114:117], v[188:191], v[230:233], v[114:117]
	v_mfma_f32_16x16x32_bf16 v[26:29], v[180:183], v[238:241], v[26:29]
	v_mfma_f32_16x16x32_bf16 v[30:33], v[188:191], v[238:241], v[30:33]
	s_setprio 0
	s_barrier
	ds_read_b128 v[118:121], v11
	ds_read_b128 v[122:125], v11 offset:1024
	ds_read_b128 v[126:129], v11 offset:2048
	ds_read_b128 v[138:141], v11 offset:3072
	ds_read_b128 v[142:145], v12
	ds_read_b128 v[146:149], v12 offset:1024
	ds_read_b128 v[180:183], v12 offset:2048
	ds_read_b128 v[184:187], v12 offset:3072
	s_add_u32 s82, s22, 0x110200
	s_addc_u32 s83, s23, 0
	s_mov_b32 m0, s35
	ds_read_b128 v[188:191], v155 offset:32768
	ds_read_b128 v[192:195], v155 offset:33792
	ds_read_b128 v[196:199], v155 offset:34816
	ds_read_b128 v[200:203], v155 offset:35840
	ds_read_b128 v[212:215], v155 offset:36864
	ds_read_b128 v[226:229], v155 offset:37888
	ds_read_b128 v[230:233], v155 offset:38912
	ds_read_b128 v[234:237], v155 offset:39936
	global_load_lds_dwordx4 v136, s[82:83]
	s_mov_b32 m0, s37
	s_nop 0
	global_load_lds_dwordx4 v132, s[82:83]
	s_waitcnt vmcnt(8)
	s_waitcnt lgkmcnt(0)
	s_barrier
	s_setprio 1
	s_waitcnt lgkmcnt(0)
	v_mfma_f32_16x16x32_bf16 v[66:69], v[118:121], v[188:191], v[66:69]
	v_mfma_f32_16x16x32_bf16 v[70:73], v[126:129], v[188:191], v[70:73]
	v_mfma_f32_16x16x32_bf16 v[74:77], v[118:121], v[196:199], v[74:77]
	v_mfma_f32_16x16x32_bf16 v[78:81], v[126:129], v[196:199], v[78:81]
	v_mfma_f32_16x16x32_bf16 v[82:85], v[118:121], v[212:215], v[82:85]
	v_mfma_f32_16x16x32_bf16 v[86:89], v[126:129], v[212:215], v[86:89]
	v_mfma_f32_16x16x32_bf16 v[90:93], v[118:121], v[230:233], v[90:93]
	v_mfma_f32_16x16x32_bf16 v[94:97], v[126:129], v[230:233], v[94:97]
	v_mfma_f32_16x16x32_bf16 v[66:69], v[122:125], v[192:195], v[66:69]
	v_mfma_f32_16x16x32_bf16 v[70:73], v[138:141], v[192:195], v[70:73]
	v_mfma_f32_16x16x32_bf16 v[74:77], v[122:125], v[200:203], v[74:77]
	v_mfma_f32_16x16x32_bf16 v[78:81], v[138:141], v[200:203], v[78:81]
	v_mfma_f32_16x16x32_bf16 v[82:85], v[122:125], v[226:229], v[82:85]
	v_mfma_f32_16x16x32_bf16 v[86:89], v[138:141], v[226:229], v[86:89]
	v_mfma_f32_16x16x32_bf16 v[90:93], v[122:125], v[234:237], v[90:93]
	v_mfma_f32_16x16x32_bf16 v[94:97], v[138:141], v[234:237], v[94:97]
	s_setprio 0
	s_setprio 1
	v_mfma_f32_16x16x32_bf16 v[98:101], v[142:145], v[188:191], v[98:101]
	v_mfma_f32_16x16x32_bf16 v[102:105], v[180:183], v[188:191], v[102:105]
	v_mfma_f32_16x16x32_bf16 v[106:109], v[142:145], v[196:199], v[106:109]
	v_mfma_f32_16x16x32_bf16 v[42:45], v[180:183], v[196:199], v[42:45]
	v_mfma_f32_16x16x32_bf16 v[46:49], v[142:145], v[212:215], v[46:49]
	v_mfma_f32_16x16x32_bf16 v[50:53], v[180:183], v[212:215], v[50:53]
	v_mfma_f32_16x16x32_bf16 v[54:57], v[142:145], v[230:233], v[54:57]
	v_mfma_f32_16x16x32_bf16 v[58:61], v[180:183], v[230:233], v[58:61]
	v_mfma_f32_16x16x32_bf16 v[98:101], v[146:149], v[192:195], v[98:101]
	v_mfma_f32_16x16x32_bf16 v[102:105], v[184:187], v[192:195], v[102:105]
	v_mfma_f32_16x16x32_bf16 v[106:109], v[146:149], v[200:203], v[106:109]
	v_mfma_f32_16x16x32_bf16 v[42:45], v[184:187], v[200:203], v[42:45]
	v_mfma_f32_16x16x32_bf16 v[46:49], v[146:149], v[226:229], v[46:49]
	v_mfma_f32_16x16x32_bf16 v[50:53], v[184:187], v[226:229], v[50:53]
	v_mfma_f32_16x16x32_bf16 v[54:57], v[146:149], v[234:237], v[54:57]
	v_mfma_f32_16x16x32_bf16 v[58:61], v[184:187], v[234:237], v[58:61]
	s_setprio 0
	s_barrier
; #define PG8_STAGE(bufoff, gbase, voff) do { _Pragma("unroll") for (int _i = 0; _i < 2; ++_i) \
;         __builtin_amdgcn_global_load_lds((const unsigned*)((const char*)(gbase) + (voff)[_i]), (LAS unsigned*)(lds + (bufoff) + ldsw + _i * 8192), 16, 0, 0); } while (0)
; #define PG8_LDA(dst, b, h) do { _Pragma("unroll") for (int m = 0; m < 4; ++m) _Pragma("unroll") for (int k = 0; k < 2; ++k) dst[m][k] = *(const LAS bf16x8*)(lds + PG8_SA(b, h) + aoff + m * 2048 + k * 1024); } while (0)
; #define PG8_LDB(dst, b, h) do { _Pragma("unroll") for (int n = 0; n < 2; ++n) _Pragma("unroll") for (int k = 0; k < 2; ++k) dst[n][k] = *(const LAS bf16x8*)(lds + PG8_SB(b, h) + boff + n * 2048 + k * 1024); } while (0)
; #define PG8_MMA(ai, bj, At, Bt) do { __builtin_amdgcn_s_setprio(1); _Pragma("unroll") for (int m = 0; m < 4; ++m) _Pragma("unroll") for (int n = 0; n < 2; ++n) _Pragma("unroll") for (int k = 0; k < 2; ++k) \
;         acc[ai][bj][m][n] = __builtin_amdgcn_mfma_f32_16x16x32_bf16(Bt[n][k], At[m][k], acc[ai][bj][m][n], 0, 0, 0); __builtin_amdgcn_s_setprio(0); } while (0)
; #define PG8_WAIT_V(n) asm volatile("s_waitcnt vmcnt(" #n ")" ::: "memory")
; #define PG8_BAR __builtin_amdgcn_s_barrier()
; template <class Epi>
; __device__ __forceinline__ void gemm_phase(LAS unsigned char* lds, const Gemm g, const StaticOrder& S, const Epi& E, int wave_s) {
;     ...
;             PG8_LDB(B0, 0, 0); PG8_LDB(B1, 0, 1); PG8_SCHED; PG8_LDA(At, 0, 0); PG8_STAGE(PG8_SA(1, 1), a1 + hstepA, voffA);
;             PG8_WAIT_V(8); PG8_WAIT_L(0); PG8_BAR; PG8_MMA(0, 0, At, B0); PG8_MMA(0, 1, At, B1); PG8_BAR; PG8_SCHED;
;             PG8_LDA(At, 0, 1); PG8_STAGE(PG8_SB(0, 0), b2, voffB); PG8_STAGE(PG8_SB(0, 1), b2 + hstepB, voffB); PG8_STAGE(PG8_SA(0, 0), a2, voffA);
;             PG8_WAIT_V(8); PG8_WAIT_L(0); PG8_BAR; PG8_MMA(1, 0, At, B0); PG8_MMA(1, 1, At, B1); PG8_BAR; PG8_SCHED;
;             PG8_LDB(B0, 1, 0); PG8_LDB(B1, 1, 1); PG8_SCHED; PG8_LDA(At, 1, 0); PG8_STAGE(PG8_SA(0, 1), a2 + hstepA, voffA);
;             PG8_WAIT_V(8); PG8_WAIT_L(0); PG8_BAR; PG8_MMA(0, 0, At, B0); PG8_MMA(0, 1, At, B1); PG8_BAR; PG8_SCHED;
;             PG8_LDA(At, 1, 1); PG8_STAGE(PG8_SB(1, 0), b3, voffB); PG8_STAGE(PG8_SB(1, 1), b3 + hstepB, voffB); PG8_STAGE(PG8_SA(1, 0), a3, voffA);
;             PG8_WAIT_V(8); PG8_WAIT_L(0); PG8_BAR; PG8_MMA(1, 0, At, B0); PG8_MMA(1, 1, At, B1); PG8_BAR; PG8_SCHED;
	s_mov_b64 s[82:83], 0x280
	s_mov_b32 m0, s79
	v_lshl_add_u64 v[2:3], v[2:3], 0, s[82:83]
	s_add_u32 s24, s24, 0x18280
	ds_read_b128 v[188:191], v155 offset:49152
	ds_read_b128 v[192:195], v155 offset:50176
	ds_read_b128 v[196:199], v155 offset:51200
	ds_read_b128 v[200:203], v155 offset:52224
	ds_read_b128 v[212:215], v155 offset:53248
	ds_read_b128 v[226:229], v155 offset:54272
	ds_read_b128 v[230:233], v155 offset:55296
	ds_read_b128 v[234:237], v155 offset:56320
	global_load_lds_dwordx4 v[2:3], off
	v_lshl_add_u64 v[2:3], v[4:5], 0, s[82:83]
	s_mov_b32 m0, s71
	s_addc_u32 s25, s25, 0
	global_load_lds_dwordx4 v[2:3], off
	s_mov_b32 m0, s72
	s_nop 0
	global_load_lds_dwordx4 v134, s[24:25]
	s_mov_b32 m0, s78
	s_nop 0
	global_load_lds_dwordx4 v130, s[24:25]
	v_lshl_add_u64 v[2:3], v[6:7], 0, s[82:83]
	s_mov_b32 m0, s40
	s_nop 0
	global_load_lds_dwordx4 v[2:3], off
	v_lshl_add_u64 v[2:3], v[8:9], 0, s[82:83]
	s_mov_b32 m0, s41
	s_nop 0
	global_load_lds_dwordx4 v[2:3], off
	s_waitcnt vmcnt(8)
	s_waitcnt lgkmcnt(0)
	s_barrier
	s_setprio 1
	s_waitcnt lgkmcnt(0)
	v_mfma_f32_16x16x32_bf16 v[2:5], v[118:121], v[188:191], v[156:159]
	v_mfma_f32_16x16x32_bf16 v[6:9], v[126:129], v[188:191], v[160:163]
	v_mfma_f32_16x16x32_bf16 v[14:17], v[118:121], v[230:233], v[14:17]
	v_mfma_f32_16x16x32_bf16 v[18:21], v[126:129], v[230:233], v[18:21]
	v_mfma_f32_16x16x32_bf16 v[2:5], v[122:125], v[192:195], v[2:5]
	v_mfma_f32_16x16x32_bf16 v[6:9], v[138:141], v[192:195], v[6:9]
	v_mfma_f32_16x16x32_bf16 v[156:159], v[118:121], v[196:199], v[164:167]
	v_mfma_f32_16x16x32_bf16 v[160:163], v[126:129], v[196:199], v[168:171]
	v_mfma_f32_16x16x32_bf16 v[164:167], v[118:121], v[212:215], v[172:175]
	v_mfma_f32_16x16x32_bf16 v[168:171], v[126:129], v[212:215], v[176:179]
	v_mfma_f32_16x16x32_bf16 v[14:17], v[122:125], v[234:237], v[14:17]
	v_mfma_f32_16x16x32_bf16 v[18:21], v[138:141], v[234:237], v[18:21]
	v_mfma_f32_16x16x32_bf16 v[156:159], v[122:125], v[200:203], v[156:159]
	v_mfma_f32_16x16x32_bf16 v[160:163], v[138:141], v[200:203], v[160:163]
	v_mfma_f32_16x16x32_bf16 v[164:167], v[122:125], v[226:229], v[164:167]
	v_mfma_f32_16x16x32_bf16 v[168:171], v[138:141], v[226:229], v[168:171]
	s_setprio 0
	s_setprio 1
	v_mfma_f32_16x16x32_bf16 v[22:25], v[142:145], v[188:191], v[22:25]
	v_mfma_f32_16x16x32_bf16 v[34:37], v[180:183], v[188:191], v[34:37]
	v_mfma_f32_16x16x32_bf16 v[38:41], v[142:145], v[196:199], v[38:41]
	v_mfma_f32_16x16x32_bf16 v[62:65], v[180:183], v[196:199], v[62:65]
	v_mfma_f32_16x16x32_bf16 v[110:113], v[142:145], v[212:215], v[110:113]
	v_mfma_f32_16x16x32_bf16 v[114:117], v[180:183], v[212:215], v[114:117]
	v_mfma_f32_16x16x32_bf16 v[26:29], v[142:145], v[230:233], v[26:29]
	v_mfma_f32_16x16x32_bf16 v[30:33], v[180:183], v[230:233], v[30:33]
	v_mfma_f32_16x16x32_bf16 v[22:25], v[146:149], v[192:195], v[22:25]
	v_mfma_f32_16x16x32_bf16 v[34:37], v[184:187], v[192:195], v[34:37]
	v_mfma_f32_16x16x32_bf16 v[38:41], v[146:149], v[200:203], v[38:41]
	v_mfma_f32_16x16x32_bf16 v[62:65], v[184:187], v[200:203], v[62:65]
	v_mfma_f32_16x16x32_bf16 v[110:113], v[146:149], v[226:229], v[110:113]
	v_mfma_f32_16x16x32_bf16 v[114:117], v[184:187], v[226:229], v[114:117]
	v_mfma_f32_16x16x32_bf16 v[26:29], v[146:149], v[234:237], v[26:29]
	v_mfma_f32_16x16x32_bf16 v[30:33], v[184:187], v[234:237], v[30:33]
	s_setprio 0
	s_barrier
	ds_read_b128 v[118:121], v0
	ds_read_b128 v[122:125], v0 offset:1024
	ds_read_b128 v[126:129], v0 offset:2048
	ds_read_b128 v[138:141], v0 offset:3072
	ds_read_b128 v[142:145], v10
	ds_read_b128 v[146:149], v10 offset:1024
	ds_read_b128 v[172:175], v10 offset:2048
	ds_read_b128 v[176:179], v10 offset:3072
	s_add_u32 s22, s22, 0x110280
	s_addc_u32 s23, s23, 0
	s_mov_b32 m0, s73
	ds_read_b128 v[180:183], v155
	ds_read_b128 v[184:187], v155 offset:1024
	ds_read_b128 v[188:191], v155 offset:2048
	ds_read_b128 v[192:195], v155 offset:3072
	ds_read_b128 v[196:199], v155 offset:4096
	ds_read_b128 v[200:203], v155 offset:5120
	ds_read_b128 v[212:215], v155 offset:6144
	ds_read_b128 v[226:229], v155 offset:7168
	global_load_lds_dwordx4 v136, s[22:23]
	s_mov_b32 m0, s4
	s_nop 0
	global_load_lds_dwordx4 v132, s[22:23]
	s_waitcnt vmcnt(8)
	s_waitcnt lgkmcnt(0)
	s_barrier
	s_setprio 1
	s_waitcnt lgkmcnt(0)
	v_mfma_f32_16x16x32_bf16 v[66:69], v[118:121], v[180:183], v[66:69]
	v_mfma_f32_16x16x32_bf16 v[70:73], v[126:129], v[180:183], v[70:73]
	v_mfma_f32_16x16x32_bf16 v[74:77], v[118:121], v[188:191], v[74:77]
	v_mfma_f32_16x16x32_bf16 v[78:81], v[126:129], v[188:191], v[78:81]
	v_mfma_f32_16x16x32_bf16 v[82:85], v[118:121], v[196:199], v[82:85]
	v_mfma_f32_16x16x32_bf16 v[86:89], v[126:129], v[196:199], v[86:89]
	v_mfma_f32_16x16x32_bf16 v[90:93], v[118:121], v[212:215], v[90:93]
	v_mfma_f32_16x16x32_bf16 v[66:69], v[122:125], v[184:187], v[66:69]
	v_mfma_f32_16x16x32_bf16 v[70:73], v[138:141], v[184:187], v[70:73]
	v_mfma_f32_16x16x32_bf16 v[74:77], v[122:125], v[192:195], v[74:77]
	v_mfma_f32_16x16x32_bf16 v[78:81], v[138:141], v[192:195], v[78:81]
	v_mfma_f32_16x16x32_bf16 v[82:85], v[122:125], v[200:203], v[82:85]
	v_mfma_f32_16x16x32_bf16 v[86:89], v[138:141], v[200:203], v[86:89]
	v_mfma_f32_16x16x32_bf16 v[230:233], v[122:125], v[226:229], v[90:93]
	v_mfma_f32_16x16x32_bf16 v[90:93], v[126:129], v[212:215], v[94:97]
	v_mfma_f32_16x16x32_bf16 v[234:237], v[138:141], v[226:229], v[90:93]
	s_setprio 0
	s_setprio 1
	v_mfma_f32_16x16x32_bf16 v[90:93], v[142:145], v[180:183], v[98:101]
	v_mfma_f32_16x16x32_bf16 v[98:101], v[146:149], v[184:187], v[90:93]
	v_mfma_f32_16x16x32_bf16 v[90:93], v[172:175], v[180:183], v[102:105]
	v_mfma_f32_16x16x32_bf16 v[42:45], v[172:175], v[188:191], v[42:45]
	v_mfma_f32_16x16x32_bf16 v[46:49], v[142:145], v[196:199], v[46:49]
	v_mfma_f32_16x16x32_bf16 v[50:53], v[172:175], v[196:199], v[50:53]
	v_mfma_f32_16x16x32_bf16 v[54:57], v[142:145], v[212:215], v[54:57]
	v_mfma_f32_16x16x32_bf16 v[58:61], v[172:175], v[212:215], v[58:61]
	v_mfma_f32_16x16x32_bf16 v[102:105], v[176:179], v[184:187], v[90:93]
	v_mfma_f32_16x16x32_bf16 v[90:93], v[142:145], v[188:191], v[106:109]
	v_mfma_f32_16x16x32_bf16 v[42:45], v[176:179], v[192:195], v[42:45]
	v_mfma_f32_16x16x32_bf16 v[46:49], v[146:149], v[200:203], v[46:49]
	v_mfma_f32_16x16x32_bf16 v[50:53], v[176:179], v[200:203], v[50:53]
	v_mfma_f32_16x16x32_bf16 v[54:57], v[146:149], v[226:229], v[54:57]
	v_mfma_f32_16x16x32_bf16 v[58:61], v[176:179], v[226:229], v[58:61]
	v_mfma_f32_16x16x32_bf16 v[180:183], v[146:149], v[192:195], v[90:93]
	s_setprio 0
	s_barrier
; #define PG8_STAGE(bufoff, gbase, voff) do { _Pragma("unroll") for (int _i = 0; _i < 2; ++_i) \
;         __builtin_amdgcn_global_load_lds((const unsigned*)((const char*)(gbase) + (voff)[_i]), (LAS unsigned*)(lds + (bufoff) + ldsw + _i * 8192), 16, 0, 0); } while (0)
; #define PG8_LDA(dst, b, h) do { _Pragma("unroll") for (int m = 0; m < 4; ++m) _Pragma("unroll") for (int k = 0; k < 2; ++k) dst[m][k] = *(const LAS bf16x8*)(lds + PG8_SA(b, h) + aoff + m * 2048 + k * 1024); } while (0)
; #define PG8_LDB(dst, b, h) do { _Pragma("unroll") for (int n = 0; n < 2; ++n) _Pragma("unroll") for (int k = 0; k < 2; ++k) dst[n][k] = *(const LAS bf16x8*)(lds + PG8_SB(b, h) + boff + n * 2048 + k * 1024); } while (0)
; #define PG8_MMA(ai, bj, At, Bt) do { __builtin_amdgcn_s_setprio(1); _Pragma("unroll") for (int m = 0; m < 4; ++m) _Pragma("unroll") for (int n = 0; n < 2; ++n) _Pragma("unroll") for (int k = 0; k < 2; ++k) \
;         acc[ai][bj][m][n] = __builtin_amdgcn_mfma_f32_16x16x32_bf16(Bt[n][k], At[m][k], acc[ai][bj][m][n], 0, 0, 0); __builtin_amdgcn_s_setprio(0); } while (0)
; #define PG8_WAIT_V(n) asm volatile("s_waitcnt vmcnt(" #n ")" ::: "memory")
; #define PG8_WAIT_L(n) asm volatile("s_waitcnt lgkmcnt(" #n ")" ::: "memory")
; #define PG8_BAR __builtin_amdgcn_s_barrier()
; #define PG8_SCHED __builtin_amdgcn_sched_barrier(0)
; template <class Epi>
; __device__ __forceinline__ void gemm_phase(LAS unsigned char* lds, const Gemm g, const StaticOrder& S, const Epi& E, int wave_s) {
;     ...
;             PG8_LDA(At, 0, 1); PG8_STAGE(PG8_SB(0, 0), b2, voffB); PG8_STAGE(PG8_SB(0, 1), b2 + hstepB, voffB); PG8_STAGE(PG8_SA(0, 0), a2, voffA);
;             PG8_WAIT_V(8); PG8_WAIT_L(0); PG8_BAR; PG8_MMA(1, 0, At, B0); PG8_MMA(1, 1, At, B1); PG8_BAR; PG8_SCHED;
;             PG8_LDB(B0, 1, 0); PG8_LDB(B1, 1, 1); PG8_SCHED; PG8_LDA(At, 1, 0); PG8_STAGE(PG8_SA(0, 1), a2 + hstepA, voffA);
;             PG8_WAIT_V(8); PG8_WAIT_L(0); PG8_BAR; PG8_MMA(0, 0, At, B0); PG8_MMA(0, 1, At, B1); PG8_BAR; PG8_SCHED;
	s_mov_b32 m0, s70
	v_lshl_add_u64 v[152:153], s[20:21], 0, v[134:135]
	s_add_u32 s4, s20, 0x18000
	ds_read_b128 v[90:93], v155 offset:16384
	ds_read_b128 v[94:97], v155 offset:17408
	ds_read_b128 v[106:109], v155 offset:18432
	ds_read_b128 v[184:187], v155 offset:19456
	ds_read_b128 v[188:191], v155 offset:20480
	ds_read_b128 v[192:195], v155 offset:21504
	ds_read_b128 v[196:199], v155 offset:22528
	ds_read_b128 v[200:203], v155 offset:23552
	global_load_lds_dwordx4 v[152:153], off
	v_lshl_add_u64 v[216:217], s[20:21], 0, v[130:131]
	s_mov_b32 m0, s5
	s_addc_u32 s5, s21, 0
	global_load_lds_dwordx4 v[216:217], off
	s_mov_b32 m0, s66
	v_lshl_add_u64 v[204:205], s[18:19], 0, v[136:137]
	global_load_lds_dwordx4 v134, s[4:5]
	v_lshl_add_u64 v[208:209], s[4:5], 0, v[130:131]
	s_mov_b32 m0, s67
	v_lshl_add_u64 v[206:207], s[18:19], 0, v[132:133]
	global_load_lds_dwordx4 v[208:209], off
	s_mov_b32 m0, s31
	s_nop 0
	global_load_lds_dwordx4 v[204:205], off
	s_mov_b32 m0, s34
	s_nop 0
	global_load_lds_dwordx4 v[206:207], off
	s_waitcnt vmcnt(8)
	s_waitcnt lgkmcnt(0)
	s_barrier
	s_setprio 1
	s_waitcnt lgkmcnt(0)
	v_mfma_f32_16x16x32_bf16 v[2:5], v[118:121], v[90:93], v[2:5]
	v_mfma_f32_16x16x32_bf16 v[6:9], v[126:129], v[90:93], v[6:9]
	v_mfma_f32_16x16x32_bf16 v[14:17], v[118:121], v[196:199], v[14:17]
	v_mfma_f32_16x16x32_bf16 v[18:21], v[126:129], v[196:199], v[18:21]
	v_mfma_f32_16x16x32_bf16 v[2:5], v[122:125], v[94:97], v[2:5]
	v_mfma_f32_16x16x32_bf16 v[6:9], v[138:141], v[94:97], v[6:9]
	v_mfma_f32_16x16x32_bf16 v[156:159], v[118:121], v[106:109], v[156:159]
	v_mfma_f32_16x16x32_bf16 v[160:163], v[126:129], v[106:109], v[160:163]
	v_mfma_f32_16x16x32_bf16 v[164:167], v[118:121], v[188:191], v[164:167]
	v_mfma_f32_16x16x32_bf16 v[168:171], v[126:129], v[188:191], v[168:171]
	v_mfma_f32_16x16x32_bf16 v[14:17], v[122:125], v[200:203], v[14:17]
	v_mfma_f32_16x16x32_bf16 v[18:21], v[138:141], v[200:203], v[18:21]
	v_mfma_f32_16x16x32_bf16 v[156:159], v[122:125], v[184:187], v[156:159]
	v_mfma_f32_16x16x32_bf16 v[160:163], v[138:141], v[184:187], v[160:163]
	v_mfma_f32_16x16x32_bf16 v[164:167], v[122:125], v[192:195], v[164:167]
	v_mfma_f32_16x16x32_bf16 v[168:171], v[138:141], v[192:195], v[168:171]
	s_setprio 0
	s_setprio 1
	v_mfma_f32_16x16x32_bf16 v[62:65], v[172:175], v[106:109], v[62:65]
	v_mfma_f32_16x16x32_bf16 v[22:25], v[142:145], v[90:93], v[22:25]
	v_mfma_f32_16x16x32_bf16 v[34:37], v[172:175], v[90:93], v[34:37]
	v_mfma_f32_16x16x32_bf16 v[38:41], v[142:145], v[106:109], v[38:41]
	v_mfma_f32_16x16x32_bf16 v[138:141], v[176:179], v[184:187], v[62:65]
	v_mfma_f32_16x16x32_bf16 v[62:65], v[142:145], v[188:191], v[110:113]
	v_mfma_f32_16x16x32_bf16 v[26:29], v[142:145], v[196:199], v[26:29]
	v_mfma_f32_16x16x32_bf16 v[22:25], v[146:149], v[94:97], v[22:25]
	v_mfma_f32_16x16x32_bf16 v[34:37], v[176:179], v[94:97], v[34:37]
	v_mfma_f32_16x16x32_bf16 v[38:41], v[146:149], v[184:187], v[38:41]
	v_mfma_f32_16x16x32_bf16 v[184:187], v[146:149], v[192:195], v[62:65]
	v_mfma_f32_16x16x32_bf16 v[62:65], v[172:175], v[188:191], v[114:117]
	v_mfma_f32_16x16x32_bf16 v[142:145], v[146:149], v[200:203], v[26:29]
	v_mfma_f32_16x16x32_bf16 v[26:29], v[172:175], v[196:199], v[30:33]
	v_mfma_f32_16x16x32_bf16 v[188:191], v[176:179], v[192:195], v[62:65]
	v_mfma_f32_16x16x32_bf16 v[146:149], v[176:179], v[200:203], v[26:29]
	s_setprio 0
	s_barrier
	ds_read_b128 v[172:175], v11
	ds_read_b128 v[176:179], v11 offset:1024
	ds_read_b128 v[192:195], v11 offset:2048
	ds_read_b128 v[196:199], v11 offset:3072
	ds_read_b128 v[200:203], v12
	ds_read_b128 v[212:215], v12 offset:1024
	ds_read_b128 v[226:229], v12 offset:2048
	ds_read_b128 v[238:241], v12 offset:3072
	s_add_u32 s4, s18, 0x110000
	s_addc_u32 s5, s19, 0
	s_mov_b32 m0, s35
	ds_read_b128 v[10:13], v155 offset:32768
	ds_read_b128 v[26:29], v155 offset:33792
	ds_read_b128 v[30:33], v155 offset:34816
	ds_read_b128 v[62:65], v155 offset:35840
	ds_read_b128 v[242:245], v155 offset:36864
	ds_read_b128 v[246:249], v155 offset:37888
	ds_read_b128 v[250:253], v155 offset:38912
	ds_read_b128 v[208:211], v155 offset:39936
	global_load_lds_dwordx4 v136, s[4:5]
	v_lshl_add_u64 v[90:91], s[4:5], 0, v[132:133]
	s_mov_b32 m0, s37
	s_nop 0
	global_load_lds_dwordx4 v[90:91], off
	s_waitcnt vmcnt(8)
	s_waitcnt lgkmcnt(0)
	s_barrier
; #define PG8_STAGE(bufoff, gbase, voff) do { _Pragma("unroll") for (int _i = 0; _i < 2; ++_i) \
;         __builtin_amdgcn_global_load_lds((const unsigned*)((const char*)(gbase) + (voff)[_i]), (LAS unsigned*)(lds + (bufoff) + ldsw + _i * 8192), 16, 0, 0); } while (0)
; #define PG8_LDA(dst, b, h) do { _Pragma("unroll") for (int m = 0; m < 4; ++m) _Pragma("unroll") for (int k = 0; k < 2; ++k) dst[m][k] = *(const LAS bf16x8*)(lds + PG8_SA(b, h) + aoff + m * 2048 + k * 1024); } while (0)
; #define PG8_MMA(ai, bj, At, Bt) do { __builtin_amdgcn_s_setprio(1); _Pragma("unroll") for (int m = 0; m < 4; ++m) _Pragma("unroll") for (int n = 0; n < 2; ++n) _Pragma("unroll") for (int k = 0; k < 2; ++k) \
;         acc[ai][bj][m][n] = __builtin_amdgcn_mfma_f32_16x16x32_bf16(Bt[n][k], At[m][k], acc[ai][bj][m][n], 0, 0, 0); __builtin_amdgcn_s_setprio(0); } while (0)
; #define PG8_WAIT_V(n) asm volatile("s_waitcnt vmcnt(" #n ")" ::: "memory")
; #define PG8_WAIT_L(n) asm volatile("s_waitcnt lgkmcnt(" #n ")" ::: "memory")
; #define PG8_BAR __builtin_amdgcn_s_barrier()
; #define PG8_SCHED __builtin_amdgcn_sched_barrier(0)
; template <class Epi>
; __device__ __forceinline__ void gemm_phase(LAS unsigned char* lds, const Gemm g, const StaticOrder& S, const Epi& E, int wave_s) {
;     ...
;             PG8_WAIT_V(8); PG8_WAIT_L(0); PG8_BAR; PG8_MMA(0, 0, At, B0); PG8_MMA(0, 1, At, B1); PG8_BAR; PG8_SCHED;
;             PG8_LDA(At, 1, 1); PG8_STAGE(PG8_SB(1, 0), b3, voffB); PG8_STAGE(PG8_SB(1, 1), b3 + hstepB, voffB); PG8_STAGE(PG8_SA(1, 0), a3, voffA);
;             PG8_WAIT_V(8); PG8_WAIT_L(0); PG8_BAR; PG8_MMA(1, 0, At, B0); PG8_MMA(1, 1, At, B1); PG8_BAR; PG8_SCHED;
;         }
;         if (wr == 0) PG8_BAR;
	s_setprio 1
	s_waitcnt lgkmcnt(0)
	v_mfma_f32_16x16x32_bf16 v[66:69], v[172:175], v[10:13], v[66:69]
	v_mfma_f32_16x16x32_bf16 v[126:129], v[176:179], v[26:29], v[66:69]
	v_mfma_f32_16x16x32_bf16 v[66:69], v[192:195], v[10:13], v[70:73]
	v_mfma_f32_16x16x32_bf16 v[122:125], v[196:199], v[26:29], v[66:69]
	v_mfma_f32_16x16x32_bf16 v[66:69], v[172:175], v[30:33], v[74:77]
	v_mfma_f32_16x16x32_bf16 v[110:113], v[176:179], v[62:65], v[66:69]
	v_mfma_f32_16x16x32_bf16 v[66:69], v[192:195], v[30:33], v[78:81]
	v_mfma_f32_16x16x32_bf16 v[106:109], v[196:199], v[62:65], v[66:69]
	v_mfma_f32_16x16x32_bf16 v[66:69], v[172:175], v[242:245], v[82:85]
	v_mfma_f32_16x16x32_bf16 v[94:97], v[176:179], v[246:249], v[66:69]
	v_mfma_f32_16x16x32_bf16 v[66:69], v[192:195], v[242:245], v[86:89]
	v_mfma_f32_16x16x32_bf16 v[90:93], v[196:199], v[246:249], v[66:69]
	v_mfma_f32_16x16x32_bf16 v[66:69], v[172:175], v[250:253], v[230:233]
	v_mfma_f32_16x16x32_bf16 v[78:81], v[176:179], v[208:211], v[66:69]
	v_mfma_f32_16x16x32_bf16 v[66:69], v[192:195], v[250:253], v[234:237]
	v_mfma_f32_16x16x32_bf16 v[74:77], v[196:199], v[208:211], v[66:69]
	s_setprio 0
	s_setprio 1
	v_mfma_f32_16x16x32_bf16 v[66:69], v[200:203], v[10:13], v[98:101]
	v_mfma_f32_16x16x32_bf16 v[10:13], v[226:229], v[10:13], v[102:105]
	v_mfma_f32_16x16x32_bf16 v[114:117], v[238:241], v[26:29], v[10:13]
	v_mfma_f32_16x16x32_bf16 v[10:13], v[200:203], v[30:33], v[180:183]
	v_mfma_f32_16x16x32_bf16 v[102:105], v[212:215], v[62:65], v[10:13]
	v_mfma_f32_16x16x32_bf16 v[10:13], v[226:229], v[30:33], v[42:45]
	v_mfma_f32_16x16x32_bf16 v[98:101], v[238:241], v[62:65], v[10:13]
	v_mfma_f32_16x16x32_bf16 v[10:13], v[200:203], v[242:245], v[46:49]
	v_mfma_f32_16x16x32_bf16 v[86:89], v[212:215], v[246:249], v[10:13]
	v_mfma_f32_16x16x32_bf16 v[10:13], v[226:229], v[242:245], v[50:53]
	v_mfma_f32_16x16x32_bf16 v[82:85], v[238:241], v[246:249], v[10:13]
	v_mfma_f32_16x16x32_bf16 v[10:13], v[200:203], v[250:253], v[54:57]
	v_mfma_f32_16x16x32_bf16 v[70:73], v[212:215], v[208:211], v[10:13]
	v_mfma_f32_16x16x32_bf16 v[10:13], v[226:229], v[250:253], v[58:61]
	v_mfma_f32_16x16x32_bf16 v[118:121], v[212:215], v[26:29], v[66:69]
	v_mfma_f32_16x16x32_bf16 v[66:69], v[238:241], v[208:211], v[10:13]
	s_setprio 0
	s_barrier
	s_mov_b32 m0, s79
	s_nop 2
	v_lshl_add_u64 v[10:11], v[152:153], 0, s[42:43]
	s_add_u32 s4, s20, 0x18080
	ds_read_b128 v[50:53], v155 offset:49152
	ds_read_b128 v[180:183], v155 offset:50176
	ds_read_b128 v[208:211], v155 offset:51200
	ds_read_b128 v[230:233], v155 offset:52224
	ds_read_b128 v[234:237], v155 offset:53248
	ds_read_b128 v[242:245], v155 offset:54272
	ds_read_b128 v[246:249], v155 offset:55296
	ds_read_b128 v[250:253], v155 offset:56320
	global_load_lds_dwordx4 v[10:11], off
	v_lshl_add_u64 v[10:11], v[216:217], 0, s[42:43]
	s_mov_b32 m0, s71
	s_addc_u32 s5, s21, 0
	global_load_lds_dwordx4 v[10:11], off
	s_mov_b32 m0, s72
	s_nop 0
	global_load_lds_dwordx4 v134, s[4:5]
	s_mov_b32 m0, s78
	s_nop 0
	global_load_lds_dwordx4 v130, s[4:5]
	v_lshl_add_u64 v[10:11], v[204:205], 0, s[42:43]
	s_mov_b32 m0, s40
	s_nop 0
	global_load_lds_dwordx4 v[10:11], off
	v_lshl_add_u64 v[10:11], v[206:207], 0, s[42:43]
	s_mov_b32 m0, s41
	s_nop 0
	global_load_lds_dwordx4 v[10:11], off
	s_waitcnt vmcnt(8)
	s_waitcnt lgkmcnt(0)
	s_barrier
	s_setprio 1
	s_waitcnt lgkmcnt(0)
	v_mfma_f32_16x16x32_bf16 v[2:5], v[172:175], v[50:53], v[2:5]
	v_mfma_f32_16x16x32_bf16 v[62:65], v[176:179], v[180:183], v[2:5]
	v_mfma_f32_16x16x32_bf16 v[2:5], v[192:195], v[50:53], v[6:9]
	v_mfma_f32_16x16x32_bf16 v[58:61], v[196:199], v[180:183], v[2:5]
	v_mfma_f32_16x16x32_bf16 v[2:5], v[172:175], v[208:211], v[156:159]
	v_mfma_f32_16x16x32_bf16 v[46:49], v[176:179], v[230:233], v[2:5]
	v_mfma_f32_16x16x32_bf16 v[2:5], v[192:195], v[208:211], v[160:163]
	v_mfma_f32_16x16x32_bf16 v[42:45], v[196:199], v[230:233], v[2:5]
	v_mfma_f32_16x16x32_bf16 v[2:5], v[172:175], v[234:237], v[164:167]
	v_mfma_f32_16x16x32_bf16 v[30:33], v[176:179], v[242:245], v[2:5]
	v_mfma_f32_16x16x32_bf16 v[2:5], v[192:195], v[234:237], v[168:171]
	v_mfma_f32_16x16x32_bf16 v[26:29], v[196:199], v[242:245], v[2:5]
	v_mfma_f32_16x16x32_bf16 v[2:5], v[172:175], v[246:249], v[14:17]
	v_mfma_f32_16x16x32_bf16 v[14:17], v[176:179], v[250:253], v[2:5]
	v_mfma_f32_16x16x32_bf16 v[2:5], v[192:195], v[246:249], v[18:21]
	v_mfma_f32_16x16x32_bf16 v[10:13], v[196:199], v[250:253], v[2:5]
	s_setprio 0
	s_setprio 1
	v_mfma_f32_16x16x32_bf16 v[2:5], v[200:203], v[50:53], v[22:25]
	v_mfma_f32_16x16x32_bf16 v[54:57], v[212:215], v[180:183], v[2:5]
	v_mfma_f32_16x16x32_bf16 v[2:5], v[226:229], v[50:53], v[34:37]
	v_mfma_f32_16x16x32_bf16 v[50:53], v[238:241], v[180:183], v[2:5]
	v_mfma_f32_16x16x32_bf16 v[2:5], v[200:203], v[208:211], v[38:41]
	v_mfma_f32_16x16x32_bf16 v[38:41], v[212:215], v[230:233], v[2:5]
	v_mfma_f32_16x16x32_bf16 v[2:5], v[226:229], v[208:211], v[138:141]
	v_mfma_f32_16x16x32_bf16 v[34:37], v[238:241], v[230:233], v[2:5]
	v_mfma_f32_16x16x32_bf16 v[2:5], v[200:203], v[234:237], v[184:187]
	v_mfma_f32_16x16x32_bf16 v[22:25], v[212:215], v[242:245], v[2:5]
	v_mfma_f32_16x16x32_bf16 v[2:5], v[226:229], v[234:237], v[188:191]
	v_mfma_f32_16x16x32_bf16 v[18:21], v[238:241], v[242:245], v[2:5]
	v_mfma_f32_16x16x32_bf16 v[2:5], v[200:203], v[246:249], v[142:145]
	v_mfma_f32_16x16x32_bf16 v[6:9], v[212:215], v[250:253], v[2:5]
	v_mfma_f32_16x16x32_bf16 v[2:5], v[226:229], v[246:249], v[146:149]
	v_mfma_f32_16x16x32_bf16 v[2:5], v[238:241], v[250:253], v[2:5]
	s_setprio 0
	s_barrier
	s_andn2_b64 vcc, exec, s[14:15]
	s_cbranch_vccnz .LBB0_311
	s_barrier

; #define PG8_STAGE(bufoff, gbase, voff) do { _Pragma("unroll") for (int _i = 0; _i < 2; ++_i) \
;         __builtin_amdgcn_global_load_lds((const unsigned*)((const char*)(gbase) + (voff)[_i]), (LAS unsigned*)(lds + (bufoff) + ldsw + _i * 8192), 16, 0, 0); } while (0)
; #define PG8_WAIT_V(n) asm volatile("s_waitcnt vmcnt(" #n ")" ::: "memory")
; #define PG8_BAR __builtin_amdgcn_s_barrier()
; template <class Epi>
; __device__ __forceinline__ void gemm_phase(LAS unsigned char* lds, const Gemm g, const StaticOrder& S, const Epi& E, int wave_s) {
;     ...
;     const char* cA = (const char*)g.A + (size_t)cur.pm * tstepA; const char* cB = (const char*)g.Bt + (size_t)cur.pn * tstepB;
;     PG8_STAGE(PG8_SB(0, 0), cB, voffB); PG8_STAGE(PG8_SB(0, 1), cB + hstepB, voffB); PG8_STAGE(PG8_SA(0, 0), cA, voffA); PG8_STAGE(PG8_SA(0, 1), cA + hstepA, voffA);
;     if (wr == 1) PG8_BAR;
;     PG8_WAIT_V(2); PG8_BAR;
;     PG8_STAGE(PG8_SB(1, 0), cB + kstep, voffB); PG8_STAGE(PG8_SA(1, 0), cA + kstep, voffA); PG8_STAGE(PG8_SB(1, 1), cB + hstepB + kstep, voffB);
;     PG8_WAIT_V(6); PG8_BAR;
.LBB0_318:
	s_add_u32 s8, s0, 0x1c000000
	s_addc_u32 s9, s1, 0
	s_add_u32 s10, s0, 0x610000
	s_addc_u32 s11, s1, 0
	v_and_b32_e32 v11, 48, v10
	v_lshlrev_b32_e32 v12, 6, v10
	s_movk_i32 s1, 0x3c0
	v_lshlrev_b32_e32 v10, 2, v10
	s_lshl_b32 s0, s5, 13
	v_and_or_b32 v11, v12, s1, v11
	v_and_b32_e32 v10, 32, v10
	v_bitop3_b32 v12, v11, s0, v10 bitop3:0xde
	s_lshl_b32 s0, s4, 5
	s_and_b32 s39, s0, 0x60
	s_add_i32 m0, s31, 0x18000
	v_lshl_add_u64 v[8:9], v[8:9], 0, s[42:43]
	s_lshl_b32 s38, s5, 6
	s_lshl_b32 s0, s39, 7
	s_waitcnt vmcnt(2)
	s_barrier
	global_load_lds_dwordx4 v[8:9], off
	v_lshl_add_u64 v[6:7], v[6:7], 0, s[42:43]
	s_add_i32 m0, s31, 0x1a000
	s_add_i32 s40, s31, 0x8000
	s_add_i32 s41, s31, 0xa000
	v_bitop3_b32 v144, s0, v11, v10 bitop3:0xf6
	global_load_lds_dwordx4 v[6:7], off
	v_lshl_add_u64 v[2:3], v[2:3], 0, s[42:43]
	s_mov_b32 m0, s40
	s_add_u32 s0, s24, 0x10080
	global_load_lds_dwordx4 v[2:3], off
	v_lshl_add_u64 v[2:3], v[4:5], 0, s[42:43]
	s_mov_b32 m0, s41
	s_addc_u32 s1, s25, 0
	global_load_lds_dwordx4 v[2:3], off
	s_add_i32 m0, s31, 0x1c000
	s_nop 0
	global_load_lds_dwordx4 v0, s[0:1]
	v_lshl_add_u64 v[2:3], s[0:1], 0, v[130:131]
	s_add_i32 m0, s31, 0x1e000
	s_cmpk_lt_u32 s12, 0x100
	global_load_lds_dwordx4 v[2:3], off
	s_waitcnt vmcnt(6)
	v_readlane_b32 s14, v255, 34
	s_cselect_b64 s[12:13], -1, 0
	v_add_u32_e32 v145, 0, v12
	v_readlane_b32 s15, v255, 35
	v_readlane_b32 s57, v255, 0
	v_readlane_b32 s64, v254, 63
	s_barrier
	s_branch .LBB0_321

; #define PG8_STAGE(bufoff, gbase, voff) do { _Pragma("unroll") for (int _i = 0; _i < 2; ++_i) \
;         __builtin_amdgcn_global_load_lds((const unsigned*)((const char*)(gbase) + (voff)[_i]), (LAS unsigned*)(lds + (bufoff) + ldsw + _i * 8192), 16, 0, 0); } while (0)
; #define PG8_LDA(dst, b, h) do { _Pragma("unroll") for (int m = 0; m < 4; ++m) _Pragma("unroll") for (int k = 0; k < 2; ++k) dst[m][k] = *(const LAS bf16x8*)(lds + PG8_SA(b, h) + aoff + m * 2048 + k * 1024); } while (0)
; #define PG8_LDB(dst, b, h) do { _Pragma("unroll") for (int n = 0; n < 2; ++n) _Pragma("unroll") for (int k = 0; k < 2; ++k) dst[n][k] = *(const LAS bf16x8*)(lds + PG8_SB(b, h) + boff + n * 2048 + k * 1024); } while (0)
; #define PG8_MMA(ai, bj, At, Bt) do { __builtin_amdgcn_s_setprio(1); _Pragma("unroll") for (int m = 0; m < 4; ++m) _Pragma("unroll") for (int n = 0; n < 2; ++n) _Pragma("unroll") for (int k = 0; k < 2; ++k) \
;         acc[ai][bj][m][n] = __builtin_amdgcn_mfma_f32_16x16x32_bf16(Bt[n][k], At[m][k], acc[ai][bj][m][n], 0, 0, 0); __builtin_amdgcn_s_setprio(0); } while (0)
; #define PG8_BAR __builtin_amdgcn_s_barrier()
; template <class Epi>
; __device__ __forceinline__ void gemm_phase(LAS unsigned char* lds, const Gemm g, const StaticOrder& S, const Epi& E, int wave_s) {
;     ...
;         const bool has_next = S.next(ui + 1, nxt);
;         const char* nA = has_next ? (const char*)g.A + (size_t)nxt.pm * tstepA : cA; const char* nB = has_next ? (const char*)g.Bt + (size_t)nxt.pn * tstepB : cB;
;         for (int t = 0; t < nt; t += 2) {
;             const bool last = (t == nt - 2);
;             const char* a1 = cA + (size_t)(t + 1) * kstep;
;             const char* a2 = last ? nA : cA + (size_t)(t + 2) * kstep; const char* b2 = last ? nB : cB + (size_t)(t + 2) * kstep;
;             const char* a3 = a2 + kstep; const char* b3 = b2 + kstep;
;             PG8_LDB(B0, 0, 0); PG8_LDB(B1, 0, 1); PG8_SCHED; PG8_LDA(At, 0, 0); PG8_STAGE(PG8_SA(1, 1), a1 + hstepA, voffA);
;             PG8_WAIT_V(8); PG8_WAIT_L(0); PG8_BAR; PG8_MMA(0, 0, At, B0); PG8_MMA(0, 1, At, B1); PG8_BAR; PG8_SCHED;
;             PG8_LDA(At, 0, 1); PG8_STAGE(PG8_SB(0, 0), b2, voffB); PG8_STAGE(PG8_SB(0, 1), b2 + hstepB, voffB); PG8_STAGE(PG8_SA(0, 0), a2, voffA);
;             PG8_WAIT_V(8); PG8_WAIT_L(0); PG8_BAR; PG8_MMA(1, 0, At, B0); PG8_MMA(1, 1, At, B1); PG8_BAR; PG8_SCHED;
.LBB0_329:
	s_ashr_i32 s17, s16, 31
	s_lshl_b64 s[20:21], s[16:17], 17
	s_add_u32 s20, s28, s20
	s_addc_u32 s21, s29, s21
	s_and_b64 s[4:5], s[4:5], exec
	s_cselect_b32 s5, s21, s25
	s_cselect_b32 s4, s20, s24
	s_add_i32 s70, 0, 0x10000
	s_add_i32 s71, 0, 0x14000
	v_add_u32_e32 v212, s70, v144
	v_add_u32_e32 v213, s71, v144
	ds_read_b128 v[2:5], v212
	ds_read_b128 v[6:9], v212 offset:1024
	ds_read_b128 v[10:13], v212 offset:2048
	ds_read_b128 v[14:17], v212 offset:3072
	ds_read_b128 v[18:21], v213
	ds_read_b128 v[22:25], v213 offset:1024
	ds_read_b128 v[26:29], v213 offset:2048
	ds_read_b128 v[30:33], v213 offset:3072
	s_add_u32 s66, s22, 0x110080
	s_addc_u32 s67, s23, 0
	s_add_i32 s72, s31, 0xc000
	s_mov_b32 m0, s72
	s_add_i32 s17, s31, 0xe000
	ds_read_b128 v[34:37], v145
	ds_read_b128 v[38:41], v145 offset:1024
	ds_read_b128 v[42:45], v145 offset:2048
	ds_read_b128 v[46:49], v145 offset:3072
	ds_read_b128 v[50:53], v145 offset:4096
	ds_read_b128 v[54:57], v145 offset:5120
	ds_read_b128 v[58:61], v145 offset:6144
	ds_read_b128 v[62:65], v145 offset:7168
	global_load_lds_dwordx4 v134, s[66:67]
	v_lshl_add_u64 v[66:67], s[66:67], 0, v[132:133]
	s_mov_b32 m0, s17
	s_nop 0
	global_load_lds_dwordx4 v[66:67], off
	s_waitcnt vmcnt(8)
	s_waitcnt lgkmcnt(0)
	s_barrier
	s_setprio 1
	s_waitcnt lgkmcnt(0)
	v_mfma_f32_16x16x32_bf16 v[66:69], v[2:5], v[34:37], 0
	v_mfma_f32_16x16x32_bf16 v[70:73], v[10:13], v[34:37], 0
	v_mfma_f32_16x16x32_bf16 v[74:77], v[2:5], v[42:45], 0
	v_mfma_f32_16x16x32_bf16 v[78:81], v[10:13], v[42:45], 0
	v_mfma_f32_16x16x32_bf16 v[82:85], v[2:5], v[50:53], 0
	v_mfma_f32_16x16x32_bf16 v[86:89], v[10:13], v[50:53], 0
	v_mfma_f32_16x16x32_bf16 v[90:93], v[2:5], v[58:61], 0
	v_mfma_f32_16x16x32_bf16 v[94:97], v[10:13], v[58:61], 0
	v_mfma_f32_16x16x32_bf16 v[66:69], v[6:9], v[38:41], v[66:69]
	v_mfma_f32_16x16x32_bf16 v[70:73], v[14:17], v[38:41], v[70:73]
	v_mfma_f32_16x16x32_bf16 v[74:77], v[6:9], v[46:49], v[74:77]
	v_mfma_f32_16x16x32_bf16 v[78:81], v[14:17], v[46:49], v[78:81]
	v_mfma_f32_16x16x32_bf16 v[82:85], v[6:9], v[54:57], v[82:85]
	v_mfma_f32_16x16x32_bf16 v[86:89], v[14:17], v[54:57], v[86:89]
	v_mfma_f32_16x16x32_bf16 v[90:93], v[6:9], v[62:65], v[90:93]
	v_mfma_f32_16x16x32_bf16 v[94:97], v[14:17], v[62:65], v[94:97]
	s_setprio 0
	s_setprio 1
	v_mfma_f32_16x16x32_bf16 v[98:101], v[18:21], v[34:37], 0
	v_mfma_f32_16x16x32_bf16 v[34:37], v[26:29], v[34:37], 0
	v_mfma_f32_16x16x32_bf16 v[98:101], v[22:25], v[38:41], v[98:101]
	v_mfma_f32_16x16x32_bf16 v[34:37], v[30:33], v[38:41], v[34:37]
	v_mfma_f32_16x16x32_bf16 v[38:41], v[18:21], v[42:45], 0
	v_mfma_f32_16x16x32_bf16 v[42:45], v[26:29], v[42:45], 0
	v_mfma_f32_16x16x32_bf16 v[38:41], v[22:25], v[46:49], v[38:41]
	v_mfma_f32_16x16x32_bf16 v[42:45], v[30:33], v[46:49], v[42:45]
	v_mfma_f32_16x16x32_bf16 v[46:49], v[18:21], v[50:53], 0
	v_mfma_f32_16x16x32_bf16 v[50:53], v[26:29], v[50:53], 0
	v_mfma_f32_16x16x32_bf16 v[46:49], v[22:25], v[54:57], v[46:49]
	v_mfma_f32_16x16x32_bf16 v[50:53], v[30:33], v[54:57], v[50:53]
	v_mfma_f32_16x16x32_bf16 v[54:57], v[18:21], v[58:61], 0
	v_mfma_f32_16x16x32_bf16 v[58:61], v[26:29], v[58:61], 0
	v_mfma_f32_16x16x32_bf16 v[54:57], v[22:25], v[62:65], v[54:57]
	v_mfma_f32_16x16x32_bf16 v[58:61], v[30:33], v[62:65], v[58:61]
	s_setprio 0
	s_barrier
	s_add_i32 s70, s70, s30
	v_lshl_add_u64 v[202:203], s[24:25], 0, v[0:1]
	s_mov_b64 s[82:83], 0x100
	s_add_i32 s65, s70, 0x2000
	v_lshl_add_u64 v[136:137], v[202:203], 0, s[82:83]
	s_mov_b32 m0, s70
	v_lshl_add_u64 v[204:205], s[24:25], 0, v[130:131]
	s_add_u32 s78, s24, 0x10100
	ds_read_b128 v[62:65], v145 offset:16384
	ds_read_b128 v[102:105], v145 offset:17408
	ds_read_b128 v[106:109], v145 offset:18432
	ds_read_b128 v[110:113], v145 offset:19456
	ds_read_b128 v[114:117], v145 offset:20480
	ds_read_b128 v[118:121], v145 offset:21504
	ds_read_b128 v[122:125], v145 offset:22528
	ds_read_b128 v[126:129], v145 offset:23552
	global_load_lds_dwordx4 v[136:137], off
	v_lshl_add_u64 v[136:137], v[204:205], 0, s[82:83]
	s_mov_b32 m0, s65
	s_addc_u32 s79, s25, 0
	s_add_i32 s66, s71, s30
	global_load_lds_dwordx4 v[136:137], off
	s_mov_b32 m0, s66
	s_add_i32 s67, s66, 0x2000
	global_load_lds_dwordx4 v0, s[78:79]
	s_mov_b32 m0, s67
	v_lshl_add_u64 v[206:207], s[22:23], 0, v[134:135]
	global_load_lds_dwordx4 v130, s[78:79]
	v_lshl_add_u64 v[136:137], v[206:207], 0, s[82:83]
	s_mov_b32 m0, s31
	v_lshl_add_u64 v[208:209], s[22:23], 0, v[132:133]
	global_load_lds_dwordx4 v[136:137], off
	v_lshl_add_u64 v[136:137], v[208:209], 0, s[82:83]
	s_mov_b32 m0, s34
	s_nop 0
	global_load_lds_dwordx4 v[136:137], off
	s_waitcnt vmcnt(8)
	s_waitcnt lgkmcnt(0)
	s_barrier
; #define PG8_STAGE(bufoff, gbase, voff) do { _Pragma("unroll") for (int _i = 0; _i < 2; ++_i) \
;         __builtin_amdgcn_global_load_lds((const unsigned*)((const char*)(gbase) + (voff)[_i]), (LAS unsigned*)(lds + (bufoff) + ldsw + _i * 8192), 16, 0, 0); } while (0)
; #define PG8_LDA(dst, b, h) do { _Pragma("unroll") for (int m = 0; m < 4; ++m) _Pragma("unroll") for (int k = 0; k < 2; ++k) dst[m][k] = *(const LAS bf16x8*)(lds + PG8_SA(b, h) + aoff + m * 2048 + k * 1024); } while (0)
; #define PG8_LDB(dst, b, h) do { _Pragma("unroll") for (int n = 0; n < 2; ++n) _Pragma("unroll") for (int k = 0; k < 2; ++k) dst[n][k] = *(const LAS bf16x8*)(lds + PG8_SB(b, h) + boff + n * 2048 + k * 1024); } while (0)
; #define PG8_MMA(ai, bj, At, Bt) do { __builtin_amdgcn_s_setprio(1); _Pragma("unroll") for (int m = 0; m < 4; ++m) _Pragma("unroll") for (int n = 0; n < 2; ++n) _Pragma("unroll") for (int k = 0; k < 2; ++k) \
;         acc[ai][bj][m][n] = __builtin_amdgcn_mfma_f32_16x16x32_bf16(Bt[n][k], At[m][k], acc[ai][bj][m][n], 0, 0, 0); __builtin_amdgcn_s_setprio(0); } while (0)
; #define PG8_WAIT_V(n) asm volatile("s_waitcnt vmcnt(" #n ")" ::: "memory")
; #define PG8_WAIT_L(n) asm volatile("s_waitcnt lgkmcnt(" #n ")" ::: "memory")
; #define PG8_BAR __builtin_amdgcn_s_barrier()
; #define PG8_SCHED __builtin_amdgcn_sched_barrier(0)
; template <class Epi>
; __device__ __forceinline__ void gemm_phase(LAS unsigned char* lds, const Gemm g, const StaticOrder& S, const Epi& E, int wave_s) {
;     ...
;             PG8_WAIT_V(8); PG8_WAIT_L(0); PG8_BAR; PG8_MMA(1, 0, At, B0); PG8_MMA(1, 1, At, B1); PG8_BAR; PG8_SCHED;
;             PG8_LDB(B0, 1, 0); PG8_LDB(B1, 1, 1); PG8_SCHED; PG8_LDA(At, 1, 0); PG8_STAGE(PG8_SA(0, 1), a2 + hstepA, voffA);
;             PG8_WAIT_V(8); PG8_WAIT_L(0); PG8_BAR; PG8_MMA(0, 0, At, B0); PG8_MMA(0, 1, At, B1); PG8_BAR; PG8_SCHED;
	s_setprio 1
	s_waitcnt lgkmcnt(0)
	v_mfma_f32_16x16x32_bf16 v[136:139], v[2:5], v[62:65], 0
	v_mfma_f32_16x16x32_bf16 v[146:149], v[2:5], v[106:109], 0
	v_mfma_f32_16x16x32_bf16 v[154:157], v[2:5], v[114:117], 0
	v_mfma_f32_16x16x32_bf16 v[2:5], v[2:5], v[122:125], 0
	v_mfma_f32_16x16x32_bf16 v[136:139], v[6:9], v[102:105], v[136:139]
	v_mfma_f32_16x16x32_bf16 v[146:149], v[6:9], v[110:113], v[146:149]
	v_mfma_f32_16x16x32_bf16 v[154:157], v[6:9], v[118:121], v[154:157]
	v_mfma_f32_16x16x32_bf16 v[2:5], v[6:9], v[126:129], v[2:5]
	v_mfma_f32_16x16x32_bf16 v[6:9], v[10:13], v[122:125], 0
	v_mfma_f32_16x16x32_bf16 v[140:143], v[10:13], v[62:65], 0
	v_mfma_f32_16x16x32_bf16 v[150:153], v[10:13], v[106:109], 0
	v_mfma_f32_16x16x32_bf16 v[158:161], v[10:13], v[114:117], 0
	v_mfma_f32_16x16x32_bf16 v[6:9], v[14:17], v[126:129], v[6:9]
	v_mfma_f32_16x16x32_bf16 v[140:143], v[14:17], v[102:105], v[140:143]
	v_mfma_f32_16x16x32_bf16 v[150:153], v[14:17], v[110:113], v[150:153]
	v_mfma_f32_16x16x32_bf16 v[158:161], v[14:17], v[118:121], v[158:161]
	s_setprio 0
	s_setprio 1
	v_mfma_f32_16x16x32_bf16 v[10:13], v[18:21], v[62:65], 0
	v_mfma_f32_16x16x32_bf16 v[14:17], v[26:29], v[62:65], 0
	v_mfma_f32_16x16x32_bf16 v[10:13], v[22:25], v[102:105], v[10:13]
	v_mfma_f32_16x16x32_bf16 v[14:17], v[30:33], v[102:105], v[14:17]
	v_mfma_f32_16x16x32_bf16 v[62:65], v[18:21], v[106:109], 0
	v_mfma_f32_16x16x32_bf16 v[102:105], v[26:29], v[106:109], 0
	v_mfma_f32_16x16x32_bf16 v[106:109], v[18:21], v[114:117], 0
	v_mfma_f32_16x16x32_bf16 v[18:21], v[18:21], v[122:125], 0
	v_mfma_f32_16x16x32_bf16 v[62:65], v[22:25], v[110:113], v[62:65]
	v_mfma_f32_16x16x32_bf16 v[102:105], v[30:33], v[110:113], v[102:105]
	v_mfma_f32_16x16x32_bf16 v[106:109], v[22:25], v[118:121], v[106:109]
	v_mfma_f32_16x16x32_bf16 v[110:113], v[26:29], v[114:117], 0
	v_mfma_f32_16x16x32_bf16 v[18:21], v[22:25], v[126:129], v[18:21]
	v_mfma_f32_16x16x32_bf16 v[22:25], v[26:29], v[122:125], 0
	v_mfma_f32_16x16x32_bf16 v[110:113], v[30:33], v[118:121], v[110:113]
	v_mfma_f32_16x16x32_bf16 v[22:25], v[30:33], v[126:129], v[22:25]
	s_setprio 0
	s_barrier
	s_add_i32 s73, 0, 0x18000
	s_add_i32 s82, 0, 0x1c000
	v_add_u32_e32 v225, s73, v144
	v_add_u32_e32 v226, s82, v144
	ds_read_b128 v[26:29], v225
	ds_read_b128 v[30:33], v225 offset:1024
	ds_read_b128 v[114:117], v225 offset:2048
	ds_read_b128 v[118:121], v225 offset:3072
	ds_read_b128 v[122:125], v226
	ds_read_b128 v[126:129], v226 offset:1024
	ds_read_b128 v[162:165], v226 offset:2048
	ds_read_b128 v[166:169], v226 offset:3072
	s_add_u32 s78, s22, 0x110100
	s_addc_u32 s79, s23, 0
	s_mov_b32 m0, s35
	ds_read_b128 v[170:173], v145 offset:32768
	ds_read_b128 v[174:177], v145 offset:33792
	ds_read_b128 v[178:181], v145 offset:34816
	ds_read_b128 v[182:185], v145 offset:35840
	ds_read_b128 v[186:189], v145 offset:36864
	ds_read_b128 v[190:193], v145 offset:37888
	ds_read_b128 v[194:197], v145 offset:38912
	ds_read_b128 v[198:201], v145 offset:39936
	global_load_lds_dwordx4 v134, s[78:79]
	v_lshl_add_u64 v[210:211], s[78:79], 0, v[132:133]
	s_mov_b32 m0, s37
	s_nop 0
	global_load_lds_dwordx4 v[210:211], off
	s_waitcnt vmcnt(8)
	s_waitcnt lgkmcnt(0)
	s_barrier
	s_setprio 1
	s_waitcnt lgkmcnt(0)
	v_mfma_f32_16x16x32_bf16 v[66:69], v[26:29], v[170:173], v[66:69]
	v_mfma_f32_16x16x32_bf16 v[70:73], v[114:117], v[170:173], v[70:73]
	v_mfma_f32_16x16x32_bf16 v[74:77], v[26:29], v[178:181], v[74:77]
	v_mfma_f32_16x16x32_bf16 v[78:81], v[114:117], v[178:181], v[78:81]
	v_mfma_f32_16x16x32_bf16 v[82:85], v[26:29], v[186:189], v[82:85]
	v_mfma_f32_16x16x32_bf16 v[86:89], v[114:117], v[186:189], v[86:89]
	v_mfma_f32_16x16x32_bf16 v[90:93], v[26:29], v[194:197], v[90:93]
	v_mfma_f32_16x16x32_bf16 v[94:97], v[114:117], v[194:197], v[94:97]
	v_mfma_f32_16x16x32_bf16 v[66:69], v[30:33], v[174:177], v[66:69]
	v_mfma_f32_16x16x32_bf16 v[70:73], v[118:121], v[174:177], v[70:73]
	v_mfma_f32_16x16x32_bf16 v[74:77], v[30:33], v[182:185], v[74:77]
	v_mfma_f32_16x16x32_bf16 v[78:81], v[118:121], v[182:185], v[78:81]
	v_mfma_f32_16x16x32_bf16 v[82:85], v[30:33], v[190:193], v[82:85]
	v_mfma_f32_16x16x32_bf16 v[86:89], v[118:121], v[190:193], v[86:89]
	v_mfma_f32_16x16x32_bf16 v[90:93], v[30:33], v[198:201], v[90:93]
	v_mfma_f32_16x16x32_bf16 v[94:97], v[118:121], v[198:201], v[94:97]
	s_setprio 0
	s_setprio 1
	v_mfma_f32_16x16x32_bf16 v[98:101], v[122:125], v[170:173], v[98:101]
	v_mfma_f32_16x16x32_bf16 v[34:37], v[162:165], v[170:173], v[34:37]
	v_mfma_f32_16x16x32_bf16 v[38:41], v[122:125], v[178:181], v[38:41]
	v_mfma_f32_16x16x32_bf16 v[42:45], v[162:165], v[178:181], v[42:45]
	v_mfma_f32_16x16x32_bf16 v[46:49], v[122:125], v[186:189], v[46:49]
	v_mfma_f32_16x16x32_bf16 v[50:53], v[162:165], v[186:189], v[50:53]
	v_mfma_f32_16x16x32_bf16 v[54:57], v[122:125], v[194:197], v[54:57]
	v_mfma_f32_16x16x32_bf16 v[58:61], v[162:165], v[194:197], v[58:61]
	v_mfma_f32_16x16x32_bf16 v[98:101], v[126:129], v[174:177], v[98:101]
	v_mfma_f32_16x16x32_bf16 v[34:37], v[166:169], v[174:177], v[34:37]
	v_mfma_f32_16x16x32_bf16 v[38:41], v[126:129], v[182:185], v[38:41]
	v_mfma_f32_16x16x32_bf16 v[42:45], v[166:169], v[182:185], v[42:45]
	v_mfma_f32_16x16x32_bf16 v[46:49], v[126:129], v[190:193], v[46:49]
	v_mfma_f32_16x16x32_bf16 v[50:53], v[166:169], v[190:193], v[50:53]
	v_mfma_f32_16x16x32_bf16 v[54:57], v[126:129], v[198:201], v[54:57]
	v_mfma_f32_16x16x32_bf16 v[58:61], v[166:169], v[198:201], v[58:61]
	s_setprio 0
	s_barrier
; #define PG8_STAGE(bufoff, gbase, voff) do { _Pragma("unroll") for (int _i = 0; _i < 2; ++_i) \
;         __builtin_amdgcn_global_load_lds((const unsigned*)((const char*)(gbase) + (voff)[_i]), (LAS unsigned*)(lds + (bufoff) + ldsw + _i * 8192), 16, 0, 0); } while (0)
; #define PG8_LDA(dst, b, h) do { _Pragma("unroll") for (int m = 0; m < 4; ++m) _Pragma("unroll") for (int k = 0; k < 2; ++k) dst[m][k] = *(const LAS bf16x8*)(lds + PG8_SA(b, h) + aoff + m * 2048 + k * 1024); } while (0)
; #define PG8_LDB(dst, b, h) do { _Pragma("unroll") for (int n = 0; n < 2; ++n) _Pragma("unroll") for (int k = 0; k < 2; ++k) dst[n][k] = *(const LAS bf16x8*)(lds + PG8_SB(b, h) + boff + n * 2048 + k * 1024); } while (0)
; #define PG8_MMA(ai, bj, At, Bt) do { __builtin_amdgcn_s_setprio(1); _Pragma("unroll") for (int m = 0; m < 4; ++m) _Pragma("unroll") for (int n = 0; n < 2; ++n) _Pragma("unroll") for (int k = 0; k < 2; ++k) \
;         acc[ai][bj][m][n] = __builtin_amdgcn_mfma_f32_16x16x32_bf16(Bt[n][k], At[m][k], acc[ai][bj][m][n], 0, 0, 0); __builtin_amdgcn_s_setprio(0); } while (0)
; #define PG8_WAIT_V(n) asm volatile("s_waitcnt vmcnt(" #n ")" ::: "memory")
; #define PG8_BAR __builtin_amdgcn_s_barrier()
; template <class Epi>
; __device__ __forceinline__ void gemm_phase(LAS unsigned char* lds, const Gemm g, const StaticOrder& S, const Epi& E, int wave_s) {
;     ...
;             PG8_LDB(B0, 0, 0); PG8_LDB(B1, 0, 1); PG8_SCHED; PG8_LDA(At, 0, 0); PG8_STAGE(PG8_SA(1, 1), a1 + hstepA, voffA);
;             PG8_WAIT_V(8); PG8_WAIT_L(0); PG8_BAR; PG8_MMA(0, 0, At, B0); PG8_MMA(0, 1, At, B1); PG8_BAR; PG8_SCHED;
;             PG8_LDA(At, 0, 1); PG8_STAGE(PG8_SB(0, 0), b2, voffB); PG8_STAGE(PG8_SB(0, 1), b2 + hstepB, voffB); PG8_STAGE(PG8_SA(0, 0), a2, voffA);
;             PG8_WAIT_V(8); PG8_WAIT_L(0); PG8_BAR; PG8_MMA(1, 0, At, B0); PG8_MMA(1, 1, At, B1); PG8_BAR; PG8_SCHED;
;             PG8_LDB(B0, 1, 0); PG8_LDB(B1, 1, 1); PG8_SCHED; PG8_LDA(At, 1, 0); PG8_STAGE(PG8_SA(0, 1), a2 + hstepA, voffA);
;             PG8_WAIT_V(8); PG8_WAIT_L(0); PG8_BAR; PG8_MMA(0, 0, At, B0); PG8_MMA(0, 1, At, B1); PG8_BAR; PG8_SCHED;
;             PG8_LDA(At, 1, 1); PG8_STAGE(PG8_SB(1, 0), b3, voffB); PG8_STAGE(PG8_SB(1, 1), b3 + hstepB, voffB); PG8_STAGE(PG8_SA(1, 0), a3, voffA);
;             PG8_WAIT_V(8); PG8_WAIT_L(0); PG8_BAR; PG8_MMA(1, 0, At, B0); PG8_MMA(1, 1, At, B1); PG8_BAR; PG8_SCHED;
	s_add_i32 s73, s73, s30
	s_mov_b64 s[88:89], 0x180
	s_add_i32 s71, s73, 0x2000
	v_lshl_add_u64 v[202:203], v[202:203], 0, s[88:89]
	s_mov_b32 m0, s73
	s_add_u32 s78, s24, 0x10180
	ds_read_b128 v[170:173], v145 offset:49152
	ds_read_b128 v[174:177], v145 offset:50176
	ds_read_b128 v[178:181], v145 offset:51200
	ds_read_b128 v[182:185], v145 offset:52224
	ds_read_b128 v[186:189], v145 offset:53248
	ds_read_b128 v[190:193], v145 offset:54272
	ds_read_b128 v[194:197], v145 offset:55296
	ds_read_b128 v[198:201], v145 offset:56320
	global_load_lds_dwordx4 v[202:203], off
	v_lshl_add_u64 v[202:203], v[204:205], 0, s[88:89]
	s_mov_b32 m0, s71
	s_addc_u32 s79, s25, 0
	s_add_i32 s24, s82, s30
	global_load_lds_dwordx4 v[202:203], off
	s_mov_b32 m0, s24
	s_add_i32 s25, s24, 0x2000
	global_load_lds_dwordx4 v0, s[78:79]
	s_mov_b32 m0, s25
	s_nop 0
	global_load_lds_dwordx4 v130, s[78:79]
	v_lshl_add_u64 v[202:203], v[206:207], 0, s[88:89]
	s_mov_b32 m0, s40
	s_nop 0
	global_load_lds_dwordx4 v[202:203], off
	v_lshl_add_u64 v[202:203], v[208:209], 0, s[88:89]
	s_mov_b32 m0, s41
	s_nop 0
	global_load_lds_dwordx4 v[202:203], off
	s_waitcnt vmcnt(8)
	s_waitcnt lgkmcnt(0)
	s_barrier
	s_setprio 1
	s_waitcnt lgkmcnt(0)
	v_mfma_f32_16x16x32_bf16 v[2:5], v[26:29], v[194:197], v[2:5]
	v_mfma_f32_16x16x32_bf16 v[6:9], v[114:117], v[194:197], v[6:9]
	v_mfma_f32_16x16x32_bf16 v[136:139], v[26:29], v[170:173], v[136:139]
	v_mfma_f32_16x16x32_bf16 v[140:143], v[114:117], v[170:173], v[140:143]
	v_mfma_f32_16x16x32_bf16 v[146:149], v[26:29], v[178:181], v[146:149]
	v_mfma_f32_16x16x32_bf16 v[150:153], v[114:117], v[178:181], v[150:153]
	v_mfma_f32_16x16x32_bf16 v[154:157], v[26:29], v[186:189], v[154:157]
	v_mfma_f32_16x16x32_bf16 v[158:161], v[114:117], v[186:189], v[158:161]
	v_mfma_f32_16x16x32_bf16 v[2:5], v[30:33], v[198:201], v[2:5]
	v_mfma_f32_16x16x32_bf16 v[6:9], v[118:121], v[198:201], v[6:9]
	v_mfma_f32_16x16x32_bf16 v[136:139], v[30:33], v[174:177], v[136:139]
	v_mfma_f32_16x16x32_bf16 v[140:143], v[118:121], v[174:177], v[140:143]
	v_mfma_f32_16x16x32_bf16 v[146:149], v[30:33], v[182:185], v[146:149]
	v_mfma_f32_16x16x32_bf16 v[150:153], v[118:121], v[182:185], v[150:153]
	v_mfma_f32_16x16x32_bf16 v[154:157], v[30:33], v[190:193], v[154:157]
	v_mfma_f32_16x16x32_bf16 v[158:161], v[118:121], v[190:193], v[158:161]
	s_setprio 0
	s_setprio 1
	v_mfma_f32_16x16x32_bf16 v[10:13], v[122:125], v[170:173], v[10:13]
	v_mfma_f32_16x16x32_bf16 v[14:17], v[162:165], v[170:173], v[14:17]
	v_mfma_f32_16x16x32_bf16 v[26:29], v[122:125], v[178:181], v[62:65]
	v_mfma_f32_16x16x32_bf16 v[30:33], v[162:165], v[178:181], v[102:105]
	v_mfma_f32_16x16x32_bf16 v[62:65], v[122:125], v[186:189], v[106:109]
	v_mfma_f32_16x16x32_bf16 v[102:105], v[162:165], v[186:189], v[110:113]
	v_mfma_f32_16x16x32_bf16 v[18:21], v[122:125], v[194:197], v[18:21]
	v_mfma_f32_16x16x32_bf16 v[22:25], v[162:165], v[194:197], v[22:25]
	v_mfma_f32_16x16x32_bf16 v[10:13], v[126:129], v[174:177], v[10:13]
	v_mfma_f32_16x16x32_bf16 v[14:17], v[166:169], v[174:177], v[14:17]
	v_mfma_f32_16x16x32_bf16 v[26:29], v[126:129], v[182:185], v[26:29]
	v_mfma_f32_16x16x32_bf16 v[30:33], v[166:169], v[182:185], v[30:33]
	v_mfma_f32_16x16x32_bf16 v[62:65], v[126:129], v[190:193], v[62:65]
	v_mfma_f32_16x16x32_bf16 v[102:105], v[166:169], v[190:193], v[102:105]
	v_mfma_f32_16x16x32_bf16 v[18:21], v[126:129], v[198:201], v[18:21]
	v_mfma_f32_16x16x32_bf16 v[22:25], v[166:169], v[198:201], v[22:25]
	s_setprio 0
	s_barrier
	ds_read_b128 v[106:109], v212
	ds_read_b128 v[110:113], v212 offset:1024
	ds_read_b128 v[114:117], v212 offset:2048
	ds_read_b128 v[118:121], v212 offset:3072
	ds_read_b128 v[122:125], v213
	ds_read_b128 v[126:129], v213 offset:1024
	ds_read_b128 v[162:165], v213 offset:2048
	ds_read_b128 v[166:169], v213 offset:3072
	s_add_u32 s22, s22, 0x110180
	s_addc_u32 s23, s23, 0
	s_mov_b32 m0, s72
	ds_read_b128 v[170:173], v145
	ds_read_b128 v[174:177], v145 offset:1024
	ds_read_b128 v[178:181], v145 offset:2048
	ds_read_b128 v[182:185], v145 offset:3072
	ds_read_b128 v[186:189], v145 offset:4096
	ds_read_b128 v[190:193], v145 offset:5120
	ds_read_b128 v[194:197], v145 offset:6144
	ds_read_b128 v[198:201], v145 offset:7168
	global_load_lds_dwordx4 v134, s[22:23]
	s_mov_b32 m0, s17
	s_nop 0
	global_load_lds_dwordx4 v132, s[22:23]
	s_waitcnt vmcnt(8)
	s_waitcnt lgkmcnt(0)
	s_barrier
	s_setprio 1
	s_waitcnt lgkmcnt(0)
	v_mfma_f32_16x16x32_bf16 v[66:69], v[106:109], v[170:173], v[66:69]
	v_mfma_f32_16x16x32_bf16 v[70:73], v[114:117], v[170:173], v[70:73]
	v_mfma_f32_16x16x32_bf16 v[74:77], v[106:109], v[178:181], v[74:77]
	v_mfma_f32_16x16x32_bf16 v[78:81], v[114:117], v[178:181], v[78:81]
	v_mfma_f32_16x16x32_bf16 v[82:85], v[106:109], v[186:189], v[82:85]
	v_mfma_f32_16x16x32_bf16 v[86:89], v[114:117], v[186:189], v[86:89]
	v_mfma_f32_16x16x32_bf16 v[90:93], v[106:109], v[194:197], v[90:93]
	v_mfma_f32_16x16x32_bf16 v[94:97], v[114:117], v[194:197], v[94:97]
	v_mfma_f32_16x16x32_bf16 v[66:69], v[110:113], v[174:177], v[66:69]
	v_mfma_f32_16x16x32_bf16 v[70:73], v[118:121], v[174:177], v[70:73]
	v_mfma_f32_16x16x32_bf16 v[74:77], v[110:113], v[182:185], v[74:77]
	v_mfma_f32_16x16x32_bf16 v[78:81], v[118:121], v[182:185], v[78:81]
	v_mfma_f32_16x16x32_bf16 v[82:85], v[110:113], v[190:193], v[82:85]
	v_mfma_f32_16x16x32_bf16 v[86:89], v[118:121], v[190:193], v[86:89]
	v_mfma_f32_16x16x32_bf16 v[90:93], v[110:113], v[198:201], v[90:93]
	v_mfma_f32_16x16x32_bf16 v[94:97], v[118:121], v[198:201], v[94:97]
	s_setprio 0
	s_setprio 1
	v_mfma_f32_16x16x32_bf16 v[34:37], v[162:165], v[170:173], v[34:37]
	v_mfma_f32_16x16x32_bf16 v[38:41], v[122:125], v[178:181], v[38:41]
	v_mfma_f32_16x16x32_bf16 v[42:45], v[162:165], v[178:181], v[42:45]
	v_mfma_f32_16x16x32_bf16 v[46:49], v[122:125], v[186:189], v[46:49]
	v_mfma_f32_16x16x32_bf16 v[50:53], v[162:165], v[186:189], v[50:53]
	v_mfma_f32_16x16x32_bf16 v[54:57], v[122:125], v[194:197], v[54:57]
	v_mfma_f32_16x16x32_bf16 v[58:61], v[162:165], v[194:197], v[58:61]
	v_mfma_f32_16x16x32_bf16 v[98:101], v[122:125], v[170:173], v[98:101]
	v_mfma_f32_16x16x32_bf16 v[34:37], v[166:169], v[174:177], v[34:37]
	v_mfma_f32_16x16x32_bf16 v[38:41], v[126:129], v[182:185], v[38:41]
	v_mfma_f32_16x16x32_bf16 v[42:45], v[166:169], v[182:185], v[42:45]
	v_mfma_f32_16x16x32_bf16 v[46:49], v[126:129], v[190:193], v[46:49]
	v_mfma_f32_16x16x32_bf16 v[50:53], v[166:169], v[190:193], v[50:53]
	v_mfma_f32_16x16x32_bf16 v[54:57], v[126:129], v[198:201], v[54:57]
	v_mfma_f32_16x16x32_bf16 v[58:61], v[166:169], v[198:201], v[58:61]
	v_mfma_f32_16x16x32_bf16 v[208:211], v[126:129], v[174:177], v[98:101]
	s_setprio 0
	s_barrier
; #define PG8_STAGE(bufoff, gbase, voff) do { _Pragma("unroll") for (int _i = 0; _i < 2; ++_i) \
;         __builtin_amdgcn_global_load_lds((const unsigned*)((const char*)(gbase) + (voff)[_i]), (LAS unsigned*)(lds + (bufoff) + ldsw + _i * 8192), 16, 0, 0); } while (0)
; #define PG8_LDA(dst, b, h) do { _Pragma("unroll") for (int m = 0; m < 4; ++m) _Pragma("unroll") for (int k = 0; k < 2; ++k) dst[m][k] = *(const LAS bf16x8*)(lds + PG8_SA(b, h) + aoff + m * 2048 + k * 1024); } while (0)
; #define PG8_LDB(dst, b, h) do { _Pragma("unroll") for (int n = 0; n < 2; ++n) _Pragma("unroll") for (int k = 0; k < 2; ++k) dst[n][k] = *(const LAS bf16x8*)(lds + PG8_SB(b, h) + boff + n * 2048 + k * 1024); } while (0)
; #define PG8_MMA(ai, bj, At, Bt) do { __builtin_amdgcn_s_setprio(1); _Pragma("unroll") for (int m = 0; m < 4; ++m) _Pragma("unroll") for (int n = 0; n < 2; ++n) _Pragma("unroll") for (int k = 0; k < 2; ++k) \
;         acc[ai][bj][m][n] = __builtin_amdgcn_mfma_f32_16x16x32_bf16(Bt[n][k], At[m][k], acc[ai][bj][m][n], 0, 0, 0); __builtin_amdgcn_s_setprio(0); } while (0)
; #define PG8_WAIT_V(n) asm volatile("s_waitcnt vmcnt(" #n ")" ::: "memory")
; #define PG8_WAIT_L(n) asm volatile("s_waitcnt lgkmcnt(" #n ")" ::: "memory")
; #define PG8_BAR __builtin_amdgcn_s_barrier()
; #define PG8_SCHED __builtin_amdgcn_sched_barrier(0)
; template <class Epi>
; __device__ __forceinline__ void gemm_phase(LAS unsigned char* lds, const Gemm g, const StaticOrder& S, const Epi& E, int wave_s) {
;     ...
;             PG8_LDA(At, 0, 1); PG8_STAGE(PG8_SB(0, 0), b2, voffB); PG8_STAGE(PG8_SB(0, 1), b2 + hstepB, voffB); PG8_STAGE(PG8_SA(0, 0), a2, voffA);
;             PG8_WAIT_V(8); PG8_WAIT_L(0); PG8_BAR; PG8_MMA(1, 0, At, B0); PG8_MMA(1, 1, At, B1); PG8_BAR; PG8_SCHED;
;             PG8_LDB(B0, 1, 0); PG8_LDB(B1, 1, 1); PG8_SCHED; PG8_LDA(At, 1, 0); PG8_STAGE(PG8_SA(0, 1), a2 + hstepA, voffA);
;             PG8_WAIT_V(8); PG8_WAIT_L(0); PG8_BAR; PG8_MMA(0, 0, At, B0); PG8_MMA(0, 1, At, B1); PG8_BAR; PG8_SCHED;
	s_mov_b32 m0, s70
	v_lshl_add_u64 v[202:203], s[4:5], 0, v[0:1]
	s_add_u32 s22, s4, 0x10000
	ds_read_b128 v[98:101], v145 offset:16384
	ds_read_b128 v[170:173], v145 offset:17408
	ds_read_b128 v[174:177], v145 offset:18432
	ds_read_b128 v[178:181], v145 offset:19456
	ds_read_b128 v[182:185], v145 offset:20480
	ds_read_b128 v[186:189], v145 offset:21504
	ds_read_b128 v[190:193], v145 offset:22528
	ds_read_b128 v[194:197], v145 offset:23552
	global_load_lds_dwordx4 v[202:203], off
	v_lshl_add_u64 v[204:205], s[4:5], 0, v[130:131]
	s_mov_b32 m0, s65
	s_addc_u32 s23, s5, 0
	global_load_lds_dwordx4 v[204:205], off
	s_mov_b32 m0, s66
	v_lshl_add_u64 v[206:207], s[18:19], 0, v[134:135]
	global_load_lds_dwordx4 v0, s[22:23]
	v_lshl_add_u64 v[198:199], s[22:23], 0, v[130:131]
	s_mov_b32 m0, s67
	v_lshl_add_u64 v[216:217], s[18:19], 0, v[132:133]
	global_load_lds_dwordx4 v[198:199], off
	s_mov_b32 m0, s31
	s_nop 0
	global_load_lds_dwordx4 v[206:207], off
	s_mov_b32 m0, s34
	s_nop 0
	global_load_lds_dwordx4 v[216:217], off
	s_waitcnt vmcnt(8)
	s_waitcnt lgkmcnt(0)
	s_barrier
	s_setprio 1
	s_waitcnt lgkmcnt(0)
	v_mfma_f32_16x16x32_bf16 v[2:5], v[106:109], v[190:193], v[2:5]
	v_mfma_f32_16x16x32_bf16 v[6:9], v[114:117], v[190:193], v[6:9]
	v_mfma_f32_16x16x32_bf16 v[136:139], v[106:109], v[98:101], v[136:139]
	v_mfma_f32_16x16x32_bf16 v[140:143], v[114:117], v[98:101], v[140:143]
	v_mfma_f32_16x16x32_bf16 v[146:149], v[106:109], v[174:177], v[146:149]
	v_mfma_f32_16x16x32_bf16 v[150:153], v[114:117], v[174:177], v[150:153]
	v_mfma_f32_16x16x32_bf16 v[154:157], v[106:109], v[182:185], v[154:157]
	v_mfma_f32_16x16x32_bf16 v[158:161], v[114:117], v[182:185], v[158:161]
	v_mfma_f32_16x16x32_bf16 v[2:5], v[110:113], v[194:197], v[2:5]
	v_mfma_f32_16x16x32_bf16 v[6:9], v[118:121], v[194:197], v[6:9]
	v_mfma_f32_16x16x32_bf16 v[136:139], v[110:113], v[170:173], v[136:139]
	v_mfma_f32_16x16x32_bf16 v[140:143], v[118:121], v[170:173], v[140:143]
	v_mfma_f32_16x16x32_bf16 v[146:149], v[110:113], v[178:181], v[146:149]
	v_mfma_f32_16x16x32_bf16 v[150:153], v[118:121], v[178:181], v[150:153]
	v_mfma_f32_16x16x32_bf16 v[154:157], v[110:113], v[186:189], v[154:157]
	v_mfma_f32_16x16x32_bf16 v[158:161], v[118:121], v[186:189], v[158:161]
	s_setprio 0
	s_setprio 1
	v_mfma_f32_16x16x32_bf16 v[10:13], v[122:125], v[98:101], v[10:13]
	v_mfma_f32_16x16x32_bf16 v[198:201], v[126:129], v[170:173], v[10:13]
	v_mfma_f32_16x16x32_bf16 v[10:13], v[162:165], v[98:101], v[14:17]
	v_mfma_f32_16x16x32_bf16 v[170:173], v[166:169], v[170:173], v[10:13]
	v_mfma_f32_16x16x32_bf16 v[10:13], v[122:125], v[174:177], v[26:29]
	v_mfma_f32_16x16x32_bf16 v[212:215], v[126:129], v[178:181], v[10:13]
	v_mfma_f32_16x16x32_bf16 v[10:13], v[162:165], v[174:177], v[30:33]
	v_mfma_f32_16x16x32_bf16 v[174:177], v[166:169], v[178:181], v[10:13]
	v_mfma_f32_16x16x32_bf16 v[10:13], v[122:125], v[182:185], v[62:65]
	v_mfma_f32_16x16x32_bf16 v[178:181], v[126:129], v[186:189], v[10:13]
	v_mfma_f32_16x16x32_bf16 v[10:13], v[162:165], v[182:185], v[102:105]
	v_mfma_f32_16x16x32_bf16 v[182:185], v[166:169], v[186:189], v[10:13]
	v_mfma_f32_16x16x32_bf16 v[10:13], v[122:125], v[190:193], v[18:21]
	v_mfma_f32_16x16x32_bf16 v[186:189], v[126:129], v[194:197], v[10:13]
	v_mfma_f32_16x16x32_bf16 v[10:13], v[162:165], v[190:193], v[22:25]
	v_mfma_f32_16x16x32_bf16 v[162:165], v[166:169], v[194:197], v[10:13]
	s_setprio 0
	s_barrier
	s_nop 4
	ds_read_b128 v[10:13], v225
	ds_read_b128 v[14:17], v225 offset:1024
	ds_read_b128 v[18:21], v225 offset:2048
	ds_read_b128 v[22:25], v225 offset:3072
	ds_read_b128 v[166:169], v226
	ds_read_b128 v[190:193], v226 offset:1024
	ds_read_b128 v[194:197], v226 offset:2048
	ds_read_b128 v[226:229], v226 offset:3072
	s_add_u32 s22, s18, 0x110000
	s_addc_u32 s23, s19, 0
	s_mov_b32 m0, s35
	ds_read_b128 v[26:29], v145 offset:32768
	ds_read_b128 v[30:33], v145 offset:33792
	ds_read_b128 v[62:65], v145 offset:34816
	ds_read_b128 v[110:113], v145 offset:35840
	ds_read_b128 v[230:233], v145 offset:36864
	ds_read_b128 v[234:237], v145 offset:37888
	ds_read_b128 v[238:241], v145 offset:38912
	ds_read_b128 v[242:245], v145 offset:39936
	global_load_lds_dwordx4 v134, s[22:23]
	v_lshl_add_u64 v[98:99], s[22:23], 0, v[132:133]
	s_mov_b32 m0, s37
	s_nop 0
	global_load_lds_dwordx4 v[98:99], off
	s_waitcnt vmcnt(8)
	s_waitcnt lgkmcnt(0)
	s_barrier
; #define PG8_STAGE(bufoff, gbase, voff) do { _Pragma("unroll") for (int _i = 0; _i < 2; ++_i) \
;         __builtin_amdgcn_global_load_lds((const unsigned*)((const char*)(gbase) + (voff)[_i]), (LAS unsigned*)(lds + (bufoff) + ldsw + _i * 8192), 16, 0, 0); } while (0)
; #define PG8_LDA(dst, b, h) do { _Pragma("unroll") for (int m = 0; m < 4; ++m) _Pragma("unroll") for (int k = 0; k < 2; ++k) dst[m][k] = *(const LAS bf16x8*)(lds + PG8_SA(b, h) + aoff + m * 2048 + k * 1024); } while (0)
; #define PG8_MMA(ai, bj, At, Bt) do { __builtin_amdgcn_s_setprio(1); _Pragma("unroll") for (int m = 0; m < 4; ++m) _Pragma("unroll") for (int n = 0; n < 2; ++n) _Pragma("unroll") for (int k = 0; k < 2; ++k) \
;         acc[ai][bj][m][n] = __builtin_amdgcn_mfma_f32_16x16x32_bf16(Bt[n][k], At[m][k], acc[ai][bj][m][n], 0, 0, 0); __builtin_amdgcn_s_setprio(0); } while (0)
; #define PG8_WAIT_V(n) asm volatile("s_waitcnt vmcnt(" #n ")" ::: "memory")
; #define PG8_WAIT_L(n) asm volatile("s_waitcnt lgkmcnt(" #n ")" ::: "memory")
; #define PG8_BAR __builtin_amdgcn_s_barrier()
; #define PG8_SCHED __builtin_amdgcn_sched_barrier(0)
; template <class Epi>
; __device__ __forceinline__ void gemm_phase(LAS unsigned char* lds, const Gemm g, const StaticOrder& S, const Epi& E, int wave_s) {
;     ...
;             PG8_WAIT_V(8); PG8_WAIT_L(0); PG8_BAR; PG8_MMA(0, 0, At, B0); PG8_MMA(0, 1, At, B1); PG8_BAR; PG8_SCHED;
;             PG8_LDA(At, 1, 1); PG8_STAGE(PG8_SB(1, 0), b3, voffB); PG8_STAGE(PG8_SB(1, 1), b3 + hstepB, voffB); PG8_STAGE(PG8_SA(1, 0), a3, voffA);
;             PG8_WAIT_V(8); PG8_WAIT_L(0); PG8_BAR; PG8_MMA(1, 0, At, B0); PG8_MMA(1, 1, At, B1); PG8_BAR; PG8_SCHED;
;         }
;         if (wr == 0) PG8_BAR;
	s_setprio 1
	s_waitcnt lgkmcnt(0)
	v_mfma_f32_16x16x32_bf16 v[66:69], v[10:13], v[26:29], v[66:69]
	v_mfma_f32_16x16x32_bf16 v[114:117], v[14:17], v[30:33], v[66:69]
	v_mfma_f32_16x16x32_bf16 v[66:69], v[18:21], v[26:29], v[70:73]
	v_mfma_f32_16x16x32_bf16 v[118:121], v[22:25], v[30:33], v[66:69]
	v_mfma_f32_16x16x32_bf16 v[66:69], v[10:13], v[62:65], v[74:77]
	v_mfma_f32_16x16x32_bf16 v[98:101], v[14:17], v[110:113], v[66:69]
	v_mfma_f32_16x16x32_bf16 v[66:69], v[18:21], v[62:65], v[78:81]
	v_mfma_f32_16x16x32_bf16 v[102:105], v[22:25], v[110:113], v[66:69]
	v_mfma_f32_16x16x32_bf16 v[66:69], v[10:13], v[230:233], v[82:85]
	v_mfma_f32_16x16x32_bf16 v[82:85], v[14:17], v[234:237], v[66:69]
	v_mfma_f32_16x16x32_bf16 v[66:69], v[18:21], v[230:233], v[86:89]
	v_mfma_f32_16x16x32_bf16 v[86:89], v[22:25], v[234:237], v[66:69]
	v_mfma_f32_16x16x32_bf16 v[66:69], v[10:13], v[238:241], v[90:93]
	v_mfma_f32_16x16x32_bf16 v[78:81], v[14:17], v[242:245], v[66:69]
	v_mfma_f32_16x16x32_bf16 v[66:69], v[18:21], v[238:241], v[94:97]
	v_mfma_f32_16x16x32_bf16 v[74:77], v[22:25], v[242:245], v[66:69]
	s_setprio 0
	s_setprio 1
	v_mfma_f32_16x16x32_bf16 v[66:69], v[166:169], v[26:29], v[208:211]
	v_mfma_f32_16x16x32_bf16 v[26:29], v[194:197], v[26:29], v[34:37]
	v_mfma_f32_16x16x32_bf16 v[126:129], v[226:229], v[30:33], v[26:29]
	v_mfma_f32_16x16x32_bf16 v[26:29], v[166:169], v[62:65], v[38:41]
	v_mfma_f32_16x16x32_bf16 v[106:109], v[190:193], v[110:113], v[26:29]
	v_mfma_f32_16x16x32_bf16 v[26:29], v[194:197], v[62:65], v[42:45]
	v_mfma_f32_16x16x32_bf16 v[110:113], v[226:229], v[110:113], v[26:29]
	v_mfma_f32_16x16x32_bf16 v[26:29], v[166:169], v[230:233], v[46:49]
	v_mfma_f32_16x16x32_bf16 v[90:93], v[190:193], v[234:237], v[26:29]
	v_mfma_f32_16x16x32_bf16 v[26:29], v[194:197], v[230:233], v[50:53]
	v_mfma_f32_16x16x32_bf16 v[94:97], v[226:229], v[234:237], v[26:29]
	v_mfma_f32_16x16x32_bf16 v[26:29], v[166:169], v[238:241], v[54:57]
	v_mfma_f32_16x16x32_bf16 v[70:73], v[190:193], v[242:245], v[26:29]
	v_mfma_f32_16x16x32_bf16 v[26:29], v[194:197], v[238:241], v[58:61]
	v_mfma_f32_16x16x32_bf16 v[122:125], v[190:193], v[30:33], v[66:69]
	v_mfma_f32_16x16x32_bf16 v[66:69], v[226:229], v[242:245], v[26:29]
	s_setprio 0
	s_barrier
	s_mov_b32 m0, s73
	s_nop 2
	v_lshl_add_u64 v[26:27], v[202:203], 0, s[42:43]
	s_add_u32 s4, s4, 0x10080
	ds_read_b128 v[34:37], v145 offset:49152
	ds_read_b128 v[38:41], v145 offset:50176
	ds_read_b128 v[208:211], v145 offset:51200
	ds_read_b128 v[230:233], v145 offset:52224
	ds_read_b128 v[234:237], v145 offset:53248
	ds_read_b128 v[238:241], v145 offset:54272
	ds_read_b128 v[242:245], v145 offset:55296
	ds_read_b128 v[246:249], v145 offset:56320
	global_load_lds_dwordx4 v[26:27], off
	v_lshl_add_u64 v[26:27], v[204:205], 0, s[42:43]
	s_mov_b32 m0, s71
	s_addc_u32 s5, s5, 0
	global_load_lds_dwordx4 v[26:27], off
	s_mov_b32 m0, s24
	s_nop 0
	global_load_lds_dwordx4 v0, s[4:5]
	s_mov_b32 m0, s25
	s_nop 0
	global_load_lds_dwordx4 v130, s[4:5]
	v_lshl_add_u64 v[26:27], v[206:207], 0, s[42:43]
	s_mov_b32 m0, s40
	s_nop 0
	global_load_lds_dwordx4 v[26:27], off
	v_lshl_add_u64 v[26:27], v[216:217], 0, s[42:43]
	s_mov_b32 m0, s41
	s_nop 0
	global_load_lds_dwordx4 v[26:27], off
	s_waitcnt vmcnt(8)
	s_waitcnt lgkmcnt(0)
	s_barrier
	s_setprio 1
	s_waitcnt lgkmcnt(0)
	v_mfma_f32_16x16x32_bf16 v[26:29], v[10:13], v[34:37], v[136:139]
	v_mfma_f32_16x16x32_bf16 v[58:61], v[14:17], v[38:41], v[26:29]
	v_mfma_f32_16x16x32_bf16 v[26:29], v[18:21], v[34:37], v[140:143]
	v_mfma_f32_16x16x32_bf16 v[62:65], v[22:25], v[38:41], v[26:29]
	v_mfma_f32_16x16x32_bf16 v[26:29], v[10:13], v[208:211], v[146:149]
	v_mfma_f32_16x16x32_bf16 v[42:45], v[14:17], v[230:233], v[26:29]
	v_mfma_f32_16x16x32_bf16 v[26:29], v[18:21], v[208:211], v[150:153]
	v_mfma_f32_16x16x32_bf16 v[2:5], v[10:13], v[242:245], v[2:5]
	v_mfma_f32_16x16x32_bf16 v[46:49], v[22:25], v[230:233], v[26:29]
	v_mfma_f32_16x16x32_bf16 v[26:29], v[10:13], v[234:237], v[154:157]
	v_mfma_f32_16x16x32_bf16 v[30:33], v[18:21], v[234:237], v[158:161]
	v_mfma_f32_16x16x32_bf16 v[10:13], v[14:17], v[246:249], v[2:5]
	v_mfma_f32_16x16x32_bf16 v[2:5], v[18:21], v[242:245], v[6:9]
	v_mfma_f32_16x16x32_bf16 v[26:29], v[14:17], v[238:241], v[26:29]
	v_mfma_f32_16x16x32_bf16 v[30:33], v[22:25], v[238:241], v[30:33]
	v_mfma_f32_16x16x32_bf16 v[14:17], v[22:25], v[246:249], v[2:5]
	s_setprio 0
	s_setprio 1
	v_mfma_f32_16x16x32_bf16 v[2:5], v[166:169], v[34:37], v[198:201]
	v_mfma_f32_16x16x32_bf16 v[50:53], v[190:193], v[38:41], v[2:5]
	v_mfma_f32_16x16x32_bf16 v[2:5], v[194:197], v[34:37], v[170:173]
	v_mfma_f32_16x16x32_bf16 v[54:57], v[226:229], v[38:41], v[2:5]
	v_mfma_f32_16x16x32_bf16 v[2:5], v[166:169], v[208:211], v[212:215]
	v_mfma_f32_16x16x32_bf16 v[38:41], v[190:193], v[230:233], v[2:5]
	v_mfma_f32_16x16x32_bf16 v[2:5], v[194:197], v[208:211], v[174:177]
	v_mfma_f32_16x16x32_bf16 v[34:37], v[226:229], v[230:233], v[2:5]
	v_mfma_f32_16x16x32_bf16 v[2:5], v[166:169], v[234:237], v[178:181]
	v_mfma_f32_16x16x32_bf16 v[18:21], v[190:193], v[238:241], v[2:5]
	v_mfma_f32_16x16x32_bf16 v[2:5], v[194:197], v[234:237], v[182:185]
	v_mfma_f32_16x16x32_bf16 v[22:25], v[226:229], v[238:241], v[2:5]
	v_mfma_f32_16x16x32_bf16 v[2:5], v[166:169], v[242:245], v[186:189]
	v_mfma_f32_16x16x32_bf16 v[6:9], v[190:193], v[246:249], v[2:5]
	v_mfma_f32_16x16x32_bf16 v[2:5], v[194:197], v[242:245], v[162:165]
	v_mfma_f32_16x16x32_bf16 v[2:5], v[226:229], v[246:249], v[2:5]
	s_setprio 0
	s_barrier
	s_andn2_b64 vcc, exec, s[12:13]
	s_cbranch_vccnz .LBB0_331
	s_barrier

; template <int MODE, bool FIRST, bool FOLD>
; __device__ __forceinline__ bool partialSM(f32x16& p0, f32x16& p1, float& m_reg, float& alpha, int relbase, bool near, const float* lut, float cb) {
;     ...
;     float pmax = p0[0];
; #pragma unroll
;     for (int r = 1; r < 16; ++r) pmax = fmaxf(pmax, p0[r]);
; #pragma unroll
;     for (int r = 0; r < 16; ++r) pmax = fmaxf(pmax, p1[r]);
;     { auto rr = __builtin_amdgcn_permlane32_swap(__float_as_uint(pmax), __float_as_uint(pmax), false, false);
;       pmax = fmaxf(__uint_as_float(rr[0]), __uint_as_float(rr[1])); }
;     bool resc;
;     if (FIRST && MODE != 2) resc = true; else resc = __any(pmax > THR2);
; template <int NQ, int MODE> ...
;     ...
;     f32x16 cinit = f32x16{}; float cur_cb = 0.f; bool dirty = true;
.LBB0_711:
	v_max_f32_e32 v0, v161, v161
	v_max_f32_e32 v10, v160, v160
	v_max_f32_e32 v0, v10, v0
	v_max_f32_e32 v10, v144, v145
	v_max3_f32 v0, v0, v162, v163
	v_max3_f32 v10, v10, v146, v147
	v_max3_f32 v0, v0, v164, v165
	v_max3_f32 v10, v10, v148, v149
	v_max3_f32 v0, v0, v166, v167
	v_max3_f32 v10, v10, v150, v151
	v_max3_f32 v0, v0, v168, v169
	v_max3_f32 v10, v10, v152, v153
	v_max3_f32 v0, v0, v170, v171
	v_max3_f32 v10, v10, v154, v155
	v_max3_f32 v0, v0, v172, v173
	v_max3_f32 v10, v10, v156, v157
	v_max3_f32 v0, v0, v174, v175
	v_max3_f32 v10, v10, v158, v159
	v_max_f32_e32 v0, v0, v10
	v_mov_b32_e32 v10, v0
	s_nop 1
	v_permlane32_swap_b32_e32 v0, v10
	v_max_f32_e32 v10, v0, v10
	v_cmp_lt_f32_e32 vcc, s51, v10
	s_cmp_lg_u64 vcc, 0
	s_cselect_b64 s[22:23], -1, 0
	v_mov_b32_e32 v0, 1.0
	s_cbranch_vccnz .LBB0_731

; template <int MODE, bool FIRST, bool FOLD>
; __device__ __forceinline__ bool partialSM(f32x16& p0, f32x16& p1, float& m_reg, float& alpha, int relbase, bool near, const float* lut, float cb) {
;     ...
;     float pmax = p0[0];
; #pragma unroll
;     for (int r = 1; r < 16; ++r) pmax = fmaxf(pmax, p0[r]);
; #pragma unroll
;     for (int r = 0; r < 16; ++r) pmax = fmaxf(pmax, p1[r]);
;     { auto rr = __builtin_amdgcn_permlane32_swap(__float_as_uint(pmax), __float_as_uint(pmax), false, false);
;       pmax = fmaxf(__uint_as_float(rr[0]), __uint_as_float(rr[1])); }
;     bool resc;
;     if (FIRST && MODE != 2) resc = true; else resc = __any(pmax > THR2);
; template <int NQ, int MODE> ...
;     ...
;     f32x16 cinit = f32x16{}; float cur_cb = 0.f; bool dirty = true;
.LBB0_726:
	v_max_f32_e32 v2, v161, v161
	v_max_f32_e32 v3, v160, v160
	v_max_f32_e32 v2, v3, v2
	v_max_f32_e32 v3, v128, v129
	v_max3_f32 v2, v2, v162, v163
	v_max3_f32 v3, v3, v130, v131
	v_max3_f32 v2, v2, v164, v165
	v_max3_f32 v3, v3, v132, v133
	v_max3_f32 v2, v2, v166, v167
	v_max3_f32 v3, v3, v134, v135
	v_max3_f32 v2, v2, v168, v169
	v_max3_f32 v3, v3, v136, v137
	v_max3_f32 v2, v2, v170, v171
	v_max3_f32 v3, v3, v138, v139
	v_max3_f32 v2, v2, v172, v173
	v_max3_f32 v3, v3, v140, v141
	v_max3_f32 v2, v2, v174, v175
	v_max3_f32 v3, v3, v142, v143
	v_max_f32_e32 v2, v2, v3
	v_mov_b32_e32 v3, v2
	s_nop 1
	v_permlane32_swap_b32_e32 v2, v3
	v_max_f32_e32 v3, v2, v3
	v_cmp_lt_f32_e32 vcc, s51, v3
	s_cmp_lg_u64 vcc, 0
	s_cselect_b64 s[20:21], -1, 0
	v_mov_b32_e32 v2, 1.0
	s_cbranch_vccnz .LBB0_736

; template <int MODE, bool FIRST, bool FOLD>
; __device__ __forceinline__ bool partialSM(f32x16& p0, f32x16& p1, float& m_reg, float& alpha, int relbase, bool near, const float* lut, float cb) {
;     ...
;     float pmax = p0[0];
; #pragma unroll
;     for (int r = 1; r < 16; ++r) pmax = fmaxf(pmax, p0[r]);
; #pragma unroll
;     for (int r = 0; r < 16; ++r) pmax = fmaxf(pmax, p1[r]);
;     { auto rr = __builtin_amdgcn_permlane32_swap(__float_as_uint(pmax), __float_as_uint(pmax), false, false);
;       pmax = fmaxf(__uint_as_float(rr[0]), __uint_as_float(rr[1])); }
;     bool resc;
;     if (FIRST && MODE != 2) resc = true; else resc = __any(pmax > THR2);
; template <int NQ, int MODE> ...
;     ...
;     f32x16 cinit = f32x16{}; float cur_cb = 0.f; bool dirty = true;
.LBB0_786:
	v_max_f32_e32 v0, v145, v145
	v_max_f32_e32 v10, v144, v144
	v_max_f32_e32 v0, v10, v0
	v_max_f32_e32 v10, v128, v129
	v_max3_f32 v0, v0, v146, v147
	v_max3_f32 v10, v10, v130, v131
	v_max3_f32 v0, v0, v148, v149
	v_max3_f32 v10, v10, v132, v133
	v_max3_f32 v0, v0, v150, v151
	v_max3_f32 v10, v10, v134, v135
	v_max3_f32 v0, v0, v152, v153
	v_max3_f32 v10, v10, v136, v137
	v_max3_f32 v0, v0, v154, v155
	v_max3_f32 v10, v10, v138, v139
	v_max3_f32 v0, v0, v156, v157
	v_max3_f32 v10, v10, v140, v141
	v_max3_f32 v0, v0, v158, v159
	v_max3_f32 v10, v10, v142, v143
	v_max_f32_e32 v0, v0, v10
	v_mov_b32_e32 v10, v0
	s_nop 1
	v_permlane32_swap_b32_e32 v0, v10
	v_max_f32_e32 v10, v0, v10
	v_cmp_lt_f32_e32 vcc, s51, v10
	s_cmp_lg_u64 vcc, 0
	s_cselect_b64 s[14:15], -1, 0
	v_mov_b32_e32 v0, 1.0
	s_cbranch_vccnz .LBB0_806

; template <int MODE, bool FIRST, bool FOLD>
; __device__ __forceinline__ bool partialSM(f32x16& p0, f32x16& p1, float& m_reg, float& alpha, int relbase, bool near, const float* lut, float cb) {
;     ...
;     float pmax = p0[0];
; #pragma unroll
;     for (int r = 1; r < 16; ++r) pmax = fmaxf(pmax, p0[r]);
; #pragma unroll
;     for (int r = 0; r < 16; ++r) pmax = fmaxf(pmax, p1[r]);
;     { auto rr = __builtin_amdgcn_permlane32_swap(__float_as_uint(pmax), __float_as_uint(pmax), false, false);
;       pmax = fmaxf(__uint_as_float(rr[0]), __uint_as_float(rr[1])); }
;     bool resc;
;     if (FIRST && MODE != 2) resc = true; else resc = __any(pmax > THR2);
; template <int NQ, int MODE> ...
;     ...
;     f32x16 cinit = f32x16{}; float cur_cb = 0.f; bool dirty = true;
.LBB0_801:
	v_max_f32_e32 v2, v145, v145
	v_max_f32_e32 v3, v144, v144
	v_max_f32_e32 v2, v3, v2
	v_max_f32_e32 v3, v112, v113
	v_max3_f32 v2, v2, v146, v147
	v_max3_f32 v3, v3, v114, v115
	v_max3_f32 v2, v2, v148, v149
	v_max3_f32 v3, v3, v116, v117
	v_max3_f32 v2, v2, v150, v151
	v_max3_f32 v3, v3, v118, v119
	v_max3_f32 v2, v2, v152, v153
	v_max3_f32 v3, v3, v120, v121
	v_max3_f32 v2, v2, v154, v155
	v_max3_f32 v3, v3, v122, v123
	v_max3_f32 v2, v2, v156, v157
	v_max3_f32 v3, v3, v124, v125
	v_max3_f32 v2, v2, v158, v159
	v_max3_f32 v3, v3, v126, v127
	v_max_f32_e32 v2, v2, v3
	v_mov_b32_e32 v3, v2
	s_nop 1
	v_permlane32_swap_b32_e32 v2, v3
	v_max_f32_e32 v3, v2, v3
	v_cmp_lt_f32_e32 vcc, s51, v3
	s_cmp_lg_u64 vcc, 0
	s_cselect_b64 s[12:13], -1, 0
	v_mov_b32_e32 v2, 1.0
	s_cbranch_vccnz .LBB0_811

; #define PG8_STAGE(bufoff, gbase, voff) do { _Pragma("unroll") for (int _i = 0; _i < 2; ++_i) \
;         __builtin_amdgcn_global_load_lds((const unsigned*)((const char*)(gbase) + (voff)[_i]), (LAS unsigned*)(lds + (bufoff) + ldsw + _i * 8192), 16, 0, 0); } while (0)
; #define PG8_WAIT_V(n) asm volatile("s_waitcnt vmcnt(" #n ")" ::: "memory")
; #define PG8_BAR __builtin_amdgcn_s_barrier()
; #define PH unsigned char* ws = a.ws; asm volatile("" : "+s"(ws)); int lq = l; asm volatile("" : "+s"(lq)); (void)lq;
; template <class Epi>
; __device__ __forceinline__ void gemm_phase(LAS unsigned char* lds, const Gemm g, const StaticOrder& S, const Epi& E, int wave_s) {
;     ...
;     const char* cA = (const char*)g.A + (size_t)cur.pm * tstepA; const char* cB = (const char*)g.Bt + (size_t)cur.pn * tstepB;
;     PG8_STAGE(PG8_SB(0, 0), cB, voffB); PG8_STAGE(PG8_SB(0, 1), cB + hstepB, voffB); PG8_STAGE(PG8_SA(0, 0), cA, voffA); PG8_STAGE(PG8_SA(0, 1), cA + hstepA, voffA);
;     if (wr == 1) PG8_BAR;
;     PG8_WAIT_V(2); PG8_BAR;
;     PG8_STAGE(PG8_SB(1, 0), cB + kstep, voffB); PG8_STAGE(PG8_SA(1, 0), cA + kstep, voffA); PG8_STAGE(PG8_SB(1, 1), cB + hstepB + kstep, voffB);
;     PG8_WAIT_V(6); PG8_BAR;
; __global__ void __launch_bounds__(NTHR, 2) mega_fwd(Args a) {
;     ...
;         { PH pg8::Gemm g{O, WOUT + (size_t)lq * DM * DM, SEQ, DM, DM, DM}; pg8::StaticOrder S; S.init(SEQ, DM, G, bx);
;           pg8::EpiRes E{(lq == 0) ? a.x : a.out, a.out, MOD + lq * 12288 + 2 * DM, DM}; pg8::gemm_phase(ldsl, g, S, E, wave_s); }
.LBB0_911:
	v_readlane_b32 s8, v254, 12
	v_readlane_b32 s10, v254, 14
	s_cmp_eq_u32 s26, 0
	v_readlane_b32 s9, v254, 13
	v_readlane_b32 s11, v254, 15
	s_mul_i32 s10, s26, 0x3000
	s_cselect_b32 s9, s9, s59
	s_cselect_b32 s8, s8, s58
	s_ashr_i32 s11, s10, 31
	s_lshl_b64 s[10:11], s[10:11], 2
	s_add_u32 s4, s4, s10
	s_addc_u32 s5, s5, s11
	s_add_u32 s10, s4, 0x104000
	s_addc_u32 s11, s5, 0
	v_and_b32_e32 v17, 48, v16
	v_lshlrev_b32_e32 v18, 6, v16
	s_movk_i32 s5, 0x3c0
	v_lshlrev_b32_e32 v16, 2, v16
	s_lshl_b32 s4, s56, 13
	v_and_or_b32 v17, v18, s5, v17
	v_and_b32_e32 v16, 32, v16
	v_bitop3_b32 v18, v17, s4, v16 bitop3:0xde
	s_lshl_b32 s4, s27, 5
	s_lshl_b32 s41, s56, 6
	s_and_b32 s56, s4, 0x60
	s_add_i32 m0, s35, 0x18000
	v_lshl_add_u64 v[8:9], v[8:9], 0, s[42:43]
	s_lshl_b32 s4, s56, 7
	s_waitcnt vmcnt(2)
	s_barrier
	global_load_lds_dwordx4 v[8:9], off
	v_lshl_add_u64 v[6:7], v[6:7], 0, s[42:43]
	s_add_i32 m0, s35, 0x1a000
	s_add_i32 s57, s35, 0x8000
	s_add_i32 s64, s35, 0xa000
	v_bitop3_b32 v158, s4, v17, v16 bitop3:0xf6
	global_load_lds_dwordx4 v[6:7], off
	v_lshl_add_u64 v[2:3], v[2:3], 0, s[42:43]
	s_mov_b32 m0, s57
	s_add_u32 s4, s72, 0x80080
	global_load_lds_dwordx4 v[2:3], off
	v_lshl_add_u64 v[2:3], v[4:5], 0, s[42:43]
	s_mov_b32 m0, s64
	s_addc_u32 s5, s73, 0
	global_load_lds_dwordx4 v[2:3], off
	s_add_i32 m0, s35, 0x1c000
	s_nop 0
	global_load_lds_dwordx4 v0, s[4:5]
	v_lshl_add_u64 v[2:3], s[4:5], 0, v[146:147]
	s_add_i32 m0, s35, 0x1e000
	v_readlane_b32 s12, v254, 16
	global_load_lds_dwordx4 v[2:3], off
	v_lshlrev_b32_e32 v2, 15, v10
	v_and_b32_e32 v2, 0xffff0000, v2
	v_lshl_add_u32 v2, v11, 12, v2
	v_and_b32_e32 v3, 1, v10
	v_lshl_or_b32 v2, v3, 6, v2
	v_lshl_add_u32 v148, v12, 1, v2
	v_lshlrev_b32_e32 v2, 15, v13
	v_and_b32_e32 v2, 0xffff0000, v2
	s_waitcnt vmcnt(6)
	v_lshl_add_u32 v2, v14, 12, v2
	v_and_b32_e32 v3, 1, v13
	v_readlane_b32 s13, v254, 17
	s_cmpk_lt_u32 s65, 0x100
	v_lshl_or_b32 v2, v3, 6, v2
	v_readlane_b32 s4, v255, 15
	s_mov_b32 s40, 0
	v_readlane_b32 s14, v254, 18
	v_readlane_b32 s16, v254, 20
	s_cselect_b64 s[12:13], -1, 0
	v_mov_b32_e32 v149, v1
	v_lshl_add_u32 v150, v15, 1, v2
	v_mov_b32_e32 v151, v1
	v_add_u32_e32 v159, 0, v18
	v_readlane_b32 s66, v255, 3
	s_mov_b32 s65, s4
	v_readlane_b32 s15, v254, 19
	v_readlane_b32 s17, v254, 21
	v_readlane_b32 s18, v254, 22
	v_readlane_b32 s19, v254, 23
	v_readlane_b32 s20, v254, 24
	v_readlane_b32 s21, v254, 25
	v_readlane_b32 s22, v254, 26
	v_readlane_b32 s23, v254, 27
	s_barrier
	v_readlane_b32 s5, v255, 16
	s_branch .LBB0_914

; #define PG8_STAGE(bufoff, gbase, voff) do { _Pragma("unroll") for (int _i = 0; _i < 2; ++_i) \
;         __builtin_amdgcn_global_load_lds((const unsigned*)((const char*)(gbase) + (voff)[_i]), (LAS unsigned*)(lds + (bufoff) + ldsw + _i * 8192), 16, 0, 0); } while (0)
; #define PG8_LDA(dst, b, h) do { _Pragma("unroll") for (int m = 0; m < 4; ++m) _Pragma("unroll") for (int k = 0; k < 2; ++k) dst[m][k] = *(const LAS bf16x8*)(lds + PG8_SA(b, h) + aoff + m * 2048 + k * 1024); } while (0)
; #define PG8_LDB(dst, b, h) do { _Pragma("unroll") for (int n = 0; n < 2; ++n) _Pragma("unroll") for (int k = 0; k < 2; ++k) dst[n][k] = *(const LAS bf16x8*)(lds + PG8_SB(b, h) + boff + n * 2048 + k * 1024); } while (0)
; #define PG8_MMA(ai, bj, At, Bt) do { __builtin_amdgcn_s_setprio(1); _Pragma("unroll") for (int m = 0; m < 4; ++m) _Pragma("unroll") for (int n = 0; n < 2; ++n) _Pragma("unroll") for (int k = 0; k < 2; ++k) \
;         acc[ai][bj][m][n] = __builtin_amdgcn_mfma_f32_16x16x32_bf16(Bt[n][k], At[m][k], acc[ai][bj][m][n], 0, 0, 0); __builtin_amdgcn_s_setprio(0); } while (0)
; #define PG8_WAIT_V(n) asm volatile("s_waitcnt vmcnt(" #n ")" ::: "memory")
; #define PG8_BAR __builtin_amdgcn_s_barrier()
; template <class Epi>
; __device__ __forceinline__ void gemm_phase(LAS unsigned char* lds, const Gemm g, const StaticOrder& S, const Epi& E, int wave_s) {
;     ...
;         const char* nA = has_next ? (const char*)g.A + (size_t)nxt.pm * tstepA : cA; const char* nB = has_next ? (const char*)g.Bt + (size_t)nxt.pn * tstepB : cB;
;         for (int t = 0; t < nt; t += 2) {
;             const bool last = (t == nt - 2);
;             const char* a1 = cA + (size_t)(t + 1) * kstep;
;             const char* a2 = last ? nA : cA + (size_t)(t + 2) * kstep; const char* b2 = last ? nB : cB + (size_t)(t + 2) * kstep;
;             const char* a3 = a2 + kstep; const char* b3 = b2 + kstep;
;             PG8_LDB(B0, 0, 0); PG8_LDB(B1, 0, 1); PG8_SCHED; PG8_LDA(At, 0, 0); PG8_STAGE(PG8_SA(1, 1), a1 + hstepA, voffA);
;             PG8_WAIT_V(8); PG8_WAIT_L(0); PG8_BAR; PG8_MMA(0, 0, At, B0); PG8_MMA(0, 1, At, B1); PG8_BAR; PG8_SCHED;
;             PG8_LDA(At, 0, 1); PG8_STAGE(PG8_SB(0, 0), b2, voffB); PG8_STAGE(PG8_SB(0, 1), b2 + hstepB, voffB); PG8_STAGE(PG8_SA(0, 0), a2, voffA);
;             PG8_WAIT_V(8); PG8_WAIT_L(0); PG8_BAR; PG8_MMA(1, 0, At, B0); PG8_MMA(1, 1, At, B1); PG8_BAR; PG8_SCHED;
.LBB0_921:
	s_add_u32 s24, s22, 0xfff80080
	s_addc_u32 s25, s23, -1
	s_add_i32 s78, 0, 0x10000
	s_cmp_eq_u32 s73, 28
	s_cselect_b32 s27, s17, s25
	s_cselect_b32 s26, s67, s24
	s_cselect_b32 s25, s15, s72
	s_cselect_b32 s24, s70, s71
	s_add_i32 s82, 0, 0x14000
	v_add_u32_e32 v142, s78, v158
	v_add_u32_e32 v156, s82, v158
	ds_read_b128 v[130:133], v142
	ds_read_b128 v[134:137], v142 offset:1024
	ds_read_b128 v[138:141], v142 offset:2048
	ds_read_b128 v[142:145], v142 offset:3072
	ds_read_b128 v[152:155], v156
	ds_read_b128 v[160:163], v156 offset:1024
	ds_read_b128 v[164:167], v156 offset:2048
	ds_read_b128 v[168:171], v156 offset:3072
	v_lshl_add_u64 v[156:157], s[22:23], 0, v[150:151]
	s_add_i32 m0, s35, 0xc000
	ds_read_b128 v[172:175], v159
	ds_read_b128 v[176:179], v159 offset:1024
	ds_read_b128 v[180:183], v159 offset:2048
	ds_read_b128 v[184:187], v159 offset:3072
	ds_read_b128 v[188:191], v159 offset:4096
	ds_read_b128 v[192:195], v159 offset:5120
	ds_read_b128 v[196:199], v159 offset:6144
	ds_read_b128 v[200:203], v159 offset:7168
	global_load_lds_dwordx4 v[156:157], off
	v_lshl_add_u64 v[156:157], s[22:23], 0, v[148:149]
	s_add_i32 m0, s35, 0xe000
	s_nop 0
	global_load_lds_dwordx4 v[156:157], off
	s_waitcnt vmcnt(8)
	s_waitcnt lgkmcnt(0)
	s_barrier
	s_setprio 1
	s_waitcnt lgkmcnt(0)
	v_mfma_f32_16x16x32_bf16 v[126:129], v[130:133], v[172:175], v[126:129]
	v_mfma_f32_16x16x32_bf16 v[122:125], v[138:141], v[172:175], v[122:125]
	v_mfma_f32_16x16x32_bf16 v[118:121], v[130:133], v[180:183], v[118:121]
	v_mfma_f32_16x16x32_bf16 v[114:117], v[138:141], v[180:183], v[114:117]
	v_mfma_f32_16x16x32_bf16 v[110:113], v[130:133], v[188:191], v[110:113]
	v_mfma_f32_16x16x32_bf16 v[98:101], v[138:141], v[188:191], v[98:101]
	v_mfma_f32_16x16x32_bf16 v[82:85], v[130:133], v[196:199], v[82:85]
	v_mfma_f32_16x16x32_bf16 v[74:77], v[138:141], v[196:199], v[74:77]
	v_mfma_f32_16x16x32_bf16 v[126:129], v[134:137], v[176:179], v[126:129]
	v_mfma_f32_16x16x32_bf16 v[122:125], v[142:145], v[176:179], v[122:125]
	v_mfma_f32_16x16x32_bf16 v[118:121], v[134:137], v[184:187], v[118:121]
	v_mfma_f32_16x16x32_bf16 v[114:117], v[142:145], v[184:187], v[114:117]
	v_mfma_f32_16x16x32_bf16 v[110:113], v[134:137], v[192:195], v[110:113]
	v_mfma_f32_16x16x32_bf16 v[98:101], v[142:145], v[192:195], v[98:101]
	v_mfma_f32_16x16x32_bf16 v[82:85], v[134:137], v[200:203], v[82:85]
	v_mfma_f32_16x16x32_bf16 v[74:77], v[142:145], v[200:203], v[74:77]
	s_setprio 0
	s_setprio 1
	v_mfma_f32_16x16x32_bf16 v[106:109], v[152:155], v[172:175], v[106:109]
	v_mfma_f32_16x16x32_bf16 v[102:105], v[164:167], v[172:175], v[102:105]
	v_mfma_f32_16x16x32_bf16 v[94:97], v[152:155], v[180:183], v[94:97]
	v_mfma_f32_16x16x32_bf16 v[90:93], v[164:167], v[180:183], v[90:93]
	v_mfma_f32_16x16x32_bf16 v[86:89], v[152:155], v[188:191], v[86:89]
	v_mfma_f32_16x16x32_bf16 v[78:81], v[164:167], v[188:191], v[78:81]
	v_mfma_f32_16x16x32_bf16 v[70:73], v[152:155], v[196:199], v[70:73]
	v_mfma_f32_16x16x32_bf16 v[66:69], v[164:167], v[196:199], v[66:69]
	v_mfma_f32_16x16x32_bf16 v[106:109], v[160:163], v[176:179], v[106:109]
	v_mfma_f32_16x16x32_bf16 v[102:105], v[168:171], v[176:179], v[102:105]
	v_mfma_f32_16x16x32_bf16 v[94:97], v[160:163], v[184:187], v[94:97]
	v_mfma_f32_16x16x32_bf16 v[90:93], v[168:171], v[184:187], v[90:93]
	v_mfma_f32_16x16x32_bf16 v[86:89], v[160:163], v[192:195], v[86:89]
	v_mfma_f32_16x16x32_bf16 v[78:81], v[168:171], v[192:195], v[78:81]
	v_mfma_f32_16x16x32_bf16 v[70:73], v[160:163], v[200:203], v[70:73]
	v_mfma_f32_16x16x32_bf16 v[66:69], v[168:171], v[200:203], v[66:69]
	s_setprio 0
	s_barrier
	s_add_i32 s78, s78, s34
	v_lshl_add_u64 v[156:157], s[24:25], 0, v[0:1]
	s_mov_b32 m0, s78
	ds_read_b128 v[172:175], v159 offset:16384
	ds_read_b128 v[176:179], v159 offset:17408
	ds_read_b128 v[180:183], v159 offset:18432
	ds_read_b128 v[184:187], v159 offset:19456
	ds_read_b128 v[188:191], v159 offset:20480
	ds_read_b128 v[192:195], v159 offset:21504
	ds_read_b128 v[196:199], v159 offset:22528
	ds_read_b128 v[200:203], v159 offset:23552
	global_load_lds_dwordx4 v[156:157], off
	s_add_i32 m0, s78, 0x2000
	s_add_u32 s78, s24, 0x80000
	v_lshl_add_u64 v[204:205], s[24:25], 0, v[146:147]
	s_addc_u32 s79, s25, 0
	s_add_i32 s82, s82, s34
	global_load_lds_dwordx4 v[204:205], off
	s_mov_b32 m0, s82
	v_lshl_add_u64 v[208:209], s[26:27], 0, v[146:147]
	global_load_lds_dwordx4 v0, s[78:79]
	v_lshl_add_u64 v[206:207], s[78:79], 0, v[146:147]
	s_add_i32 m0, s82, 0x2000
	s_nop 0
	global_load_lds_dwordx4 v[206:207], off
	v_lshl_add_u64 v[206:207], s[26:27], 0, v[0:1]
	s_mov_b32 m0, s35
	s_nop 0
	global_load_lds_dwordx4 v[206:207], off
	s_mov_b32 m0, s37
	s_nop 0
	global_load_lds_dwordx4 v[208:209], off
	s_waitcnt vmcnt(8)
	s_waitcnt lgkmcnt(0)
	s_barrier
; #define PG8_STAGE(bufoff, gbase, voff) do { _Pragma("unroll") for (int _i = 0; _i < 2; ++_i) \
;         __builtin_amdgcn_global_load_lds((const unsigned*)((const char*)(gbase) + (voff)[_i]), (LAS unsigned*)(lds + (bufoff) + ldsw + _i * 8192), 16, 0, 0); } while (0)
; #define PG8_LDA(dst, b, h) do { _Pragma("unroll") for (int m = 0; m < 4; ++m) _Pragma("unroll") for (int k = 0; k < 2; ++k) dst[m][k] = *(const LAS bf16x8*)(lds + PG8_SA(b, h) + aoff + m * 2048 + k * 1024); } while (0)
; #define PG8_LDB(dst, b, h) do { _Pragma("unroll") for (int n = 0; n < 2; ++n) _Pragma("unroll") for (int k = 0; k < 2; ++k) dst[n][k] = *(const LAS bf16x8*)(lds + PG8_SB(b, h) + boff + n * 2048 + k * 1024); } while (0)
; #define PG8_MMA(ai, bj, At, Bt) do { __builtin_amdgcn_s_setprio(1); _Pragma("unroll") for (int m = 0; m < 4; ++m) _Pragma("unroll") for (int n = 0; n < 2; ++n) _Pragma("unroll") for (int k = 0; k < 2; ++k) \
;         acc[ai][bj][m][n] = __builtin_amdgcn_mfma_f32_16x16x32_bf16(Bt[n][k], At[m][k], acc[ai][bj][m][n], 0, 0, 0); __builtin_amdgcn_s_setprio(0); } while (0)
; #define PG8_WAIT_V(n) asm volatile("s_waitcnt vmcnt(" #n ")" ::: "memory")
; #define PG8_WAIT_L(n) asm volatile("s_waitcnt lgkmcnt(" #n ")" ::: "memory")
; #define PG8_BAR __builtin_amdgcn_s_barrier()
; #define PG8_SCHED __builtin_amdgcn_sched_barrier(0)
; template <class Epi>
; __device__ __forceinline__ void gemm_phase(LAS unsigned char* lds, const Gemm g, const StaticOrder& S, const Epi& E, int wave_s) {
;     ...
;             PG8_WAIT_V(8); PG8_WAIT_L(0); PG8_BAR; PG8_MMA(1, 0, At, B0); PG8_MMA(1, 1, At, B1); PG8_BAR; PG8_SCHED;
;             PG8_LDB(B0, 1, 0); PG8_LDB(B1, 1, 1); PG8_SCHED; PG8_LDA(At, 1, 0); PG8_STAGE(PG8_SA(0, 1), a2 + hstepA, voffA);
;             PG8_WAIT_V(8); PG8_WAIT_L(0); PG8_BAR; PG8_MMA(0, 0, At, B0); PG8_MMA(0, 1, At, B1); PG8_BAR; PG8_SCHED;
	s_setprio 1
	s_waitcnt lgkmcnt(0)
	v_mfma_f32_16x16x32_bf16 v[62:65], v[130:133], v[172:175], v[62:65]
	v_mfma_f32_16x16x32_bf16 v[58:61], v[138:141], v[172:175], v[58:61]
	v_mfma_f32_16x16x32_bf16 v[54:57], v[130:133], v[180:183], v[54:57]
	v_mfma_f32_16x16x32_bf16 v[50:53], v[138:141], v[180:183], v[50:53]
	v_mfma_f32_16x16x32_bf16 v[46:49], v[130:133], v[188:191], v[46:49]
	v_mfma_f32_16x16x32_bf16 v[34:37], v[138:141], v[188:191], v[34:37]
	v_mfma_f32_16x16x32_bf16 v[22:25], v[130:133], v[196:199], v[22:25]
	v_mfma_f32_16x16x32_bf16 v[14:17], v[138:141], v[196:199], v[14:17]
	v_mfma_f32_16x16x32_bf16 v[62:65], v[134:137], v[176:179], v[62:65]
	v_mfma_f32_16x16x32_bf16 v[58:61], v[142:145], v[176:179], v[58:61]
	v_mfma_f32_16x16x32_bf16 v[54:57], v[134:137], v[184:187], v[54:57]
	v_mfma_f32_16x16x32_bf16 v[50:53], v[142:145], v[184:187], v[50:53]
	v_mfma_f32_16x16x32_bf16 v[46:49], v[134:137], v[192:195], v[46:49]
	v_mfma_f32_16x16x32_bf16 v[34:37], v[142:145], v[192:195], v[34:37]
	v_mfma_f32_16x16x32_bf16 v[22:25], v[134:137], v[200:203], v[22:25]
	v_mfma_f32_16x16x32_bf16 v[14:17], v[142:145], v[200:203], v[14:17]
	s_setprio 0
	s_setprio 1
	v_mfma_f32_16x16x32_bf16 v[42:45], v[152:155], v[172:175], v[42:45]
	v_mfma_f32_16x16x32_bf16 v[38:41], v[164:167], v[172:175], v[38:41]
	v_mfma_f32_16x16x32_bf16 v[30:33], v[152:155], v[180:183], v[30:33]
	v_mfma_f32_16x16x32_bf16 v[26:29], v[164:167], v[180:183], v[26:29]
	v_mfma_f32_16x16x32_bf16 v[18:21], v[152:155], v[188:191], v[18:21]
	v_mfma_f32_16x16x32_bf16 v[10:13], v[164:167], v[188:191], v[10:13]
	v_mfma_f32_16x16x32_bf16 v[6:9], v[152:155], v[196:199], v[6:9]
	v_mfma_f32_16x16x32_bf16 v[2:5], v[164:167], v[196:199], v[2:5]
	v_mfma_f32_16x16x32_bf16 v[42:45], v[160:163], v[176:179], v[42:45]
	v_mfma_f32_16x16x32_bf16 v[38:41], v[168:171], v[176:179], v[38:41]
	v_mfma_f32_16x16x32_bf16 v[30:33], v[160:163], v[184:187], v[30:33]
	v_mfma_f32_16x16x32_bf16 v[26:29], v[168:171], v[184:187], v[26:29]
	v_mfma_f32_16x16x32_bf16 v[18:21], v[160:163], v[192:195], v[18:21]
	v_mfma_f32_16x16x32_bf16 v[10:13], v[168:171], v[192:195], v[10:13]
	v_mfma_f32_16x16x32_bf16 v[6:9], v[160:163], v[200:203], v[6:9]
	v_mfma_f32_16x16x32_bf16 v[2:5], v[168:171], v[200:203], v[2:5]
	s_setprio 0
	s_barrier
	s_add_i32 s78, 0, 0x18000
	s_add_i32 s79, 0, 0x1c000
	v_add_u32_e32 v142, s78, v158
	v_add_u32_e32 v168, s79, v158
	ds_read_b128 v[130:133], v142
	ds_read_b128 v[134:137], v142 offset:1024
	ds_read_b128 v[138:141], v142 offset:2048
	ds_read_b128 v[142:145], v142 offset:3072
	ds_read_b128 v[152:155], v168
	ds_read_b128 v[160:163], v168 offset:1024
	ds_read_b128 v[164:167], v168 offset:2048
	ds_read_b128 v[168:171], v168 offset:3072
	s_add_u32 s26, s26, 0x80000
	s_addc_u32 s27, s27, 0
	s_mov_b32 m0, s38
	ds_read_b128 v[172:175], v159 offset:32768
	ds_read_b128 v[176:179], v159 offset:33792
	ds_read_b128 v[180:183], v159 offset:34816
	ds_read_b128 v[184:187], v159 offset:35840
	ds_read_b128 v[188:191], v159 offset:36864
	ds_read_b128 v[192:195], v159 offset:37888
	ds_read_b128 v[196:199], v159 offset:38912
	ds_read_b128 v[200:203], v159 offset:39936
	global_load_lds_dwordx4 v0, s[26:27]
	v_lshl_add_u64 v[210:211], s[26:27], 0, v[146:147]
	s_mov_b32 m0, s39
	s_nop 0
	global_load_lds_dwordx4 v[210:211], off
	s_waitcnt vmcnt(8)
	s_waitcnt lgkmcnt(0)
	s_barrier
	s_setprio 1
	s_waitcnt lgkmcnt(0)
	v_mfma_f32_16x16x32_bf16 v[126:129], v[130:133], v[172:175], v[126:129]
	v_mfma_f32_16x16x32_bf16 v[122:125], v[138:141], v[172:175], v[122:125]
	v_mfma_f32_16x16x32_bf16 v[118:121], v[130:133], v[180:183], v[118:121]
	v_mfma_f32_16x16x32_bf16 v[114:117], v[138:141], v[180:183], v[114:117]
	v_mfma_f32_16x16x32_bf16 v[110:113], v[130:133], v[188:191], v[110:113]
	v_mfma_f32_16x16x32_bf16 v[98:101], v[138:141], v[188:191], v[98:101]
	v_mfma_f32_16x16x32_bf16 v[82:85], v[130:133], v[196:199], v[82:85]
	v_mfma_f32_16x16x32_bf16 v[74:77], v[138:141], v[196:199], v[74:77]
	v_mfma_f32_16x16x32_bf16 v[126:129], v[134:137], v[176:179], v[126:129]
	v_mfma_f32_16x16x32_bf16 v[122:125], v[142:145], v[176:179], v[122:125]
	v_mfma_f32_16x16x32_bf16 v[118:121], v[134:137], v[184:187], v[118:121]
	v_mfma_f32_16x16x32_bf16 v[114:117], v[142:145], v[184:187], v[114:117]
	v_mfma_f32_16x16x32_bf16 v[110:113], v[134:137], v[192:195], v[110:113]
	v_mfma_f32_16x16x32_bf16 v[98:101], v[142:145], v[192:195], v[98:101]
	v_mfma_f32_16x16x32_bf16 v[82:85], v[134:137], v[200:203], v[82:85]
	v_mfma_f32_16x16x32_bf16 v[74:77], v[142:145], v[200:203], v[74:77]
	s_setprio 0
	s_setprio 1
	v_mfma_f32_16x16x32_bf16 v[106:109], v[152:155], v[172:175], v[106:109]
	v_mfma_f32_16x16x32_bf16 v[102:105], v[164:167], v[172:175], v[102:105]
	v_mfma_f32_16x16x32_bf16 v[94:97], v[152:155], v[180:183], v[94:97]
	v_mfma_f32_16x16x32_bf16 v[90:93], v[164:167], v[180:183], v[90:93]
	v_mfma_f32_16x16x32_bf16 v[86:89], v[152:155], v[188:191], v[86:89]
	v_mfma_f32_16x16x32_bf16 v[78:81], v[164:167], v[188:191], v[78:81]
	v_mfma_f32_16x16x32_bf16 v[70:73], v[152:155], v[196:199], v[70:73]
	v_mfma_f32_16x16x32_bf16 v[66:69], v[164:167], v[196:199], v[66:69]
	v_mfma_f32_16x16x32_bf16 v[106:109], v[160:163], v[176:179], v[106:109]
	v_mfma_f32_16x16x32_bf16 v[102:105], v[168:171], v[176:179], v[102:105]
	v_mfma_f32_16x16x32_bf16 v[94:97], v[160:163], v[184:187], v[94:97]
	v_mfma_f32_16x16x32_bf16 v[90:93], v[168:171], v[184:187], v[90:93]
	v_mfma_f32_16x16x32_bf16 v[86:89], v[160:163], v[192:195], v[86:89]
	v_mfma_f32_16x16x32_bf16 v[78:81], v[168:171], v[192:195], v[78:81]
	v_mfma_f32_16x16x32_bf16 v[70:73], v[160:163], v[200:203], v[70:73]
	v_mfma_f32_16x16x32_bf16 v[66:69], v[168:171], v[200:203], v[66:69]
	s_setprio 0
	s_barrier
; #define PG8_STAGE(bufoff, gbase, voff) do { _Pragma("unroll") for (int _i = 0; _i < 2; ++_i) \
;         __builtin_amdgcn_global_load_lds((const unsigned*)((const char*)(gbase) + (voff)[_i]), (LAS unsigned*)(lds + (bufoff) + ldsw + _i * 8192), 16, 0, 0); } while (0)
; #define PG8_LDA(dst, b, h) do { _Pragma("unroll") for (int m = 0; m < 4; ++m) _Pragma("unroll") for (int k = 0; k < 2; ++k) dst[m][k] = *(const LAS bf16x8*)(lds + PG8_SA(b, h) + aoff + m * 2048 + k * 1024); } while (0)
; #define PG8_MMA(ai, bj, At, Bt) do { __builtin_amdgcn_s_setprio(1); _Pragma("unroll") for (int m = 0; m < 4; ++m) _Pragma("unroll") for (int n = 0; n < 2; ++n) _Pragma("unroll") for (int k = 0; k < 2; ++k) \
;         acc[ai][bj][m][n] = __builtin_amdgcn_mfma_f32_16x16x32_bf16(Bt[n][k], At[m][k], acc[ai][bj][m][n], 0, 0, 0); __builtin_amdgcn_s_setprio(0); } while (0)
; #define PG8_WAIT_V(n) asm volatile("s_waitcnt vmcnt(" #n ")" ::: "memory")
; #define PG8_WAIT_L(n) asm volatile("s_waitcnt lgkmcnt(" #n ")" ::: "memory")
; #define PG8_BAR __builtin_amdgcn_s_barrier()
; #define PG8_SCHED __builtin_amdgcn_sched_barrier(0)
; template <class Epi>
; __device__ __forceinline__ void gemm_phase(LAS unsigned char* lds, const Gemm g, const StaticOrder& S, const Epi& E, int wave_s) {
;     ...
;             PG8_LDA(At, 1, 1); PG8_STAGE(PG8_SB(1, 0), b3, voffB); PG8_STAGE(PG8_SB(1, 1), b3 + hstepB, voffB); PG8_STAGE(PG8_SA(1, 0), a3, voffA);
;             PG8_WAIT_V(8); PG8_WAIT_L(0); PG8_BAR; PG8_MMA(1, 0, At, B0); PG8_MMA(1, 1, At, B1); PG8_BAR; PG8_SCHED;
;         }
;         if (wr == 0) PG8_BAR;
	s_add_i32 s26, s78, s34
	v_lshl_add_u64 v[156:157], v[156:157], 0, s[42:43]
	s_mov_b32 m0, s26
	ds_read_b128 v[172:175], v159 offset:49152
	ds_read_b128 v[176:179], v159 offset:50176
	ds_read_b128 v[180:183], v159 offset:51200
	ds_read_b128 v[184:187], v159 offset:52224
	ds_read_b128 v[188:191], v159 offset:53248
	ds_read_b128 v[192:195], v159 offset:54272
	ds_read_b128 v[196:199], v159 offset:55296
	ds_read_b128 v[200:203], v159 offset:56320
	global_load_lds_dwordx4 v[156:157], off
	s_add_i32 m0, s26, 0x2000
	s_add_u32 s24, s24, 0x80080
	v_lshl_add_u64 v[156:157], v[204:205], 0, s[42:43]
	s_addc_u32 s25, s25, 0
	s_add_i32 s26, s79, s34
	global_load_lds_dwordx4 v[156:157], off
	s_mov_b32 m0, s26
	s_nop 0
	global_load_lds_dwordx4 v0, s[24:25]
	v_lshl_add_u64 v[156:157], s[24:25], 0, v[146:147]
	s_add_i32 m0, s26, 0x2000
	s_nop 0
	global_load_lds_dwordx4 v[156:157], off
	v_lshl_add_u64 v[156:157], v[206:207], 0, s[42:43]
	s_mov_b32 m0, s57
	s_nop 0
	global_load_lds_dwordx4 v[156:157], off
	v_lshl_add_u64 v[156:157], v[208:209], 0, s[42:43]
	s_mov_b32 m0, s64
	s_nop 0
	global_load_lds_dwordx4 v[156:157], off
	s_waitcnt vmcnt(8)
	s_waitcnt lgkmcnt(0)
	s_barrier
	s_setprio 1
	s_waitcnt lgkmcnt(0)
	v_mfma_f32_16x16x32_bf16 v[62:65], v[130:133], v[172:175], v[62:65]
	v_mfma_f32_16x16x32_bf16 v[58:61], v[138:141], v[172:175], v[58:61]
	v_mfma_f32_16x16x32_bf16 v[54:57], v[130:133], v[180:183], v[54:57]
	v_mfma_f32_16x16x32_bf16 v[50:53], v[138:141], v[180:183], v[50:53]
	v_mfma_f32_16x16x32_bf16 v[46:49], v[130:133], v[188:191], v[46:49]
	v_mfma_f32_16x16x32_bf16 v[34:37], v[138:141], v[188:191], v[34:37]
	v_mfma_f32_16x16x32_bf16 v[22:25], v[130:133], v[196:199], v[22:25]
	v_mfma_f32_16x16x32_bf16 v[14:17], v[138:141], v[196:199], v[14:17]
	v_mfma_f32_16x16x32_bf16 v[62:65], v[134:137], v[176:179], v[62:65]
	v_mfma_f32_16x16x32_bf16 v[58:61], v[142:145], v[176:179], v[58:61]
	v_mfma_f32_16x16x32_bf16 v[54:57], v[134:137], v[184:187], v[54:57]
	v_mfma_f32_16x16x32_bf16 v[50:53], v[142:145], v[184:187], v[50:53]
	v_mfma_f32_16x16x32_bf16 v[46:49], v[134:137], v[192:195], v[46:49]
	v_mfma_f32_16x16x32_bf16 v[34:37], v[142:145], v[192:195], v[34:37]
	v_mfma_f32_16x16x32_bf16 v[22:25], v[134:137], v[200:203], v[22:25]
	v_mfma_f32_16x16x32_bf16 v[14:17], v[142:145], v[200:203], v[14:17]
	s_setprio 0
	s_setprio 1
	v_mfma_f32_16x16x32_bf16 v[42:45], v[152:155], v[172:175], v[42:45]
	v_mfma_f32_16x16x32_bf16 v[38:41], v[164:167], v[172:175], v[38:41]
	v_mfma_f32_16x16x32_bf16 v[30:33], v[152:155], v[180:183], v[30:33]
	v_mfma_f32_16x16x32_bf16 v[26:29], v[164:167], v[180:183], v[26:29]
	v_mfma_f32_16x16x32_bf16 v[18:21], v[152:155], v[188:191], v[18:21]
	v_mfma_f32_16x16x32_bf16 v[10:13], v[164:167], v[188:191], v[10:13]
	v_mfma_f32_16x16x32_bf16 v[6:9], v[152:155], v[196:199], v[6:9]
	v_mfma_f32_16x16x32_bf16 v[2:5], v[164:167], v[196:199], v[2:5]
	v_mfma_f32_16x16x32_bf16 v[42:45], v[160:163], v[176:179], v[42:45]
	v_mfma_f32_16x16x32_bf16 v[38:41], v[168:171], v[176:179], v[38:41]
	v_mfma_f32_16x16x32_bf16 v[30:33], v[160:163], v[184:187], v[30:33]
	v_mfma_f32_16x16x32_bf16 v[26:29], v[168:171], v[184:187], v[26:29]
	v_mfma_f32_16x16x32_bf16 v[18:21], v[160:163], v[192:195], v[18:21]
	v_mfma_f32_16x16x32_bf16 v[10:13], v[168:171], v[192:195], v[10:13]
	v_mfma_f32_16x16x32_bf16 v[6:9], v[160:163], v[200:203], v[6:9]
	v_mfma_f32_16x16x32_bf16 v[2:5], v[168:171], v[200:203], v[2:5]
	s_setprio 0
	s_barrier
	s_add_i32 s73, s73, 2
	s_add_u32 s71, s71, 0x100
	s_addc_u32 s72, s72, 0
	s_add_u32 s22, s22, 0x100
	s_addc_u32 s23, s23, 0
	s_cmp_gt_u32 s73, 29
	s_cbranch_scc0 .LBB0_921
	s_and_b64 vcc, exec, s[12:13]
	s_cbranch_vccz .LBB0_924
	s_barrier

; template <bool FINAL>
; __device__ __forceinline__ void norm_pass(const float* X, const float* g, const float* scale, const float* shift, bf16_t* H, float* OUTF, int vcu_, int NGW_, int wave_s) {
;     ...
;         for (int j = 0; j < 8; ++j) ss += (v[j].x * v[j].x + v[j].y * v[j].y) + (v[j].z * v[j].z + v[j].w * v[j].w);
;         const float rstd = 1.0f / sqrtf(wave_sum(ss) * (1.f / DM) + EPS);
.LBB0_974:
	v_mul_f32_e32 v0, v95, v95
	v_mul_f32_e32 v134, v97, v97
	v_fmac_f32_e32 v0, v94, v94
	v_fmac_f32_e32 v134, v96, v96
	v_add_f32_e32 v0, v0, v134
	v_mul_f32_e32 v134, v91, v91
	v_mul_f32_e32 v135, v93, v93
	v_fmac_f32_e32 v134, v90, v90
	v_fmac_f32_e32 v135, v92, v92
	v_add_f32_e32 v134, v134, v135
	v_add_f32_e32 v0, v134, v0
	v_mul_f32_e32 v134, v87, v87
	v_mul_f32_e32 v135, v89, v89
	v_fmac_f32_e32 v134, v86, v86
	v_fmac_f32_e32 v135, v88, v88
	v_add_f32_e32 v134, v134, v135
	v_add_f32_e32 v0, v134, v0
	v_mul_f32_e32 v134, v83, v83
	v_mul_f32_e32 v135, v85, v85
	v_fmac_f32_e32 v134, v82, v82
	v_fmac_f32_e32 v135, v84, v84
	v_add_f32_e32 v134, v134, v135
	v_add_f32_e32 v0, v134, v0
	v_mul_f32_e32 v134, v79, v79
	v_mul_f32_e32 v135, v81, v81
	v_fmac_f32_e32 v134, v78, v78
	v_fmac_f32_e32 v135, v80, v80
	v_add_f32_e32 v134, v134, v135
	v_add_f32_e32 v0, v134, v0
	v_mul_f32_e32 v134, v75, v75
	v_mul_f32_e32 v135, v77, v77
	v_fmac_f32_e32 v134, v74, v74
	v_fmac_f32_e32 v135, v76, v76
	v_add_f32_e32 v134, v134, v135
	v_add_f32_e32 v0, v134, v0
	v_mul_f32_e32 v134, v39, v39
	v_mul_f32_e32 v135, v41, v41
	v_fmac_f32_e32 v134, v38, v38
	v_fmac_f32_e32 v135, v40, v40
	v_add_f32_e32 v134, v134, v135
	v_add_f32_e32 v0, v134, v0
	v_mul_f32_e32 v134, v35, v35
	v_mul_f32_e32 v135, v37, v37
	v_fmac_f32_e32 v134, v34, v34
	v_fmac_f32_e32 v135, v36, v36
	v_add_f32_e32 v134, v134, v135
	v_add_f32_e32 v0, v134, v0
	ds_swizzle_b32 v134, v0 offset:swizzle(SWAP,1)
	v_lshl_add_u64 v[132:133], v[132:133], 0, s[12:13]
	s_waitcnt lgkmcnt(0)
	v_add_f32_e32 v0, v0, v134
	ds_swizzle_b32 v134, v0 offset:swizzle(SWAP,2)
	s_waitcnt lgkmcnt(0)
	v_add_f32_e32 v0, v0, v134
	ds_swizzle_b32 v134, v0 offset:swizzle(SWAP,4)
	s_waitcnt lgkmcnt(0)
	v_add_f32_e32 v0, v0, v134
	ds_swizzle_b32 v134, v0 offset:swizzle(SWAP,8)
	s_waitcnt lgkmcnt(0)
	v_add_f32_e32 v0, v0, v134
	ds_swizzle_b32 v134, v0 offset:swizzle(SWAP,16)
	s_waitcnt lgkmcnt(0)
; __device__ __forceinline__ unsigned pk2(float lo, float hi) { return f2bf(lo) | (f2bf(hi) << 16); }
; template <bool FINAL>
; __device__ __forceinline__ void norm_pass(const float* X, const float* g, const float* scale, const float* shift, bf16_t* H, float* OUTF, int vcu_, int NGW_, int wave_s) {
;     ...
;     for (int m = gw; m < SEQ; m += NGW) {
;         f32x4 v[8]; float ss = 0.f;
; #pragma unroll
;         for (int j = 0; j < 8; ++j) v[j] = nv[j];
;         if (m + NGW < SEQ) { const f32x4* xn = (const f32x4*)(X + (size_t)(m + NGW) * DM) + lane;
; #pragma unroll
;             for (int j = 0; j < 8; ++j) nv[j] = xn[64 * j]; }
;     ...
;         const float rstd = 1.0f / sqrtf(wave_sum(ss) * (1.f / DM) + EPS);
;         if (FINAL) { f32x4* orow = (f32x4*)(OUTF + (size_t)m * DM) + lane;
; #pragma unroll
;             for (int j = 0; j < 8; ++j) orow[64 * j] = v[j] * rstd * gm[j]; }
;         else { u32x2* orow = (u32x2*)(H + (size_t)m * DM) + lane;
; #pragma unroll
;             for (int j = 0; j < 8; ++j) { const f32x4 y = v[j] * rstd * gm[j] + sh[j]; u32x2 w; w.x = pk2(y.x, y.y); w.y = pk2(y.z, y.w); orow[64 * j] = w; } }
	v_add_f32_e32 v0, v0, v134
	v_mov_b32_e32 v134, v0
	s_nop 1
	v_permlane32_swap_b32_e32 v0, v134
	v_add_f32_e32 v0, v0, v134
	v_fmamk_f32 v0, v0, 0x3a000000, v218
	v_mul_f32_e32 v134, 0x4f800000, v0
	v_cmp_gt_f32_e32 vcc, s68, v0
	s_nop 1
	v_cndmask_b32_e32 v0, v0, v134, vcc
	v_sqrt_f32_e32 v134, v0
	s_nop 0
	v_add_u32_e32 v135, -1, v134
	v_fma_f32 v136, -v135, v134, v0
	v_cmp_ge_f32_e64 s[4:5], 0, v136
	v_add_u32_e32 v136, 1, v134
	s_nop 0
	v_cndmask_b32_e64 v135, v134, v135, s[4:5]
	v_fma_f32 v134, -v136, v134, v0
	v_cmp_lt_f32_e64 s[4:5], 0, v134
	s_nop 1
	v_cndmask_b32_e64 v134, v135, v136, s[4:5]
	v_mul_f32_e32 v135, 0x37800000, v134
	v_cndmask_b32_e32 v134, v134, v135, vcc
	v_cmp_class_f32_e32 vcc, v0, v219
	s_nop 1
	v_cndmask_b32_e32 v0, v134, v0, vcc
	v_div_scale_f32 v134, s[4:5], v0, v0, 1.0
	v_rcp_f32_e32 v135, v134
	s_nop 0
	v_fma_f32 v136, -v134, v135, 1.0
	v_fmac_f32_e32 v135, v136, v135
	v_div_scale_f32 v136, vcc, 1.0, v0, 1.0
	v_mul_f32_e32 v137, v136, v135
	v_fma_f32 v138, -v134, v137, v136
	v_fmac_f32_e32 v137, v138, v135
	v_fma_f32 v134, -v134, v137, v136
	v_div_fmas_f32 v134, v134, v135, v137
	v_div_fixup_f32 v0, v134, v0, 1.0
	v_pk_mul_f32 v[94:95], v[94:95], v[0:1] op_sel_hi:[1,0]
	v_pk_mul_f32 v[96:97], v[96:97], v[0:1] op_sel_hi:[1,0]
	v_pk_fma_f32 v[94:95], v[100:101], v[94:95], v[2:3]
	v_pk_fma_f32 v[96:97], v[98:99], v[96:97], v[4:5]
	v_bfe_u32 v134, v94, 16, 1
	v_add3_u32 v94, v94, v134, s33
	v_bfe_u32 v134, v95, 16, 1
	v_lshrrev_b32_e32 v94, 16, v94
	v_add3_u32 v95, v95, v134, s33
	v_and_or_b32 v94, v95, s48, v94
	v_bfe_u32 v95, v96, 16, 1
	v_add3_u32 v95, v96, v95, s33
	v_bfe_u32 v96, v97, 16, 1
	v_lshrrev_b32_e32 v95, 16, v95
	v_add3_u32 v96, v97, v96, s33
	v_pk_mul_f32 v[90:91], v[90:91], v[0:1] op_sel_hi:[1,0]
	v_and_or_b32 v95, v96, s48, v95
	v_pk_fma_f32 v[90:91], v[104:105], v[90:91], v[14:15]
	global_store_dwordx2 v[130:131], v[94:95], off
	v_bfe_u32 v94, v90, 16, 1
	v_pk_mul_f32 v[92:93], v[92:93], v[0:1] op_sel_hi:[1,0]
	v_add3_u32 v90, v90, v94, s33
	v_bfe_u32 v94, v91, 16, 1
	v_pk_fma_f32 v[92:93], v[102:103], v[92:93], v[16:17]
	v_lshrrev_b32_e32 v90, 16, v90
	v_add3_u32 v91, v91, v94, s33
	v_and_or_b32 v90, v91, s48, v90
	v_bfe_u32 v91, v92, 16, 1
	v_add3_u32 v91, v92, v91, s33
	v_bfe_u32 v92, v93, 16, 1
	v_lshrrev_b32_e32 v91, 16, v91
	v_add3_u32 v92, v93, v92, s33
	v_pk_mul_f32 v[86:87], v[86:87], v[0:1] op_sel_hi:[1,0]
	v_and_or_b32 v91, v92, s48, v91
	v_pk_fma_f32 v[86:87], v[108:109], v[86:87], v[18:19]
	global_store_dwordx2 v[130:131], v[90:91], off offset:512
	v_bfe_u32 v90, v86, 16, 1
	v_pk_mul_f32 v[88:89], v[88:89], v[0:1] op_sel_hi:[1,0]
	v_add3_u32 v86, v86, v90, s33
	v_bfe_u32 v90, v87, 16, 1
	v_pk_fma_f32 v[88:89], v[106:107], v[88:89], v[20:21]
	v_lshrrev_b32_e32 v86, 16, v86
	v_add3_u32 v87, v87, v90, s33
	v_and_or_b32 v86, v87, s48, v86
	v_bfe_u32 v87, v88, 16, 1
	v_add3_u32 v87, v88, v87, s33
	v_bfe_u32 v88, v89, 16, 1
	v_lshrrev_b32_e32 v87, 16, v87
	v_add3_u32 v88, v89, v88, s33
	v_pk_mul_f32 v[82:83], v[82:83], v[0:1] op_sel_hi:[1,0]
	v_and_or_b32 v87, v88, s48, v87
	v_pk_fma_f32 v[82:83], v[112:113], v[82:83], v[22:23]
	global_store_dwordx2 v[130:131], v[86:87], off offset:1024
	v_bfe_u32 v86, v82, 16, 1
	v_pk_mul_f32 v[84:85], v[84:85], v[0:1] op_sel_hi:[1,0]
	v_add3_u32 v82, v82, v86, s33
	v_bfe_u32 v86, v83, 16, 1
	v_pk_fma_f32 v[84:85], v[110:111], v[84:85], v[24:25]
	v_lshrrev_b32_e32 v82, 16, v82
	v_add3_u32 v83, v83, v86, s33
	v_and_or_b32 v82, v83, s48, v82
	v_bfe_u32 v83, v84, 16, 1
	v_add3_u32 v83, v84, v83, s33
	v_bfe_u32 v84, v85, 16, 1
	v_lshrrev_b32_e32 v83, 16, v83
	v_add3_u32 v84, v85, v84, s33
	v_pk_mul_f32 v[78:79], v[78:79], v[0:1] op_sel_hi:[1,0]
	v_and_or_b32 v83, v84, s48, v83
	v_pk_fma_f32 v[78:79], v[116:117], v[78:79], v[6:7]
	global_store_dwordx2 v[130:131], v[82:83], off offset:1536
	v_bfe_u32 v82, v78, 16, 1
	v_pk_mul_f32 v[80:81], v[80:81], v[0:1] op_sel_hi:[1,0]
	v_add3_u32 v78, v78, v82, s33
	v_bfe_u32 v82, v79, 16, 1
	v_pk_fma_f32 v[80:81], v[114:115], v[80:81], v[8:9]
	v_lshrrev_b32_e32 v78, 16, v78
	v_add3_u32 v79, v79, v82, s33
	v_and_or_b32 v78, v79, s48, v78
	v_bfe_u32 v79, v80, 16, 1
	v_add3_u32 v79, v80, v79, s33
	v_bfe_u32 v80, v81, 16, 1
	v_lshrrev_b32_e32 v79, 16, v79
	v_add3_u32 v80, v81, v80, s33
	v_pk_mul_f32 v[74:75], v[74:75], v[0:1] op_sel_hi:[1,0]
	v_and_or_b32 v79, v80, s48, v79
	v_pk_fma_f32 v[74:75], v[120:121], v[74:75], v[26:27]
	global_store_dwordx2 v[130:131], v[78:79], off offset:2048
	v_bfe_u32 v78, v74, 16, 1
	v_pk_mul_f32 v[76:77], v[76:77], v[0:1] op_sel_hi:[1,0]
	v_add3_u32 v74, v74, v78, s33
	v_bfe_u32 v78, v75, 16, 1
	v_pk_fma_f32 v[76:77], v[118:119], v[76:77], v[28:29]
	v_lshrrev_b32_e32 v74, 16, v74
	v_add3_u32 v75, v75, v78, s33
	v_and_or_b32 v74, v75, s48, v74
	v_bfe_u32 v75, v76, 16, 1
	v_add3_u32 v75, v76, v75, s33
	v_bfe_u32 v76, v77, 16, 1
	v_lshrrev_b32_e32 v75, 16, v75
	v_add3_u32 v76, v77, v76, s33
	v_pk_mul_f32 v[38:39], v[38:39], v[0:1] op_sel_hi:[1,0]
	v_pk_mul_f32 v[34:35], v[34:35], v[0:1] op_sel_hi:[1,0]
	v_and_or_b32 v75, v76, s48, v75
	v_pk_fma_f32 v[38:39], v[124:125], v[38:39], v[10:11]
	v_pk_fma_f32 v[34:35], v[128:129], v[34:35], v[30:31]
	global_store_dwordx2 v[130:131], v[74:75], off offset:2560
	v_pk_mul_f32 v[40:41], v[40:41], v[0:1] op_sel_hi:[1,0]
	v_bfe_u32 v74, v38, 16, 1
	v_pk_mul_f32 v[36:37], v[36:37], v[0:1] op_sel_hi:[1,0]
	v_bfe_u32 v0, v34, 16, 1
	v_add3_u32 v38, v38, v74, s33
	v_bfe_u32 v74, v39, 16, 1
	v_add3_u32 v0, v34, v0, s33
	v_bfe_u32 v34, v35, 16, 1
	v_pk_fma_f32 v[40:41], v[122:123], v[40:41], v[12:13]
	v_lshrrev_b32_e32 v38, 16, v38
	v_add3_u32 v39, v39, v74, s33
	v_pk_fma_f32 v[36:37], v[126:127], v[36:37], v[32:33]
	v_lshrrev_b32_e32 v0, 16, v0
	v_add3_u32 v34, v35, v34, s33
	v_and_or_b32 v38, v39, s48, v38
	v_bfe_u32 v39, v40, 16, 1
	v_and_or_b32 v34, v34, s48, v0
	v_bfe_u32 v0, v36, 16, 1
	v_add3_u32 v39, v40, v39, s33
	v_bfe_u32 v40, v41, 16, 1
	v_add3_u32 v0, v36, v0, s33
	v_bfe_u32 v35, v37, 16, 1
	v_lshrrev_b32_e32 v39, 16, v39
	v_add3_u32 v40, v41, v40, s33
	v_lshrrev_b32_e32 v0, 16, v0
	v_add3_u32 v35, v37, v35, s33
	v_and_or_b32 v39, v40, s48, v39
	v_and_or_b32 v35, v35, s48, v0
	global_store_dwordx2 v[130:131], v[38:39], off offset:3072
	global_store_dwordx2 v[130:131], v[34:35], off offset:3584
	s_waitcnt vmcnt(8)
	v_mov_b64_e32 v[34:35], v[42:43]
	v_mov_b64_e32 v[38:39], v[46:47]
	v_mov_b64_e32 v[76:77], v[52:53]
	v_mov_b64_e32 v[80:81], v[56:57]
	v_mov_b64_e32 v[84:85], v[60:61]
	v_mov_b64_e32 v[88:89], v[64:65]
	v_mov_b64_e32 v[92:93], v[68:69]
	v_mov_b64_e32 v[96:97], v[72:73]
	v_lshl_add_u64 v[130:131], v[130:131], 0, s[10:11]
	s_andn2_b64 vcc, exec, s[14:15]
	v_mov_b64_e32 v[36:37], v[44:45]
	v_mov_b64_e32 v[40:41], v[48:49]
	v_mov_b64_e32 v[74:75], v[50:51]
	v_mov_b64_e32 v[78:79], v[54:55]
	v_mov_b64_e32 v[82:83], v[58:59]
	v_mov_b64_e32 v[86:87], v[62:63]
	v_mov_b64_e32 v[90:91], v[66:67]
	v_mov_b64_e32 v[94:95], v[70:71]
	s_cbranch_vccz .LBB0_977

; #define PG8_STAGE(bufoff, gbase, voff) do { _Pragma("unroll") for (int _i = 0; _i < 2; ++_i) \
;         __builtin_amdgcn_global_load_lds((const unsigned*)((const char*)(gbase) + (voff)[_i]), (LAS unsigned*)(lds + (bufoff) + ldsw + _i * 8192), 16, 0, 0); } while (0)
; #define PG8_WAIT_V(n) asm volatile("s_waitcnt vmcnt(" #n ")" ::: "memory")
; #define PG8_BAR __builtin_amdgcn_s_barrier()
; #define PH unsigned char* ws = a.ws; asm volatile("" : "+s"(ws)); int lq = l; asm volatile("" : "+s"(lq)); (void)lq;
; template <class Epi>
; __device__ __forceinline__ void gemm_phase(LAS unsigned char* lds, const Gemm g, const StaticOrder& S, const Epi& E, int wave_s) {
;     ...
;     const char* cA = (const char*)g.A + (size_t)cur.pm * tstepA; const char* cB = (const char*)g.Bt + (size_t)cur.pn * tstepB;
;     PG8_STAGE(PG8_SB(0, 0), cB, voffB); PG8_STAGE(PG8_SB(0, 1), cB + hstepB, voffB); PG8_STAGE(PG8_SA(0, 0), cA, voffA); PG8_STAGE(PG8_SA(0, 1), cA + hstepA, voffA);
;     if (wr == 1) PG8_BAR;
;     PG8_WAIT_V(2); PG8_BAR;
;     PG8_STAGE(PG8_SB(1, 0), cB + kstep, voffB); PG8_STAGE(PG8_SA(1, 0), cA + kstep, voffA); PG8_STAGE(PG8_SB(1, 1), cB + hstepB + kstep, voffB);
;     PG8_WAIT_V(6); PG8_BAR;
; __global__ void __launch_bounds__(NTHR, 2) mega_fwd(Args a) {
;     ...
;         { PH pg8::Gemm g{H, WFF1 + (size_t)lq * DFF * DM, SEQ, DFF, DM, DM}; pg8::StaticOrder S; S.init(SEQ, DFF, G, bx);
;           pg8::EpiBf16<1> E{HID, DFF, nullptr, nullptr}; pg8::gemm_phase(ldsl, g, S, E, wave_s); }
.LBB0_1024:
	s_add_u32 s8, s4, 0x12000000
	s_addc_u32 s9, s5, 0
	v_and_b32_e32 v17, 48, v16
	v_lshlrev_b32_e32 v18, 6, v16
	s_movk_i32 s5, 0x3c0
	v_lshlrev_b32_e32 v16, 2, v16
	s_lshl_b32 s4, s12, 13
	v_and_or_b32 v17, v18, s5, v17
	v_and_b32_e32 v16, 32, v16
	v_bitop3_b32 v18, v17, s4, v16 bitop3:0xde
	s_lshl_b32 s4, s11, 5
	s_and_b32 s39, s4, 0x60
	s_add_i32 m0, s31, 0x18000
	v_lshl_add_u64 v[8:9], v[8:9], 0, s[42:43]
	s_lshl_b32 s38, s12, 6
	s_lshl_b32 s4, s39, 7
	s_waitcnt vmcnt(2)
	s_barrier
	global_load_lds_dwordx4 v[8:9], off
	v_lshl_add_u64 v[6:7], v[6:7], 0, s[42:43]
	s_add_i32 m0, s31, 0x1a000
	s_add_i32 s40, s31, 0x8000
	s_add_i32 s41, s31, 0xa000
	v_bitop3_b32 v142, s4, v17, v16 bitop3:0xf6
	global_load_lds_dwordx4 v[6:7], off
	v_lshl_add_u64 v[2:3], v[2:3], 0, s[42:43]
	s_mov_b32 m0, s40
	s_add_u32 s4, s20, 0x80080
	global_load_lds_dwordx4 v[2:3], off
	v_lshl_add_u64 v[2:3], v[4:5], 0, s[42:43]
	s_mov_b32 m0, s41
	s_addc_u32 s5, s21, 0
	global_load_lds_dwordx4 v[2:3], off
	s_add_i32 m0, s31, 0x1c000
	s_nop 0
	global_load_lds_dwordx4 v0, s[4:5]
	v_lshl_add_u64 v[2:3], s[4:5], 0, v[130:131]
	s_add_i32 m0, s31, 0x1e000
	s_cmpk_lt_u32 s10, 0x100
	global_load_lds_dwordx4 v[2:3], off
	v_lshlrev_b32_e32 v2, 15, v10
	v_and_b32_e32 v2, 0xffff0000, v2
	v_lshl_add_u32 v2, v11, 12, v2
	v_and_b32_e32 v3, 1, v10
	v_lshl_or_b32 v2, v3, 6, v2
	v_lshl_add_u32 v136, v12, 1, v2
	v_lshlrev_b32_e32 v2, 15, v14
	v_and_b32_e32 v2, 0xffff0000, v2
	s_waitcnt vmcnt(6)
	v_lshl_add_u32 v2, v13, 12, v2
	v_and_b32_e32 v3, 1, v14
	v_lshl_or_b32 v2, v3, 6, v2
	v_readlane_b32 s4, v255, 9
	s_cselect_b64 s[10:11], -1, 0
	v_mov_b32_e32 v137, v1
	v_lshl_add_u32 v138, v15, 1, v2
	v_mov_b32_e32 v139, v1
	s_mov_b32 s56, 0
	v_add_u32_e32 v143, 0, v18
	v_readlane_b32 s57, v255, 8
	s_mov_b32 s64, s4
	s_barrier
	v_readlane_b32 s5, v255, 10
	s_branch .LBB0_1027

; #define PG8_STAGE(bufoff, gbase, voff) do { _Pragma("unroll") for (int _i = 0; _i < 2; ++_i) \
;         __builtin_amdgcn_global_load_lds((const unsigned*)((const char*)(gbase) + (voff)[_i]), (LAS unsigned*)(lds + (bufoff) + ldsw + _i * 8192), 16, 0, 0); } while (0)
; #define PG8_LDA(dst, b, h) do { _Pragma("unroll") for (int m = 0; m < 4; ++m) _Pragma("unroll") for (int k = 0; k < 2; ++k) dst[m][k] = *(const LAS bf16x8*)(lds + PG8_SA(b, h) + aoff + m * 2048 + k * 1024); } while (0)
; #define PG8_LDB(dst, b, h) do { _Pragma("unroll") for (int n = 0; n < 2; ++n) _Pragma("unroll") for (int k = 0; k < 2; ++k) dst[n][k] = *(const LAS bf16x8*)(lds + PG8_SB(b, h) + boff + n * 2048 + k * 1024); } while (0)
; #define PG8_MMA(ai, bj, At, Bt) do { __builtin_amdgcn_s_setprio(1); _Pragma("unroll") for (int m = 0; m < 4; ++m) _Pragma("unroll") for (int n = 0; n < 2; ++n) _Pragma("unroll") for (int k = 0; k < 2; ++k) \
;         acc[ai][bj][m][n] = __builtin_amdgcn_mfma_f32_16x16x32_bf16(Bt[n][k], At[m][k], acc[ai][bj][m][n], 0, 0, 0); __builtin_amdgcn_s_setprio(0); } while (0)
; #define PG8_WAIT_V(n) asm volatile("s_waitcnt vmcnt(" #n ")" ::: "memory")
; #define PG8_BAR __builtin_amdgcn_s_barrier()
; template <class Epi>
; __device__ __forceinline__ void gemm_phase(LAS unsigned char* lds, const Gemm g, const StaticOrder& S, const Epi& E, int wave_s) {
;     ...
;         const char* nA = has_next ? (const char*)g.A + (size_t)nxt.pm * tstepA : cA; const char* nB = has_next ? (const char*)g.Bt + (size_t)nxt.pn * tstepB : cB;
;         for (int t = 0; t < nt; t += 2) {
;             const bool last = (t == nt - 2);
;             const char* a1 = cA + (size_t)(t + 1) * kstep;
;             const char* a2 = last ? nA : cA + (size_t)(t + 2) * kstep; const char* b2 = last ? nB : cB + (size_t)(t + 2) * kstep;
;             const char* a3 = a2 + kstep; const char* b3 = b2 + kstep;
;             PG8_LDB(B0, 0, 0); PG8_LDB(B1, 0, 1); PG8_SCHED; PG8_LDA(At, 0, 0); PG8_STAGE(PG8_SA(1, 1), a1 + hstepA, voffA);
;             PG8_WAIT_V(8); PG8_WAIT_L(0); PG8_BAR; PG8_MMA(0, 0, At, B0); PG8_MMA(0, 1, At, B1); PG8_BAR; PG8_SCHED;
;             PG8_LDA(At, 0, 1); PG8_STAGE(PG8_SB(0, 0), b2, voffB); PG8_STAGE(PG8_SB(0, 1), b2 + hstepB, voffB); PG8_STAGE(PG8_SA(0, 0), a2, voffA);
;             PG8_WAIT_V(8); PG8_WAIT_L(0); PG8_BAR; PG8_MMA(1, 0, At, B0); PG8_MMA(1, 1, At, B1); PG8_BAR; PG8_SCHED;
.LBB0_1034:
	s_add_u32 s22, s20, 0xfff80080
	s_addc_u32 s23, s21, -1
	s_add_i32 s72, 0, 0x10000
	s_cmp_eq_u32 s71, 28
	s_cselect_b32 s25, s15, s23
	s_cselect_b32 s24, s65, s22
	v_add_u32_e32 v140, s72, v142
	s_cselect_b32 s23, s13, s70
	s_cselect_b32 s22, s66, s67
	s_add_i32 s78, 0, 0x14000
	ds_read_b128 v[144:147], v140
	ds_read_b128 v[148:151], v140 offset:1024
	ds_read_b128 v[152:155], v140 offset:2048
	ds_read_b128 v[156:159], v140 offset:3072
	v_add_u32_e32 v140, s78, v142
	ds_read_b128 v[160:163], v140
	ds_read_b128 v[164:167], v140 offset:1024
	ds_read_b128 v[168:171], v140 offset:2048
	ds_read_b128 v[172:175], v140 offset:3072
	s_add_i32 m0, s31, 0xc000
	ds_read_b128 v[176:179], v143
	ds_read_b128 v[180:183], v143 offset:1024
	ds_read_b128 v[184:187], v143 offset:2048
	ds_read_b128 v[188:191], v143 offset:3072
	ds_read_b128 v[192:195], v143 offset:4096
	ds_read_b128 v[196:199], v143 offset:5120
	ds_read_b128 v[200:203], v143 offset:6144
	ds_read_b128 v[208:211], v143 offset:7168
	global_load_lds_dwordx4 v138, s[20:21]
	s_add_i32 m0, s31, 0xe000
	s_nop 0
	global_load_lds_dwordx4 v136, s[20:21]
	s_waitcnt vmcnt(8)
	s_waitcnt lgkmcnt(0)
	s_barrier
	s_setprio 1
	s_waitcnt lgkmcnt(0)
	v_mfma_f32_16x16x32_bf16 v[126:129], v[144:147], v[176:179], v[126:129]
	v_mfma_f32_16x16x32_bf16 v[122:125], v[152:155], v[176:179], v[122:125]
	v_mfma_f32_16x16x32_bf16 v[110:113], v[144:147], v[184:187], v[110:113]
	v_mfma_f32_16x16x32_bf16 v[106:109], v[152:155], v[184:187], v[106:109]
	v_mfma_f32_16x16x32_bf16 v[94:97], v[144:147], v[192:195], v[94:97]
	v_mfma_f32_16x16x32_bf16 v[90:93], v[152:155], v[192:195], v[90:93]
	v_mfma_f32_16x16x32_bf16 v[78:81], v[144:147], v[200:203], v[78:81]
	v_mfma_f32_16x16x32_bf16 v[74:77], v[152:155], v[200:203], v[74:77]
	v_mfma_f32_16x16x32_bf16 v[126:129], v[148:151], v[180:183], v[126:129]
	v_mfma_f32_16x16x32_bf16 v[122:125], v[156:159], v[180:183], v[122:125]
	v_mfma_f32_16x16x32_bf16 v[110:113], v[148:151], v[188:191], v[110:113]
	v_mfma_f32_16x16x32_bf16 v[106:109], v[156:159], v[188:191], v[106:109]
	v_mfma_f32_16x16x32_bf16 v[94:97], v[148:151], v[196:199], v[94:97]
	v_mfma_f32_16x16x32_bf16 v[90:93], v[156:159], v[196:199], v[90:93]
	v_mfma_f32_16x16x32_bf16 v[78:81], v[148:151], v[208:211], v[78:81]
	v_mfma_f32_16x16x32_bf16 v[74:77], v[156:159], v[208:211], v[74:77]
	s_setprio 0
	s_setprio 1
	v_mfma_f32_16x16x32_bf16 v[118:121], v[160:163], v[176:179], v[118:121]
	v_mfma_f32_16x16x32_bf16 v[114:117], v[168:171], v[176:179], v[114:117]
	v_mfma_f32_16x16x32_bf16 v[102:105], v[160:163], v[184:187], v[102:105]
	v_mfma_f32_16x16x32_bf16 v[98:101], v[168:171], v[184:187], v[98:101]
	v_mfma_f32_16x16x32_bf16 v[86:89], v[160:163], v[192:195], v[86:89]
	v_mfma_f32_16x16x32_bf16 v[82:85], v[168:171], v[192:195], v[82:85]
	v_mfma_f32_16x16x32_bf16 v[70:73], v[160:163], v[200:203], v[70:73]
	v_mfma_f32_16x16x32_bf16 v[66:69], v[168:171], v[200:203], v[66:69]
	v_mfma_f32_16x16x32_bf16 v[118:121], v[164:167], v[180:183], v[118:121]
	v_mfma_f32_16x16x32_bf16 v[114:117], v[172:175], v[180:183], v[114:117]
	v_mfma_f32_16x16x32_bf16 v[102:105], v[164:167], v[188:191], v[102:105]
	v_mfma_f32_16x16x32_bf16 v[98:101], v[172:175], v[188:191], v[98:101]
	v_mfma_f32_16x16x32_bf16 v[86:89], v[164:167], v[196:199], v[86:89]
	v_mfma_f32_16x16x32_bf16 v[82:85], v[172:175], v[196:199], v[82:85]
	v_mfma_f32_16x16x32_bf16 v[70:73], v[164:167], v[208:211], v[70:73]
	v_mfma_f32_16x16x32_bf16 v[66:69], v[172:175], v[208:211], v[66:69]
	s_setprio 0
	s_barrier
	s_add_i32 s72, s72, s30
	v_lshl_add_u64 v[140:141], s[22:23], 0, v[0:1]
	s_mov_b32 m0, s72
	ds_read_b128 v[176:179], v143 offset:16384
	ds_read_b128 v[180:183], v143 offset:17408
	ds_read_b128 v[184:187], v143 offset:18432
	ds_read_b128 v[188:191], v143 offset:19456
	ds_read_b128 v[192:195], v143 offset:20480
	ds_read_b128 v[196:199], v143 offset:21504
	ds_read_b128 v[200:203], v143 offset:22528
	ds_read_b128 v[208:211], v143 offset:23552
	global_load_lds_dwordx4 v[140:141], off
	s_add_i32 m0, s72, 0x2000
	s_add_u32 s72, s22, 0x80000
	v_lshl_add_u64 v[204:205], s[22:23], 0, v[130:131]
	s_addc_u32 s73, s23, 0
	s_add_i32 s78, s78, s30
	global_load_lds_dwordx4 v[204:205], off
	s_mov_b32 m0, s78
	v_lshl_add_u64 v[212:213], s[24:25], 0, v[132:133]
	global_load_lds_dwordx4 v0, s[72:73]
	s_add_i32 m0, s78, 0x2000
	s_nop 0
	global_load_lds_dwordx4 v130, s[72:73]
	v_lshl_add_u64 v[206:207], s[24:25], 0, v[134:135]
	s_mov_b32 m0, s31
	s_nop 0
	global_load_lds_dwordx4 v[206:207], off
	s_mov_b32 m0, s34
	s_nop 0
	global_load_lds_dwordx4 v[212:213], off
	s_waitcnt vmcnt(8)
	s_waitcnt lgkmcnt(0)
	s_barrier
; #define PG8_STAGE(bufoff, gbase, voff) do { _Pragma("unroll") for (int _i = 0; _i < 2; ++_i) \
;         __builtin_amdgcn_global_load_lds((const unsigned*)((const char*)(gbase) + (voff)[_i]), (LAS unsigned*)(lds + (bufoff) + ldsw + _i * 8192), 16, 0, 0); } while (0)
; #define PG8_LDA(dst, b, h) do { _Pragma("unroll") for (int m = 0; m < 4; ++m) _Pragma("unroll") for (int k = 0; k < 2; ++k) dst[m][k] = *(const LAS bf16x8*)(lds + PG8_SA(b, h) + aoff + m * 2048 + k * 1024); } while (0)
; #define PG8_LDB(dst, b, h) do { _Pragma("unroll") for (int n = 0; n < 2; ++n) _Pragma("unroll") for (int k = 0; k < 2; ++k) dst[n][k] = *(const LAS bf16x8*)(lds + PG8_SB(b, h) + boff + n * 2048 + k * 1024); } while (0)
; #define PG8_MMA(ai, bj, At, Bt) do { __builtin_amdgcn_s_setprio(1); _Pragma("unroll") for (int m = 0; m < 4; ++m) _Pragma("unroll") for (int n = 0; n < 2; ++n) _Pragma("unroll") for (int k = 0; k < 2; ++k) \
;         acc[ai][bj][m][n] = __builtin_amdgcn_mfma_f32_16x16x32_bf16(Bt[n][k], At[m][k], acc[ai][bj][m][n], 0, 0, 0); __builtin_amdgcn_s_setprio(0); } while (0)
; #define PG8_WAIT_V(n) asm volatile("s_waitcnt vmcnt(" #n ")" ::: "memory")
; #define PG8_WAIT_L(n) asm volatile("s_waitcnt lgkmcnt(" #n ")" ::: "memory")
; #define PG8_BAR __builtin_amdgcn_s_barrier()
; #define PG8_SCHED __builtin_amdgcn_sched_barrier(0)
; template <class Epi>
; __device__ __forceinline__ void gemm_phase(LAS unsigned char* lds, const Gemm g, const StaticOrder& S, const Epi& E, int wave_s) {
;     ...
;             PG8_WAIT_V(8); PG8_WAIT_L(0); PG8_BAR; PG8_MMA(1, 0, At, B0); PG8_MMA(1, 1, At, B1); PG8_BAR; PG8_SCHED;
;             PG8_LDB(B0, 1, 0); PG8_LDB(B1, 1, 1); PG8_SCHED; PG8_LDA(At, 1, 0); PG8_STAGE(PG8_SA(0, 1), a2 + hstepA, voffA);
;             PG8_WAIT_V(8); PG8_WAIT_L(0); PG8_BAR; PG8_MMA(0, 0, At, B0); PG8_MMA(0, 1, At, B1); PG8_BAR; PG8_SCHED;
	s_setprio 1
	s_waitcnt lgkmcnt(0)
	v_mfma_f32_16x16x32_bf16 v[62:65], v[144:147], v[176:179], v[62:65]
	v_mfma_f32_16x16x32_bf16 v[58:61], v[152:155], v[176:179], v[58:61]
	v_mfma_f32_16x16x32_bf16 v[46:49], v[144:147], v[184:187], v[46:49]
	v_mfma_f32_16x16x32_bf16 v[42:45], v[152:155], v[184:187], v[42:45]
	v_mfma_f32_16x16x32_bf16 v[30:33], v[144:147], v[192:195], v[30:33]
	v_mfma_f32_16x16x32_bf16 v[26:29], v[152:155], v[192:195], v[26:29]
	v_mfma_f32_16x16x32_bf16 v[14:17], v[144:147], v[200:203], v[14:17]
	v_mfma_f32_16x16x32_bf16 v[10:13], v[152:155], v[200:203], v[10:13]
	v_mfma_f32_16x16x32_bf16 v[62:65], v[148:151], v[180:183], v[62:65]
	v_mfma_f32_16x16x32_bf16 v[58:61], v[156:159], v[180:183], v[58:61]
	v_mfma_f32_16x16x32_bf16 v[46:49], v[148:151], v[188:191], v[46:49]
	v_mfma_f32_16x16x32_bf16 v[42:45], v[156:159], v[188:191], v[42:45]
	v_mfma_f32_16x16x32_bf16 v[30:33], v[148:151], v[196:199], v[30:33]
	v_mfma_f32_16x16x32_bf16 v[26:29], v[156:159], v[196:199], v[26:29]
	v_mfma_f32_16x16x32_bf16 v[14:17], v[148:151], v[208:211], v[14:17]
	v_mfma_f32_16x16x32_bf16 v[10:13], v[156:159], v[208:211], v[10:13]
	s_setprio 0
	s_setprio 1
	v_mfma_f32_16x16x32_bf16 v[54:57], v[160:163], v[176:179], v[54:57]
	v_mfma_f32_16x16x32_bf16 v[50:53], v[168:171], v[176:179], v[50:53]
	v_mfma_f32_16x16x32_bf16 v[38:41], v[160:163], v[184:187], v[38:41]
	v_mfma_f32_16x16x32_bf16 v[34:37], v[168:171], v[184:187], v[34:37]
	v_mfma_f32_16x16x32_bf16 v[22:25], v[160:163], v[192:195], v[22:25]
	v_mfma_f32_16x16x32_bf16 v[18:21], v[168:171], v[192:195], v[18:21]
	v_mfma_f32_16x16x32_bf16 v[6:9], v[160:163], v[200:203], v[6:9]
	v_mfma_f32_16x16x32_bf16 v[2:5], v[168:171], v[200:203], v[2:5]
	v_mfma_f32_16x16x32_bf16 v[54:57], v[164:167], v[180:183], v[54:57]
	v_mfma_f32_16x16x32_bf16 v[50:53], v[172:175], v[180:183], v[50:53]
	v_mfma_f32_16x16x32_bf16 v[38:41], v[164:167], v[188:191], v[38:41]
	v_mfma_f32_16x16x32_bf16 v[34:37], v[172:175], v[188:191], v[34:37]
	v_mfma_f32_16x16x32_bf16 v[22:25], v[164:167], v[196:199], v[22:25]
	v_mfma_f32_16x16x32_bf16 v[18:21], v[172:175], v[196:199], v[18:21]
	v_mfma_f32_16x16x32_bf16 v[6:9], v[164:167], v[208:211], v[6:9]
	v_mfma_f32_16x16x32_bf16 v[2:5], v[172:175], v[208:211], v[2:5]
	s_setprio 0
	s_barrier
	s_add_i32 s72, 0, 0x18000
	s_add_i32 s73, 0, 0x1c000
	v_add_u32_e32 v156, s72, v142
	v_add_u32_e32 v172, s73, v142
	ds_read_b128 v[144:147], v156
	ds_read_b128 v[148:151], v156 offset:1024
	ds_read_b128 v[152:155], v156 offset:2048
	ds_read_b128 v[156:159], v156 offset:3072
	ds_read_b128 v[160:163], v172
	ds_read_b128 v[164:167], v172 offset:1024
	ds_read_b128 v[168:171], v172 offset:2048
	ds_read_b128 v[172:175], v172 offset:3072
	s_add_u32 s24, s24, 0x80000
	s_addc_u32 s25, s25, 0
	s_mov_b32 m0, s35
	ds_read_b128 v[176:179], v143 offset:32768
	ds_read_b128 v[180:183], v143 offset:33792
	ds_read_b128 v[184:187], v143 offset:34816
	ds_read_b128 v[188:191], v143 offset:35840
	ds_read_b128 v[192:195], v143 offset:36864
	ds_read_b128 v[196:199], v143 offset:37888
	ds_read_b128 v[200:203], v143 offset:38912
	ds_read_b128 v[208:211], v143 offset:39936
	global_load_lds_dwordx4 v134, s[24:25]
	v_lshl_add_u64 v[214:215], s[24:25], 0, v[132:133]
	s_mov_b32 m0, s37
	s_nop 0
	global_load_lds_dwordx4 v[214:215], off
	s_waitcnt vmcnt(8)
	s_waitcnt lgkmcnt(0)
	s_barrier
	s_setprio 1
	s_waitcnt lgkmcnt(0)
	v_mfma_f32_16x16x32_bf16 v[126:129], v[144:147], v[176:179], v[126:129]
	v_mfma_f32_16x16x32_bf16 v[122:125], v[152:155], v[176:179], v[122:125]
	v_mfma_f32_16x16x32_bf16 v[110:113], v[144:147], v[184:187], v[110:113]
	v_mfma_f32_16x16x32_bf16 v[106:109], v[152:155], v[184:187], v[106:109]
	v_mfma_f32_16x16x32_bf16 v[94:97], v[144:147], v[192:195], v[94:97]
	v_mfma_f32_16x16x32_bf16 v[90:93], v[152:155], v[192:195], v[90:93]
	v_mfma_f32_16x16x32_bf16 v[78:81], v[144:147], v[200:203], v[78:81]
	v_mfma_f32_16x16x32_bf16 v[74:77], v[152:155], v[200:203], v[74:77]
	v_mfma_f32_16x16x32_bf16 v[126:129], v[148:151], v[180:183], v[126:129]
	v_mfma_f32_16x16x32_bf16 v[122:125], v[156:159], v[180:183], v[122:125]
	v_mfma_f32_16x16x32_bf16 v[110:113], v[148:151], v[188:191], v[110:113]
	v_mfma_f32_16x16x32_bf16 v[106:109], v[156:159], v[188:191], v[106:109]
	v_mfma_f32_16x16x32_bf16 v[94:97], v[148:151], v[196:199], v[94:97]
	v_mfma_f32_16x16x32_bf16 v[90:93], v[156:159], v[196:199], v[90:93]
	v_mfma_f32_16x16x32_bf16 v[78:81], v[148:151], v[208:211], v[78:81]
	v_mfma_f32_16x16x32_bf16 v[74:77], v[156:159], v[208:211], v[74:77]
	s_setprio 0
	s_setprio 1
	v_mfma_f32_16x16x32_bf16 v[118:121], v[160:163], v[176:179], v[118:121]
	v_mfma_f32_16x16x32_bf16 v[114:117], v[168:171], v[176:179], v[114:117]
	v_mfma_f32_16x16x32_bf16 v[102:105], v[160:163], v[184:187], v[102:105]
	v_mfma_f32_16x16x32_bf16 v[98:101], v[168:171], v[184:187], v[98:101]
	v_mfma_f32_16x16x32_bf16 v[86:89], v[160:163], v[192:195], v[86:89]
	v_mfma_f32_16x16x32_bf16 v[82:85], v[168:171], v[192:195], v[82:85]
	v_mfma_f32_16x16x32_bf16 v[70:73], v[160:163], v[200:203], v[70:73]
	v_mfma_f32_16x16x32_bf16 v[66:69], v[168:171], v[200:203], v[66:69]
	v_mfma_f32_16x16x32_bf16 v[118:121], v[164:167], v[180:183], v[118:121]
	v_mfma_f32_16x16x32_bf16 v[114:117], v[172:175], v[180:183], v[114:117]
	v_mfma_f32_16x16x32_bf16 v[102:105], v[164:167], v[188:191], v[102:105]
	v_mfma_f32_16x16x32_bf16 v[98:101], v[172:175], v[188:191], v[98:101]
	v_mfma_f32_16x16x32_bf16 v[86:89], v[164:167], v[196:199], v[86:89]
	v_mfma_f32_16x16x32_bf16 v[82:85], v[172:175], v[196:199], v[82:85]
	v_mfma_f32_16x16x32_bf16 v[70:73], v[164:167], v[208:211], v[70:73]
	v_mfma_f32_16x16x32_bf16 v[66:69], v[172:175], v[208:211], v[66:69]
	s_setprio 0
	s_barrier
; #define PG8_STAGE(bufoff, gbase, voff) do { _Pragma("unroll") for (int _i = 0; _i < 2; ++_i) \
;         __builtin_amdgcn_global_load_lds((const unsigned*)((const char*)(gbase) + (voff)[_i]), (LAS unsigned*)(lds + (bufoff) + ldsw + _i * 8192), 16, 0, 0); } while (0)
; #define PG8_LDA(dst, b, h) do { _Pragma("unroll") for (int m = 0; m < 4; ++m) _Pragma("unroll") for (int k = 0; k < 2; ++k) dst[m][k] = *(const LAS bf16x8*)(lds + PG8_SA(b, h) + aoff + m * 2048 + k * 1024); } while (0)
; #define PG8_MMA(ai, bj, At, Bt) do { __builtin_amdgcn_s_setprio(1); _Pragma("unroll") for (int m = 0; m < 4; ++m) _Pragma("unroll") for (int n = 0; n < 2; ++n) _Pragma("unroll") for (int k = 0; k < 2; ++k) \
;         acc[ai][bj][m][n] = __builtin_amdgcn_mfma_f32_16x16x32_bf16(Bt[n][k], At[m][k], acc[ai][bj][m][n], 0, 0, 0); __builtin_amdgcn_s_setprio(0); } while (0)
; #define PG8_WAIT_V(n) asm volatile("s_waitcnt vmcnt(" #n ")" ::: "memory")
; #define PG8_WAIT_L(n) asm volatile("s_waitcnt lgkmcnt(" #n ")" ::: "memory")
; #define PG8_BAR __builtin_amdgcn_s_barrier()
; #define PG8_SCHED __builtin_amdgcn_sched_barrier(0)
; template <class Epi>
; __device__ __forceinline__ void gemm_phase(LAS unsigned char* lds, const Gemm g, const StaticOrder& S, const Epi& E, int wave_s) {
;     ...
;             PG8_LDA(At, 1, 1); PG8_STAGE(PG8_SB(1, 0), b3, voffB); PG8_STAGE(PG8_SB(1, 1), b3 + hstepB, voffB); PG8_STAGE(PG8_SA(1, 0), a3, voffA);
;             PG8_WAIT_V(8); PG8_WAIT_L(0); PG8_BAR; PG8_MMA(1, 0, At, B0); PG8_MMA(1, 1, At, B1); PG8_BAR; PG8_SCHED;
;         }
;         if (wr == 0) PG8_BAR;
	s_add_i32 s24, s72, s30
	v_lshl_add_u64 v[140:141], v[140:141], 0, s[42:43]
	s_mov_b32 m0, s24
	ds_read_b128 v[176:179], v143 offset:49152
	ds_read_b128 v[180:183], v143 offset:50176
	ds_read_b128 v[184:187], v143 offset:51200
	ds_read_b128 v[188:191], v143 offset:52224
	ds_read_b128 v[192:195], v143 offset:53248
	ds_read_b128 v[196:199], v143 offset:54272
	ds_read_b128 v[200:203], v143 offset:55296
	ds_read_b128 v[208:211], v143 offset:56320
	global_load_lds_dwordx4 v[140:141], off
	s_add_i32 m0, s24, 0x2000
	s_add_u32 s22, s22, 0x80080
	v_lshl_add_u64 v[140:141], v[204:205], 0, s[42:43]
	s_addc_u32 s23, s23, 0
	s_add_i32 s24, s73, s30
	global_load_lds_dwordx4 v[140:141], off
	s_mov_b32 m0, s24
	s_nop 0
	global_load_lds_dwordx4 v0, s[22:23]
	s_add_i32 m0, s24, 0x2000
	s_nop 0
	global_load_lds_dwordx4 v130, s[22:23]
	v_lshl_add_u64 v[140:141], v[206:207], 0, s[42:43]
	s_mov_b32 m0, s40
	s_nop 0
	global_load_lds_dwordx4 v[140:141], off
	v_lshl_add_u64 v[140:141], v[212:213], 0, s[42:43]
	s_mov_b32 m0, s41
	s_nop 0
	global_load_lds_dwordx4 v[140:141], off
	s_waitcnt vmcnt(8)
	s_waitcnt lgkmcnt(0)
	s_barrier
	s_setprio 1
	s_waitcnt lgkmcnt(0)
	v_mfma_f32_16x16x32_bf16 v[62:65], v[144:147], v[176:179], v[62:65]
	v_mfma_f32_16x16x32_bf16 v[58:61], v[152:155], v[176:179], v[58:61]
	v_mfma_f32_16x16x32_bf16 v[46:49], v[144:147], v[184:187], v[46:49]
	v_mfma_f32_16x16x32_bf16 v[42:45], v[152:155], v[184:187], v[42:45]
	v_mfma_f32_16x16x32_bf16 v[30:33], v[144:147], v[192:195], v[30:33]
	v_mfma_f32_16x16x32_bf16 v[26:29], v[152:155], v[192:195], v[26:29]
	v_mfma_f32_16x16x32_bf16 v[14:17], v[144:147], v[200:203], v[14:17]
	v_mfma_f32_16x16x32_bf16 v[10:13], v[152:155], v[200:203], v[10:13]
	v_mfma_f32_16x16x32_bf16 v[62:65], v[148:151], v[180:183], v[62:65]
	v_mfma_f32_16x16x32_bf16 v[58:61], v[156:159], v[180:183], v[58:61]
	v_mfma_f32_16x16x32_bf16 v[46:49], v[148:151], v[188:191], v[46:49]
	v_mfma_f32_16x16x32_bf16 v[42:45], v[156:159], v[188:191], v[42:45]
	v_mfma_f32_16x16x32_bf16 v[30:33], v[148:151], v[196:199], v[30:33]
	v_mfma_f32_16x16x32_bf16 v[26:29], v[156:159], v[196:199], v[26:29]
	v_mfma_f32_16x16x32_bf16 v[14:17], v[148:151], v[208:211], v[14:17]
	v_mfma_f32_16x16x32_bf16 v[10:13], v[156:159], v[208:211], v[10:13]
	s_setprio 0
	s_setprio 1
	v_mfma_f32_16x16x32_bf16 v[54:57], v[160:163], v[176:179], v[54:57]
	v_mfma_f32_16x16x32_bf16 v[50:53], v[168:171], v[176:179], v[50:53]
	v_mfma_f32_16x16x32_bf16 v[38:41], v[160:163], v[184:187], v[38:41]
	v_mfma_f32_16x16x32_bf16 v[34:37], v[168:171], v[184:187], v[34:37]
	v_mfma_f32_16x16x32_bf16 v[22:25], v[160:163], v[192:195], v[22:25]
	v_mfma_f32_16x16x32_bf16 v[18:21], v[168:171], v[192:195], v[18:21]
	v_mfma_f32_16x16x32_bf16 v[6:9], v[160:163], v[200:203], v[6:9]
	v_mfma_f32_16x16x32_bf16 v[2:5], v[168:171], v[200:203], v[2:5]
	v_mfma_f32_16x16x32_bf16 v[54:57], v[164:167], v[180:183], v[54:57]
	v_mfma_f32_16x16x32_bf16 v[50:53], v[172:175], v[180:183], v[50:53]
	v_mfma_f32_16x16x32_bf16 v[38:41], v[164:167], v[188:191], v[38:41]
	v_mfma_f32_16x16x32_bf16 v[34:37], v[172:175], v[188:191], v[34:37]
	v_mfma_f32_16x16x32_bf16 v[22:25], v[164:167], v[196:199], v[22:25]
	v_mfma_f32_16x16x32_bf16 v[18:21], v[172:175], v[196:199], v[18:21]
	v_mfma_f32_16x16x32_bf16 v[6:9], v[164:167], v[208:211], v[6:9]
	v_mfma_f32_16x16x32_bf16 v[2:5], v[172:175], v[208:211], v[2:5]
	s_setprio 0
	s_barrier
	s_add_i32 s71, s71, 2
	s_add_u32 s67, s67, 0x100
	s_addc_u32 s70, s70, 0
	s_add_u32 s20, s20, 0x100
	s_addc_u32 s21, s21, 0
	s_cmp_gt_u32 s71, 29
	s_cbranch_scc0 .LBB0_1034
	s_and_b64 vcc, exec, s[10:11]
	s_cbranch_vccz .LBB0_1037
	s_barrier

; #define PG8_STAGE(bufoff, gbase, voff) do { _Pragma("unroll") for (int _i = 0; _i < 2; ++_i) \
;         __builtin_amdgcn_global_load_lds((const unsigned*)((const char*)(gbase) + (voff)[_i]), (LAS unsigned*)(lds + (bufoff) + ldsw + _i * 8192), 16, 0, 0); } while (0)
; #define PG8_WAIT_V(n) asm volatile("s_waitcnt vmcnt(" #n ")" ::: "memory")
; #define PG8_BAR __builtin_amdgcn_s_barrier()
; #define PH unsigned char* ws = a.ws; asm volatile("" : "+s"(ws)); int lq = l; asm volatile("" : "+s"(lq)); (void)lq;
; template <class Epi>
; __device__ __forceinline__ void gemm_phase(LAS unsigned char* lds, const Gemm g, const StaticOrder& S, const Epi& E, int wave_s) {
;     ...
;     const char* cA = (const char*)g.A + (size_t)cur.pm * tstepA; const char* cB = (const char*)g.Bt + (size_t)cur.pn * tstepB;
;     PG8_STAGE(PG8_SB(0, 0), cB, voffB); PG8_STAGE(PG8_SB(0, 1), cB + hstepB, voffB); PG8_STAGE(PG8_SA(0, 0), cA, voffA); PG8_STAGE(PG8_SA(0, 1), cA + hstepA, voffA);
;     if (wr == 1) PG8_BAR;
;     PG8_WAIT_V(2); PG8_BAR;
;     PG8_STAGE(PG8_SB(1, 0), cB + kstep, voffB); PG8_STAGE(PG8_SA(1, 0), cA + kstep, voffA); PG8_STAGE(PG8_SB(1, 1), cB + hstepB + kstep, voffB);
;     PG8_WAIT_V(6); PG8_BAR;
; __global__ void __launch_bounds__(NTHR, 2) mega_fwd(Args a) {
;     ...
;         { PH pg8::Gemm g{HID, WFF2 + (size_t)lq * DM * DFF, SEQ, DM, DFF, DFF}; pg8::StaticOrder S; S.init(SEQ, DM, G, bx);
;           pg8::EpiRes E{a.out, a.out, MOD + lq * 12288 + 5 * DM, DM}; pg8::gemm_phase(ldsl, g, S, E, wave_s); }
.LBB0_1088:
	s_mul_i32 s10, s84, 0x3000
	s_ashr_i32 s11, s10, 31
	s_lshl_b64 s[10:11], s[10:11], 2
	s_add_u32 s6, s6, s10
	s_addc_u32 s7, s7, s11
	s_add_u32 s6, s6, 0x10a000
	s_addc_u32 s7, s7, 0
	s_lshl_b32 s1, s1, 5
	v_and_b32_e32 v17, 48, v16
	v_lshlrev_b32_e32 v18, 6, v16
	s_movk_i32 s9, 0x3c0
	v_lshlrev_b32_e32 v16, 2, v16
	s_and_b32 s37, s1, 0x60
	s_add_i32 m0, s29, 0x18000
	v_lshl_add_u64 v[8:9], v[8:9], 0, s[42:43]
	s_lshl_b32 s35, s8, 6
	s_lshl_b32 s8, s8, 13
	v_and_or_b32 v17, v18, s9, v17
	v_and_b32_e32 v16, 32, v16
	s_lshl_b32 s1, s37, 7
	s_waitcnt vmcnt(2)
	s_barrier
	global_load_lds_dwordx4 v[8:9], off
	v_lshl_add_u64 v[6:7], v[6:7], 0, s[42:43]
	s_add_i32 m0, s29, 0x1a000
	s_add_i32 s38, s29, 0x8000
	s_add_i32 s39, s29, 0xa000
	v_bitop3_b32 v18, v17, s8, v16 bitop3:0xde
	global_load_lds_dwordx4 v[6:7], off
	v_lshl_add_u64 v[2:3], v[2:3], 0, s[42:43]
	s_mov_b32 m0, s38
	s_add_u32 s8, s18, 0x200080
	global_load_lds_dwordx4 v[2:3], off
	v_lshl_add_u64 v[2:3], v[4:5], 0, s[42:43]
	s_mov_b32 m0, s39
	s_addc_u32 s9, s19, 0
	global_load_lds_dwordx4 v[2:3], off
	s_add_i32 m0, s29, 0x1c000
	s_nop 0
	global_load_lds_dwordx4 v0, s[8:9]
	v_lshl_add_u64 v[2:3], s[8:9], 0, v[146:147]
	s_add_i32 m0, s29, 0x1e000
	v_bitop3_b32 v158, s1, v17, v16 bitop3:0xf6
	global_load_lds_dwordx4 v[2:3], off
	v_lshlrev_b32_e32 v2, 17, v10
	v_and_b32_e32 v2, 0xfffc0000, v2
	v_lshl_add_u32 v2, v11, 14, v2
	v_and_b32_e32 v3, 1, v10
	v_lshl_or_b32 v2, v3, 6, v2
	v_lshl_add_u32 v148, v12, 1, v2
	v_lshlrev_b32_e32 v2, 17, v13
	v_and_b32_e32 v2, 0xfffc0000, v2
	s_waitcnt vmcnt(6)
	v_lshl_add_u32 v2, v14, 14, v2
	v_and_b32_e32 v3, 1, v13
	s_cmpk_lt_u32 s0, 0x100
	v_lshl_or_b32 v2, v3, 6, v2
	v_readlane_b32 s0, v255, 15
	s_cselect_b64 s[8:9], -1, 0
	v_mov_b32_e32 v149, v1
	v_lshl_add_u32 v150, v15, 1, v2
	v_mov_b32_e32 v151, v1
	s_mov_b32 s40, 0
	v_add_u32_e32 v159, 0, v18
	v_readlane_b32 s56, v255, 3
	s_mov_b32 s41, s0
	s_barrier
	v_readlane_b32 s1, v255, 16
	s_branch .LBB0_1091

; #define PG8_STAGE(bufoff, gbase, voff) do { _Pragma("unroll") for (int _i = 0; _i < 2; ++_i) \
;         __builtin_amdgcn_global_load_lds((const unsigned*)((const char*)(gbase) + (voff)[_i]), (LAS unsigned*)(lds + (bufoff) + ldsw + _i * 8192), 16, 0, 0); } while (0)
; #define PG8_LDA(dst, b, h) do { _Pragma("unroll") for (int m = 0; m < 4; ++m) _Pragma("unroll") for (int k = 0; k < 2; ++k) dst[m][k] = *(const LAS bf16x8*)(lds + PG8_SA(b, h) + aoff + m * 2048 + k * 1024); } while (0)
; #define PG8_LDB(dst, b, h) do { _Pragma("unroll") for (int n = 0; n < 2; ++n) _Pragma("unroll") for (int k = 0; k < 2; ++k) dst[n][k] = *(const LAS bf16x8*)(lds + PG8_SB(b, h) + boff + n * 2048 + k * 1024); } while (0)
; #define PG8_MMA(ai, bj, At, Bt) do { __builtin_amdgcn_s_setprio(1); _Pragma("unroll") for (int m = 0; m < 4; ++m) _Pragma("unroll") for (int n = 0; n < 2; ++n) _Pragma("unroll") for (int k = 0; k < 2; ++k) \
;         acc[ai][bj][m][n] = __builtin_amdgcn_mfma_f32_16x16x32_bf16(Bt[n][k], At[m][k], acc[ai][bj][m][n], 0, 0, 0); __builtin_amdgcn_s_setprio(0); } while (0)
; #define PG8_WAIT_V(n) asm volatile("s_waitcnt vmcnt(" #n ")" ::: "memory")
; #define PG8_BAR __builtin_amdgcn_s_barrier()
; template <class Epi>
; __device__ __forceinline__ void gemm_phase(LAS unsigned char* lds, const Gemm g, const StaticOrder& S, const Epi& E, int wave_s) {
;     ...
;         const char* nA = has_next ? (const char*)g.A + (size_t)nxt.pm * tstepA : cA; const char* nB = has_next ? (const char*)g.Bt + (size_t)nxt.pn * tstepB : cB;
;         for (int t = 0; t < nt; t += 2) {
;             const bool last = (t == nt - 2);
;             const char* a1 = cA + (size_t)(t + 1) * kstep;
;             const char* a2 = last ? nA : cA + (size_t)(t + 2) * kstep; const char* b2 = last ? nB : cB + (size_t)(t + 2) * kstep;
;             const char* a3 = a2 + kstep; const char* b3 = b2 + kstep;
;             PG8_LDB(B0, 0, 0); PG8_LDB(B1, 0, 1); PG8_SCHED; PG8_LDA(At, 0, 0); PG8_STAGE(PG8_SA(1, 1), a1 + hstepA, voffA);
;             PG8_WAIT_V(8); PG8_WAIT_L(0); PG8_BAR; PG8_MMA(0, 0, At, B0); PG8_MMA(0, 1, At, B1); PG8_BAR; PG8_SCHED;
;             PG8_LDA(At, 0, 1); PG8_STAGE(PG8_SB(0, 0), b2, voffB); PG8_STAGE(PG8_SB(0, 1), b2 + hstepB, voffB); PG8_STAGE(PG8_SA(0, 0), a2, voffA);
;             PG8_WAIT_V(8); PG8_WAIT_L(0); PG8_BAR; PG8_MMA(1, 0, At, B0); PG8_MMA(1, 1, At, B1); PG8_BAR; PG8_SCHED;
.LBB0_1098:
	s_add_u32 s20, s18, 0xffe00080
	s_addc_u32 s21, s19, -1
	s_add_i32 s70, 0, 0x10000
	s_cmpk_eq_i32 s67, 0x7c
	s_cselect_b32 s23, s13, s21
	s_cselect_b32 s22, s57, s20
	s_cselect_b32 s21, s11, s66
	s_cselect_b32 s20, s64, s65
	s_add_i32 s72, 0, 0x14000
	v_add_u32_e32 v142, s70, v158
	v_add_u32_e32 v156, s72, v158
	ds_read_b128 v[130:133], v142
	ds_read_b128 v[134:137], v142 offset:1024
	ds_read_b128 v[138:141], v142 offset:2048
	ds_read_b128 v[142:145], v142 offset:3072
	ds_read_b128 v[152:155], v156
	ds_read_b128 v[160:163], v156 offset:1024
	ds_read_b128 v[164:167], v156 offset:2048
	ds_read_b128 v[168:171], v156 offset:3072
	v_lshl_add_u64 v[156:157], s[18:19], 0, v[150:151]
	s_add_i32 m0, s29, 0xc000
	ds_read_b128 v[172:175], v159
	ds_read_b128 v[176:179], v159 offset:1024
	ds_read_b128 v[180:183], v159 offset:2048
	ds_read_b128 v[184:187], v159 offset:3072
	ds_read_b128 v[188:191], v159 offset:4096
	ds_read_b128 v[192:195], v159 offset:5120
	ds_read_b128 v[196:199], v159 offset:6144
	ds_read_b128 v[200:203], v159 offset:7168
	global_load_lds_dwordx4 v[156:157], off
	v_lshl_add_u64 v[156:157], s[18:19], 0, v[148:149]
	s_add_i32 m0, s29, 0xe000
	s_nop 0
	global_load_lds_dwordx4 v[156:157], off
	s_waitcnt vmcnt(8)
	s_waitcnt lgkmcnt(0)
	s_barrier
	s_setprio 1
	s_waitcnt lgkmcnt(0)
	v_mfma_f32_16x16x32_bf16 v[126:129], v[130:133], v[172:175], v[126:129]
	v_mfma_f32_16x16x32_bf16 v[122:125], v[138:141], v[172:175], v[122:125]
	v_mfma_f32_16x16x32_bf16 v[118:121], v[130:133], v[180:183], v[118:121]
	v_mfma_f32_16x16x32_bf16 v[114:117], v[138:141], v[180:183], v[114:117]
	v_mfma_f32_16x16x32_bf16 v[110:113], v[130:133], v[188:191], v[110:113]
	v_mfma_f32_16x16x32_bf16 v[98:101], v[138:141], v[188:191], v[98:101]
	v_mfma_f32_16x16x32_bf16 v[82:85], v[130:133], v[196:199], v[82:85]
	v_mfma_f32_16x16x32_bf16 v[74:77], v[138:141], v[196:199], v[74:77]
	v_mfma_f32_16x16x32_bf16 v[126:129], v[134:137], v[176:179], v[126:129]
	v_mfma_f32_16x16x32_bf16 v[122:125], v[142:145], v[176:179], v[122:125]
	v_mfma_f32_16x16x32_bf16 v[118:121], v[134:137], v[184:187], v[118:121]
	v_mfma_f32_16x16x32_bf16 v[114:117], v[142:145], v[184:187], v[114:117]
	v_mfma_f32_16x16x32_bf16 v[110:113], v[134:137], v[192:195], v[110:113]
	v_mfma_f32_16x16x32_bf16 v[98:101], v[142:145], v[192:195], v[98:101]
	v_mfma_f32_16x16x32_bf16 v[82:85], v[134:137], v[200:203], v[82:85]
	v_mfma_f32_16x16x32_bf16 v[74:77], v[142:145], v[200:203], v[74:77]
	s_setprio 0
	s_setprio 1
	v_mfma_f32_16x16x32_bf16 v[106:109], v[152:155], v[172:175], v[106:109]
	v_mfma_f32_16x16x32_bf16 v[102:105], v[164:167], v[172:175], v[102:105]
	v_mfma_f32_16x16x32_bf16 v[94:97], v[152:155], v[180:183], v[94:97]
	v_mfma_f32_16x16x32_bf16 v[90:93], v[164:167], v[180:183], v[90:93]
	v_mfma_f32_16x16x32_bf16 v[86:89], v[152:155], v[188:191], v[86:89]
	v_mfma_f32_16x16x32_bf16 v[78:81], v[164:167], v[188:191], v[78:81]
	v_mfma_f32_16x16x32_bf16 v[70:73], v[152:155], v[196:199], v[70:73]
	v_mfma_f32_16x16x32_bf16 v[66:69], v[164:167], v[196:199], v[66:69]
	v_mfma_f32_16x16x32_bf16 v[106:109], v[160:163], v[176:179], v[106:109]
	v_mfma_f32_16x16x32_bf16 v[102:105], v[168:171], v[176:179], v[102:105]
	v_mfma_f32_16x16x32_bf16 v[94:97], v[160:163], v[184:187], v[94:97]
	v_mfma_f32_16x16x32_bf16 v[90:93], v[168:171], v[184:187], v[90:93]
	v_mfma_f32_16x16x32_bf16 v[86:89], v[160:163], v[192:195], v[86:89]
	v_mfma_f32_16x16x32_bf16 v[78:81], v[168:171], v[192:195], v[78:81]
	v_mfma_f32_16x16x32_bf16 v[70:73], v[160:163], v[200:203], v[70:73]
	v_mfma_f32_16x16x32_bf16 v[66:69], v[168:171], v[200:203], v[66:69]
	s_setprio 0
	s_barrier
	s_add_i32 s70, s70, s28
	v_lshl_add_u64 v[156:157], s[20:21], 0, v[0:1]
	s_mov_b32 m0, s70
	ds_read_b128 v[172:175], v159 offset:16384
	ds_read_b128 v[176:179], v159 offset:17408
	ds_read_b128 v[180:183], v159 offset:18432
	ds_read_b128 v[184:187], v159 offset:19456
	ds_read_b128 v[188:191], v159 offset:20480
	ds_read_b128 v[192:195], v159 offset:21504
	ds_read_b128 v[196:199], v159 offset:22528
	ds_read_b128 v[200:203], v159 offset:23552
	global_load_lds_dwordx4 v[156:157], off
	s_add_i32 m0, s70, 0x2000
	s_add_u32 s70, s20, 0x200000
	v_lshl_add_u64 v[204:205], s[20:21], 0, v[146:147]
	s_addc_u32 s71, s21, 0
	s_add_i32 s72, s72, s28
	global_load_lds_dwordx4 v[204:205], off
	s_mov_b32 m0, s72
	v_lshl_add_u64 v[208:209], s[22:23], 0, v[146:147]
	global_load_lds_dwordx4 v0, s[70:71]
	v_lshl_add_u64 v[206:207], s[70:71], 0, v[146:147]
	s_add_i32 m0, s72, 0x2000
	s_nop 0
	global_load_lds_dwordx4 v[206:207], off
	v_lshl_add_u64 v[206:207], s[22:23], 0, v[0:1]
	s_mov_b32 m0, s29
	s_nop 0
	global_load_lds_dwordx4 v[206:207], off
	s_mov_b32 m0, s30
	s_nop 0
	global_load_lds_dwordx4 v[208:209], off
	s_waitcnt vmcnt(8)
	s_waitcnt lgkmcnt(0)
	s_barrier
; #define PG8_STAGE(bufoff, gbase, voff) do { _Pragma("unroll") for (int _i = 0; _i < 2; ++_i) \
;         __builtin_amdgcn_global_load_lds((const unsigned*)((const char*)(gbase) + (voff)[_i]), (LAS unsigned*)(lds + (bufoff) + ldsw + _i * 8192), 16, 0, 0); } while (0)
; #define PG8_LDA(dst, b, h) do { _Pragma("unroll") for (int m = 0; m < 4; ++m) _Pragma("unroll") for (int k = 0; k < 2; ++k) dst[m][k] = *(const LAS bf16x8*)(lds + PG8_SA(b, h) + aoff + m * 2048 + k * 1024); } while (0)
; #define PG8_LDB(dst, b, h) do { _Pragma("unroll") for (int n = 0; n < 2; ++n) _Pragma("unroll") for (int k = 0; k < 2; ++k) dst[n][k] = *(const LAS bf16x8*)(lds + PG8_SB(b, h) + boff + n * 2048 + k * 1024); } while (0)
; #define PG8_MMA(ai, bj, At, Bt) do { __builtin_amdgcn_s_setprio(1); _Pragma("unroll") for (int m = 0; m < 4; ++m) _Pragma("unroll") for (int n = 0; n < 2; ++n) _Pragma("unroll") for (int k = 0; k < 2; ++k) \
;         acc[ai][bj][m][n] = __builtin_amdgcn_mfma_f32_16x16x32_bf16(Bt[n][k], At[m][k], acc[ai][bj][m][n], 0, 0, 0); __builtin_amdgcn_s_setprio(0); } while (0)
; #define PG8_WAIT_V(n) asm volatile("s_waitcnt vmcnt(" #n ")" ::: "memory")
; #define PG8_WAIT_L(n) asm volatile("s_waitcnt lgkmcnt(" #n ")" ::: "memory")
; #define PG8_BAR __builtin_amdgcn_s_barrier()
; #define PG8_SCHED __builtin_amdgcn_sched_barrier(0)
; template <class Epi>
; __device__ __forceinline__ void gemm_phase(LAS unsigned char* lds, const Gemm g, const StaticOrder& S, const Epi& E, int wave_s) {
;     ...
;             PG8_WAIT_V(8); PG8_WAIT_L(0); PG8_BAR; PG8_MMA(1, 0, At, B0); PG8_MMA(1, 1, At, B1); PG8_BAR; PG8_SCHED;
;             PG8_LDB(B0, 1, 0); PG8_LDB(B1, 1, 1); PG8_SCHED; PG8_LDA(At, 1, 0); PG8_STAGE(PG8_SA(0, 1), a2 + hstepA, voffA);
;             PG8_WAIT_V(8); PG8_WAIT_L(0); PG8_BAR; PG8_MMA(0, 0, At, B0); PG8_MMA(0, 1, At, B1); PG8_BAR; PG8_SCHED;
	s_setprio 1
	s_waitcnt lgkmcnt(0)
	v_mfma_f32_16x16x32_bf16 v[62:65], v[130:133], v[172:175], v[62:65]
	v_mfma_f32_16x16x32_bf16 v[58:61], v[138:141], v[172:175], v[58:61]
	v_mfma_f32_16x16x32_bf16 v[54:57], v[130:133], v[180:183], v[54:57]
	v_mfma_f32_16x16x32_bf16 v[50:53], v[138:141], v[180:183], v[50:53]
	v_mfma_f32_16x16x32_bf16 v[46:49], v[130:133], v[188:191], v[46:49]
	v_mfma_f32_16x16x32_bf16 v[34:37], v[138:141], v[188:191], v[34:37]
	v_mfma_f32_16x16x32_bf16 v[22:25], v[130:133], v[196:199], v[22:25]
	v_mfma_f32_16x16x32_bf16 v[14:17], v[138:141], v[196:199], v[14:17]
	v_mfma_f32_16x16x32_bf16 v[62:65], v[134:137], v[176:179], v[62:65]
	v_mfma_f32_16x16x32_bf16 v[58:61], v[142:145], v[176:179], v[58:61]
	v_mfma_f32_16x16x32_bf16 v[54:57], v[134:137], v[184:187], v[54:57]
	v_mfma_f32_16x16x32_bf16 v[50:53], v[142:145], v[184:187], v[50:53]
	v_mfma_f32_16x16x32_bf16 v[46:49], v[134:137], v[192:195], v[46:49]
	v_mfma_f32_16x16x32_bf16 v[34:37], v[142:145], v[192:195], v[34:37]
	v_mfma_f32_16x16x32_bf16 v[22:25], v[134:137], v[200:203], v[22:25]
	v_mfma_f32_16x16x32_bf16 v[14:17], v[142:145], v[200:203], v[14:17]
	s_setprio 0
	s_setprio 1
	v_mfma_f32_16x16x32_bf16 v[42:45], v[152:155], v[172:175], v[42:45]
	v_mfma_f32_16x16x32_bf16 v[38:41], v[164:167], v[172:175], v[38:41]
	v_mfma_f32_16x16x32_bf16 v[30:33], v[152:155], v[180:183], v[30:33]
	v_mfma_f32_16x16x32_bf16 v[26:29], v[164:167], v[180:183], v[26:29]
	v_mfma_f32_16x16x32_bf16 v[18:21], v[152:155], v[188:191], v[18:21]
	v_mfma_f32_16x16x32_bf16 v[10:13], v[164:167], v[188:191], v[10:13]
	v_mfma_f32_16x16x32_bf16 v[6:9], v[152:155], v[196:199], v[6:9]
	v_mfma_f32_16x16x32_bf16 v[2:5], v[164:167], v[196:199], v[2:5]
	v_mfma_f32_16x16x32_bf16 v[42:45], v[160:163], v[176:179], v[42:45]
	v_mfma_f32_16x16x32_bf16 v[38:41], v[168:171], v[176:179], v[38:41]
	v_mfma_f32_16x16x32_bf16 v[30:33], v[160:163], v[184:187], v[30:33]
	v_mfma_f32_16x16x32_bf16 v[26:29], v[168:171], v[184:187], v[26:29]
	v_mfma_f32_16x16x32_bf16 v[18:21], v[160:163], v[192:195], v[18:21]
	v_mfma_f32_16x16x32_bf16 v[10:13], v[168:171], v[192:195], v[10:13]
	v_mfma_f32_16x16x32_bf16 v[6:9], v[160:163], v[200:203], v[6:9]
	v_mfma_f32_16x16x32_bf16 v[2:5], v[168:171], v[200:203], v[2:5]
	s_setprio 0
	s_barrier
	s_add_i32 s70, 0, 0x18000
	s_add_i32 s71, 0, 0x1c000
	v_add_u32_e32 v142, s70, v158
	v_add_u32_e32 v168, s71, v158
	ds_read_b128 v[130:133], v142
	ds_read_b128 v[134:137], v142 offset:1024
	ds_read_b128 v[138:141], v142 offset:2048
	ds_read_b128 v[142:145], v142 offset:3072
	ds_read_b128 v[152:155], v168
	ds_read_b128 v[160:163], v168 offset:1024
	ds_read_b128 v[164:167], v168 offset:2048
	ds_read_b128 v[168:171], v168 offset:3072
	s_add_u32 s22, s22, 0x200000
	s_addc_u32 s23, s23, 0
	s_mov_b32 m0, s31
	ds_read_b128 v[172:175], v159 offset:32768
	ds_read_b128 v[176:179], v159 offset:33792
	ds_read_b128 v[180:183], v159 offset:34816
	ds_read_b128 v[184:187], v159 offset:35840
	ds_read_b128 v[188:191], v159 offset:36864
	ds_read_b128 v[192:195], v159 offset:37888
	ds_read_b128 v[196:199], v159 offset:38912
	ds_read_b128 v[200:203], v159 offset:39936
	global_load_lds_dwordx4 v0, s[22:23]
	v_lshl_add_u64 v[210:211], s[22:23], 0, v[146:147]
	s_mov_b32 m0, s34
	s_nop 0
	global_load_lds_dwordx4 v[210:211], off
	s_waitcnt vmcnt(8)
	s_waitcnt lgkmcnt(0)
	s_barrier
	s_setprio 1
	s_waitcnt lgkmcnt(0)
	v_mfma_f32_16x16x32_bf16 v[126:129], v[130:133], v[172:175], v[126:129]
	v_mfma_f32_16x16x32_bf16 v[122:125], v[138:141], v[172:175], v[122:125]
	v_mfma_f32_16x16x32_bf16 v[118:121], v[130:133], v[180:183], v[118:121]
	v_mfma_f32_16x16x32_bf16 v[114:117], v[138:141], v[180:183], v[114:117]
	v_mfma_f32_16x16x32_bf16 v[110:113], v[130:133], v[188:191], v[110:113]
	v_mfma_f32_16x16x32_bf16 v[98:101], v[138:141], v[188:191], v[98:101]
	v_mfma_f32_16x16x32_bf16 v[82:85], v[130:133], v[196:199], v[82:85]
	v_mfma_f32_16x16x32_bf16 v[74:77], v[138:141], v[196:199], v[74:77]
	v_mfma_f32_16x16x32_bf16 v[126:129], v[134:137], v[176:179], v[126:129]
	v_mfma_f32_16x16x32_bf16 v[122:125], v[142:145], v[176:179], v[122:125]
	v_mfma_f32_16x16x32_bf16 v[118:121], v[134:137], v[184:187], v[118:121]
	v_mfma_f32_16x16x32_bf16 v[114:117], v[142:145], v[184:187], v[114:117]
	v_mfma_f32_16x16x32_bf16 v[110:113], v[134:137], v[192:195], v[110:113]
	v_mfma_f32_16x16x32_bf16 v[98:101], v[142:145], v[192:195], v[98:101]
	v_mfma_f32_16x16x32_bf16 v[82:85], v[134:137], v[200:203], v[82:85]
	v_mfma_f32_16x16x32_bf16 v[74:77], v[142:145], v[200:203], v[74:77]
	s_setprio 0
	s_setprio 1
	v_mfma_f32_16x16x32_bf16 v[106:109], v[152:155], v[172:175], v[106:109]
	v_mfma_f32_16x16x32_bf16 v[102:105], v[164:167], v[172:175], v[102:105]
	v_mfma_f32_16x16x32_bf16 v[94:97], v[152:155], v[180:183], v[94:97]
	v_mfma_f32_16x16x32_bf16 v[90:93], v[164:167], v[180:183], v[90:93]
	v_mfma_f32_16x16x32_bf16 v[86:89], v[152:155], v[188:191], v[86:89]
	v_mfma_f32_16x16x32_bf16 v[78:81], v[164:167], v[188:191], v[78:81]
	v_mfma_f32_16x16x32_bf16 v[70:73], v[152:155], v[196:199], v[70:73]
	v_mfma_f32_16x16x32_bf16 v[66:69], v[164:167], v[196:199], v[66:69]
	v_mfma_f32_16x16x32_bf16 v[106:109], v[160:163], v[176:179], v[106:109]
	v_mfma_f32_16x16x32_bf16 v[102:105], v[168:171], v[176:179], v[102:105]
	v_mfma_f32_16x16x32_bf16 v[94:97], v[160:163], v[184:187], v[94:97]
	v_mfma_f32_16x16x32_bf16 v[90:93], v[168:171], v[184:187], v[90:93]
	v_mfma_f32_16x16x32_bf16 v[86:89], v[160:163], v[192:195], v[86:89]
	v_mfma_f32_16x16x32_bf16 v[78:81], v[168:171], v[192:195], v[78:81]
	v_mfma_f32_16x16x32_bf16 v[70:73], v[160:163], v[200:203], v[70:73]
	v_mfma_f32_16x16x32_bf16 v[66:69], v[168:171], v[200:203], v[66:69]
	s_setprio 0
	s_barrier
; #define PG8_STAGE(bufoff, gbase, voff) do { _Pragma("unroll") for (int _i = 0; _i < 2; ++_i) \
;         __builtin_amdgcn_global_load_lds((const unsigned*)((const char*)(gbase) + (voff)[_i]), (LAS unsigned*)(lds + (bufoff) + ldsw + _i * 8192), 16, 0, 0); } while (0)
; #define PG8_LDA(dst, b, h) do { _Pragma("unroll") for (int m = 0; m < 4; ++m) _Pragma("unroll") for (int k = 0; k < 2; ++k) dst[m][k] = *(const LAS bf16x8*)(lds + PG8_SA(b, h) + aoff + m * 2048 + k * 1024); } while (0)
; #define PG8_MMA(ai, bj, At, Bt) do { __builtin_amdgcn_s_setprio(1); _Pragma("unroll") for (int m = 0; m < 4; ++m) _Pragma("unroll") for (int n = 0; n < 2; ++n) _Pragma("unroll") for (int k = 0; k < 2; ++k) \
;         acc[ai][bj][m][n] = __builtin_amdgcn_mfma_f32_16x16x32_bf16(Bt[n][k], At[m][k], acc[ai][bj][m][n], 0, 0, 0); __builtin_amdgcn_s_setprio(0); } while (0)
; #define PG8_WAIT_V(n) asm volatile("s_waitcnt vmcnt(" #n ")" ::: "memory")
; #define PG8_WAIT_L(n) asm volatile("s_waitcnt lgkmcnt(" #n ")" ::: "memory")
; #define PG8_BAR __builtin_amdgcn_s_barrier()
; #define PG8_SCHED __builtin_amdgcn_sched_barrier(0)
; template <class Epi>
; __device__ __forceinline__ void gemm_phase(LAS unsigned char* lds, const Gemm g, const StaticOrder& S, const Epi& E, int wave_s) {
;     ...
;             PG8_LDA(At, 1, 1); PG8_STAGE(PG8_SB(1, 0), b3, voffB); PG8_STAGE(PG8_SB(1, 1), b3 + hstepB, voffB); PG8_STAGE(PG8_SA(1, 0), a3, voffA);
;             PG8_WAIT_V(8); PG8_WAIT_L(0); PG8_BAR; PG8_MMA(1, 0, At, B0); PG8_MMA(1, 1, At, B1); PG8_BAR; PG8_SCHED;
;         }
;         if (wr == 0) PG8_BAR;
	s_add_i32 s22, s70, s28
	v_lshl_add_u64 v[156:157], v[156:157], 0, s[42:43]
	s_mov_b32 m0, s22
	ds_read_b128 v[172:175], v159 offset:49152
	ds_read_b128 v[176:179], v159 offset:50176
	ds_read_b128 v[180:183], v159 offset:51200
	ds_read_b128 v[184:187], v159 offset:52224
	ds_read_b128 v[188:191], v159 offset:53248
	ds_read_b128 v[192:195], v159 offset:54272
	ds_read_b128 v[196:199], v159 offset:55296
	ds_read_b128 v[200:203], v159 offset:56320
	global_load_lds_dwordx4 v[156:157], off
	s_add_i32 m0, s22, 0x2000
	s_add_u32 s20, s20, 0x200080
	v_lshl_add_u64 v[156:157], v[204:205], 0, s[42:43]
	s_addc_u32 s21, s21, 0
	s_add_i32 s22, s71, s28
	global_load_lds_dwordx4 v[156:157], off
	s_mov_b32 m0, s22
	s_nop 0
	global_load_lds_dwordx4 v0, s[20:21]
	v_lshl_add_u64 v[156:157], s[20:21], 0, v[146:147]
	s_add_i32 m0, s22, 0x2000
	s_nop 0
	global_load_lds_dwordx4 v[156:157], off
	v_lshl_add_u64 v[156:157], v[206:207], 0, s[42:43]
	s_mov_b32 m0, s38
	s_nop 0
	global_load_lds_dwordx4 v[156:157], off
	v_lshl_add_u64 v[156:157], v[208:209], 0, s[42:43]
	s_mov_b32 m0, s39
	s_nop 0
	global_load_lds_dwordx4 v[156:157], off
	s_waitcnt vmcnt(8)
	s_waitcnt lgkmcnt(0)
	s_barrier
	s_setprio 1
	s_waitcnt lgkmcnt(0)
	v_mfma_f32_16x16x32_bf16 v[62:65], v[130:133], v[172:175], v[62:65]
	v_mfma_f32_16x16x32_bf16 v[58:61], v[138:141], v[172:175], v[58:61]
	v_mfma_f32_16x16x32_bf16 v[54:57], v[130:133], v[180:183], v[54:57]
	v_mfma_f32_16x16x32_bf16 v[50:53], v[138:141], v[180:183], v[50:53]
	v_mfma_f32_16x16x32_bf16 v[46:49], v[130:133], v[188:191], v[46:49]
	v_mfma_f32_16x16x32_bf16 v[34:37], v[138:141], v[188:191], v[34:37]
	v_mfma_f32_16x16x32_bf16 v[22:25], v[130:133], v[196:199], v[22:25]
	v_mfma_f32_16x16x32_bf16 v[14:17], v[138:141], v[196:199], v[14:17]
	v_mfma_f32_16x16x32_bf16 v[62:65], v[134:137], v[176:179], v[62:65]
	v_mfma_f32_16x16x32_bf16 v[58:61], v[142:145], v[176:179], v[58:61]
	v_mfma_f32_16x16x32_bf16 v[54:57], v[134:137], v[184:187], v[54:57]
	v_mfma_f32_16x16x32_bf16 v[50:53], v[142:145], v[184:187], v[50:53]
	v_mfma_f32_16x16x32_bf16 v[46:49], v[134:137], v[192:195], v[46:49]
	v_mfma_f32_16x16x32_bf16 v[34:37], v[142:145], v[192:195], v[34:37]
	v_mfma_f32_16x16x32_bf16 v[22:25], v[134:137], v[200:203], v[22:25]
	v_mfma_f32_16x16x32_bf16 v[14:17], v[142:145], v[200:203], v[14:17]
	s_setprio 0
	s_setprio 1
	v_mfma_f32_16x16x32_bf16 v[42:45], v[152:155], v[172:175], v[42:45]
	v_mfma_f32_16x16x32_bf16 v[38:41], v[164:167], v[172:175], v[38:41]
	v_mfma_f32_16x16x32_bf16 v[30:33], v[152:155], v[180:183], v[30:33]
	v_mfma_f32_16x16x32_bf16 v[26:29], v[164:167], v[180:183], v[26:29]
	v_mfma_f32_16x16x32_bf16 v[18:21], v[152:155], v[188:191], v[18:21]
	v_mfma_f32_16x16x32_bf16 v[10:13], v[164:167], v[188:191], v[10:13]
	v_mfma_f32_16x16x32_bf16 v[6:9], v[152:155], v[196:199], v[6:9]
	v_mfma_f32_16x16x32_bf16 v[2:5], v[164:167], v[196:199], v[2:5]
	v_mfma_f32_16x16x32_bf16 v[42:45], v[160:163], v[176:179], v[42:45]
	v_mfma_f32_16x16x32_bf16 v[38:41], v[168:171], v[176:179], v[38:41]
	v_mfma_f32_16x16x32_bf16 v[30:33], v[160:163], v[184:187], v[30:33]
	v_mfma_f32_16x16x32_bf16 v[26:29], v[168:171], v[184:187], v[26:29]
	v_mfma_f32_16x16x32_bf16 v[18:21], v[160:163], v[192:195], v[18:21]
	v_mfma_f32_16x16x32_bf16 v[10:13], v[168:171], v[192:195], v[10:13]
	v_mfma_f32_16x16x32_bf16 v[6:9], v[160:163], v[200:203], v[6:9]
	v_mfma_f32_16x16x32_bf16 v[2:5], v[168:171], v[200:203], v[2:5]
	s_setprio 0
	s_barrier
	s_add_i32 s67, s67, 2
	s_add_u32 s65, s65, 0x100
	s_addc_u32 s66, s66, 0
	s_add_u32 s18, s18, 0x100
	s_addc_u32 s19, s19, 0
	s_cmpk_gt_u32 s67, 0x7d
	s_cbranch_scc0 .LBB0_1098
	s_and_b64 vcc, exec, s[8:9]
	s_cbranch_vccz .LBB0_1101
	s_barrier
